# GEMM MMA blocks: MFMAs reordered so each accumulator's two K-steps issue back-to-back (SrcC forwarding chains), no other change
# speedup vs baseline: 1.0123x; 1.0123x over previous
.LBB0_254:
	ds_read_b128 v[90:93], v86
	ds_read_b128 v[94:97], v86 offset:1024
	ds_read_b128 v[98:101], v86 offset:2048
	ds_read_b128 v[102:105], v86 offset:3072
	ds_read_b128 v[106:109], v87
	ds_read_b128 v[110:113], v87 offset:1024
	ds_read_b128 v[114:117], v87 offset:2048
	ds_read_b128 v[118:121], v87 offset:3072
	s_add_u32 s38, s36, 0xfff80080
	s_addc_u32 s39, s37, -1
	s_cmp_eq_u32 s59, 28
	s_cselect_b32 s41, s17, s39
	s_cselect_b32 s40, s16, s38
	s_cselect_b32 s39, s2, s58
	s_cselect_b32 s38, s3, s29
	s_mov_b32 m0, s57
	v_lshl_add_u64 v[80:81], s[36:37], 0, v[76:77]
	ds_read_b128 v[122:125], v88
	ds_read_b128 v[126:129], v88 offset:1024
	ds_read_b128 v[130:133], v88 offset:2048
	ds_read_b128 v[134:137], v88 offset:3072
	ds_read_b128 v[138:141], v88 offset:4096
	ds_read_b128 v[142:145], v88 offset:5120
	ds_read_b128 v[146:149], v88 offset:6144
	ds_read_b128 v[150:153], v88 offset:7168
	global_load_lds_dwordx4 v[80:81], off
	v_lshl_add_u64 v[80:81], s[36:37], 0, v[78:79]
	s_add_i32 m0, s19, 0xe000
	s_nop 0
	global_load_lds_dwordx4 v[80:81], off
	s_waitcnt vmcnt(8)
	s_waitcnt lgkmcnt(0)
	s_barrier
	s_setprio 1
	s_waitcnt lgkmcnt(0)
	v_mfma_f32_16x16x32_bf16 v[60:63], v[90:93], v[122:125], v[60:63]
	v_mfma_f32_16x16x32_bf16 v[60:63], v[94:97], v[126:129], v[60:63]
	v_mfma_f32_16x16x32_bf16 v[52:55], v[90:93], v[130:133], v[52:55]
	v_mfma_f32_16x16x32_bf16 v[52:55], v[94:97], v[134:137], v[52:55]
	v_mfma_f32_16x16x32_bf16 v[36:39], v[90:93], v[138:141], v[36:39]
	v_mfma_f32_16x16x32_bf16 v[36:39], v[94:97], v[142:145], v[36:39]
	v_mfma_f32_16x16x32_bf16 v[20:23], v[90:93], v[146:149], v[20:23]
	v_mfma_f32_16x16x32_bf16 v[20:23], v[94:97], v[150:153], v[20:23]
	v_mfma_f32_16x16x32_bf16 v[56:59], v[98:101], v[122:125], v[56:59]
	v_mfma_f32_16x16x32_bf16 v[56:59], v[102:105], v[126:129], v[56:59]
	v_mfma_f32_16x16x32_bf16 v[48:51], v[98:101], v[130:133], v[48:51]
	v_mfma_f32_16x16x32_bf16 v[48:51], v[102:105], v[134:137], v[48:51]
	v_mfma_f32_16x16x32_bf16 v[32:35], v[98:101], v[138:141], v[32:35]
	v_mfma_f32_16x16x32_bf16 v[32:35], v[102:105], v[142:145], v[32:35]
	v_mfma_f32_16x16x32_bf16 v[16:19], v[98:101], v[146:149], v[16:19]
	v_mfma_f32_16x16x32_bf16 v[16:19], v[102:105], v[150:153], v[16:19]
	s_setprio 0
	s_setprio 1
	v_mfma_f32_16x16x32_bf16 v[44:47], v[106:109], v[122:125], v[44:47]
	v_mfma_f32_16x16x32_bf16 v[44:47], v[110:113], v[126:129], v[44:47]
	v_mfma_f32_16x16x32_bf16 v[28:31], v[106:109], v[130:133], v[28:31]
	v_mfma_f32_16x16x32_bf16 v[28:31], v[110:113], v[134:137], v[28:31]
	v_mfma_f32_16x16x32_bf16 v[12:15], v[106:109], v[138:141], v[12:15]
	v_mfma_f32_16x16x32_bf16 v[12:15], v[110:113], v[142:145], v[12:15]
	v_mfma_f32_16x16x32_bf16 v[4:7], v[106:109], v[146:149], v[4:7]
	v_mfma_f32_16x16x32_bf16 v[4:7], v[110:113], v[150:153], v[4:7]
	v_mfma_f32_16x16x32_bf16 v[40:43], v[114:117], v[122:125], v[40:43]
	v_mfma_f32_16x16x32_bf16 v[40:43], v[118:121], v[126:129], v[40:43]
	v_mfma_f32_16x16x32_bf16 v[24:27], v[114:117], v[130:133], v[24:27]
	v_mfma_f32_16x16x32_bf16 v[24:27], v[118:121], v[134:137], v[24:27]
	v_mfma_f32_16x16x32_bf16 v[8:11], v[114:117], v[138:141], v[8:11]
	v_mfma_f32_16x16x32_bf16 v[8:11], v[118:121], v[142:145], v[8:11]
	v_mfma_f32_16x16x32_bf16 v[0:3], v[114:117], v[146:149], v[0:3]
	v_mfma_f32_16x16x32_bf16 v[0:3], v[118:121], v[150:153], v[0:3]
	s_setprio 0
	s_barrier
	s_nop 1
	s_add_i32 s60, s55, s48
	v_lshl_add_u64 v[80:81], s[38:39], 0, v[64:65]
	s_mov_b32 m0, s60
	v_lshl_add_u64 v[154:155], s[38:39], 0, v[66:67]
	global_load_lds_dwordx4 v[80:81], off
	s_add_i32 m0, s60, 0x2000
	s_add_u32 s60, s38, 0x80000
	s_addc_u32 s61, s39, 0
	s_add_i32 s62, s56, s48
	global_load_lds_dwordx4 v[154:155], off
	v_lshl_add_u64 v[90:91], s[60:61], 0, v[64:65]
	s_mov_b32 m0, s62
	v_lshl_add_u64 v[156:157], s[40:41], 0, v[64:65]
	global_load_lds_dwordx4 v[90:91], off
	v_lshl_add_u64 v[90:91], s[60:61], 0, v[66:67]
	s_add_i32 m0, s62, 0x2000
	v_lshl_add_u64 v[158:159], s[40:41], 0, v[66:67]
	global_load_lds_dwordx4 v[90:91], off
	s_mov_b32 m0, s19
	s_nop 0
	global_load_lds_dwordx4 v[156:157], off
	s_mov_b32 m0, s49
	s_nop 0
	global_load_lds_dwordx4 v[158:159], off
	s_waitcnt vmcnt(8)
	s_waitcnt lgkmcnt(0)
	s_barrier
	s_setprio 1
	s_setprio 0
	s_setprio 1
	s_setprio 0
	s_barrier
	s_add_i32 s60, 0, 0x18000
	v_add_u32_e32 v89, s60, v84
	s_add_i32 s61, 0, 0x1c000
	ds_read_b128 v[90:93], v89
	ds_read_b128 v[94:97], v89 offset:1024
	ds_read_b128 v[98:101], v89 offset:2048
	ds_read_b128 v[102:105], v89 offset:3072
	v_add_u32_e32 v89, s61, v84
	ds_read_b128 v[106:109], v89
	ds_read_b128 v[110:113], v89 offset:1024
	ds_read_b128 v[114:117], v89 offset:2048
	ds_read_b128 v[118:121], v89 offset:3072
	s_add_u32 s40, s40, 0x80000
	s_addc_u32 s41, s41, 0
	s_mov_b32 m0, s50
	v_lshl_add_u64 v[160:161], s[40:41], 0, v[64:65]
	ds_read_b128 v[122:125], v88 offset:32768
	ds_read_b128 v[126:129], v88 offset:33792
	ds_read_b128 v[130:133], v88 offset:34816
	ds_read_b128 v[134:137], v88 offset:35840
	ds_read_b128 v[138:141], v88 offset:36864
	ds_read_b128 v[142:145], v88 offset:37888
	ds_read_b128 v[146:149], v88 offset:38912
	ds_read_b128 v[150:153], v88 offset:39936
	global_load_lds_dwordx4 v[160:161], off
	v_lshl_add_u64 v[160:161], s[40:41], 0, v[66:67]
	s_mov_b32 m0, s51
	s_nop 0
	global_load_lds_dwordx4 v[160:161], off
	s_waitcnt vmcnt(8)
	s_waitcnt lgkmcnt(0)
	s_barrier
	s_setprio 1
	s_waitcnt lgkmcnt(0)
	v_mfma_f32_16x16x32_bf16 v[60:63], v[90:93], v[122:125], v[60:63]
	v_mfma_f32_16x16x32_bf16 v[60:63], v[94:97], v[126:129], v[60:63]
	v_mfma_f32_16x16x32_bf16 v[52:55], v[90:93], v[130:133], v[52:55]
	v_mfma_f32_16x16x32_bf16 v[52:55], v[94:97], v[134:137], v[52:55]
	v_mfma_f32_16x16x32_bf16 v[36:39], v[90:93], v[138:141], v[36:39]
	v_mfma_f32_16x16x32_bf16 v[36:39], v[94:97], v[142:145], v[36:39]
	v_mfma_f32_16x16x32_bf16 v[20:23], v[90:93], v[146:149], v[20:23]
	v_mfma_f32_16x16x32_bf16 v[20:23], v[94:97], v[150:153], v[20:23]
	v_mfma_f32_16x16x32_bf16 v[56:59], v[98:101], v[122:125], v[56:59]
	v_mfma_f32_16x16x32_bf16 v[56:59], v[102:105], v[126:129], v[56:59]
	v_mfma_f32_16x16x32_bf16 v[48:51], v[98:101], v[130:133], v[48:51]
	v_mfma_f32_16x16x32_bf16 v[48:51], v[102:105], v[134:137], v[48:51]
	v_mfma_f32_16x16x32_bf16 v[32:35], v[98:101], v[138:141], v[32:35]
	v_mfma_f32_16x16x32_bf16 v[32:35], v[102:105], v[142:145], v[32:35]
	v_mfma_f32_16x16x32_bf16 v[16:19], v[98:101], v[146:149], v[16:19]
	v_mfma_f32_16x16x32_bf16 v[16:19], v[102:105], v[150:153], v[16:19]
	s_setprio 0
	s_setprio 1
	v_mfma_f32_16x16x32_bf16 v[44:47], v[106:109], v[122:125], v[44:47]
	v_mfma_f32_16x16x32_bf16 v[44:47], v[110:113], v[126:129], v[44:47]
	v_mfma_f32_16x16x32_bf16 v[28:31], v[106:109], v[130:133], v[28:31]
	v_mfma_f32_16x16x32_bf16 v[28:31], v[110:113], v[134:137], v[28:31]
	v_mfma_f32_16x16x32_bf16 v[12:15], v[106:109], v[138:141], v[12:15]
	v_mfma_f32_16x16x32_bf16 v[12:15], v[110:113], v[142:145], v[12:15]
	v_mfma_f32_16x16x32_bf16 v[4:7], v[106:109], v[146:149], v[4:7]
	v_mfma_f32_16x16x32_bf16 v[4:7], v[110:113], v[150:153], v[4:7]
	v_mfma_f32_16x16x32_bf16 v[40:43], v[114:117], v[122:125], v[40:43]
	v_mfma_f32_16x16x32_bf16 v[40:43], v[118:121], v[126:129], v[40:43]
	v_mfma_f32_16x16x32_bf16 v[24:27], v[114:117], v[130:133], v[24:27]
	v_mfma_f32_16x16x32_bf16 v[24:27], v[118:121], v[134:137], v[24:27]
	v_mfma_f32_16x16x32_bf16 v[8:11], v[114:117], v[138:141], v[8:11]
	v_mfma_f32_16x16x32_bf16 v[8:11], v[118:121], v[142:145], v[8:11]
	v_mfma_f32_16x16x32_bf16 v[0:3], v[114:117], v[146:149], v[0:3]
	v_mfma_f32_16x16x32_bf16 v[0:3], v[118:121], v[150:153], v[0:3]
	s_setprio 0
	s_barrier
	s_nop 1
	s_add_i32 s40, s60, s48
	v_lshl_add_u64 v[80:81], v[80:81], 0, s[22:23]
	s_mov_b32 m0, s40
	s_nop 0
	global_load_lds_dwordx4 v[80:81], off
	s_add_i32 m0, s40, 0x2000
	s_add_u32 s38, s38, 0x80080
	v_lshl_add_u64 v[80:81], v[154:155], 0, s[22:23]
	s_addc_u32 s39, s39, 0
	s_add_i32 s40, s61, s48
	global_load_lds_dwordx4 v[80:81], off
	v_lshl_add_u64 v[80:81], s[38:39], 0, v[64:65]
	s_mov_b32 m0, s40
	s_nop 0
	global_load_lds_dwordx4 v[80:81], off
	v_lshl_add_u64 v[80:81], s[38:39], 0, v[66:67]
	s_add_i32 m0, s40, 0x2000
	s_nop 0
	global_load_lds_dwordx4 v[80:81], off
	v_lshl_add_u64 v[80:81], v[156:157], 0, s[22:23]
	s_mov_b32 m0, s53
	s_nop 0
	global_load_lds_dwordx4 v[80:81], off
	v_lshl_add_u64 v[80:81], v[158:159], 0, s[22:23]
	s_mov_b32 m0, s54
	s_nop 0
	global_load_lds_dwordx4 v[80:81], off
	s_waitcnt vmcnt(8)
	s_waitcnt lgkmcnt(0)
	s_barrier
	s_setprio 1
	s_setprio 0
	s_setprio 1
	s_setprio 0
	s_barrier
	s_add_i32 s59, s59, 2
	s_add_u32 s36, s36, 0x100
	s_addc_u32 s37, s37, 0
	s_add_u32 s29, s29, 0x100
	s_addc_u32 s58, s58, 0
	s_cmp_gt_u32 s59, 29
	s_cbranch_scc0 .LBB0_254
	s_and_b64 vcc, exec, s[24:25]
	s_cbranch_vccz .LBB0_261
	s_barrier
	v_lshl_or_b32 v80, s18, 8, v85
	v_ashrrev_i32_e32 v81, 31, v80
	s_and_saveexec_b64 s[2:3], s[10:11]
	s_cbranch_execnz .LBB0_262

.LBB0_370:
	s_add_u32 s26, s18, 0x100
	s_addc_u32 s27, s19, 0
	s_cmp_eq_u32 s5, 30
	s_cselect_b32 s31, s40, s27
	s_cselect_b32 s30, s41, s26
	s_cselect_b32 s29, s57, s75
	s_cselect_b32 s28, s4, s15
	s_add_i32 s2, 0, 0x10000
	v_add_u32_e32 v152, s2, v154
	s_add_i32 vcc_lo, 0, 0x14000
	ds_read_b128 v[140:143], v152
	ds_read_b128 v[144:147], v152 offset:1024
	ds_read_b128 v[148:151], v152 offset:2048
	ds_read_b128 v[156:159], v152 offset:3072
	v_add_u32_e32 v152, vcc_lo, v154
	ds_read_b128 v[160:163], v152
	ds_read_b128 v[164:167], v152 offset:1024
	ds_read_b128 v[168:171], v152 offset:2048
	ds_read_b128 v[172:175], v152 offset:3072
	v_lshl_add_u64 v[152:153], s[18:19], 0, v[136:137]
	s_add_i32 m0, s63, 0xc000
	ds_read_b128 v[176:179], v155
	ds_read_b128 v[180:183], v155 offset:1024
	ds_read_b128 v[184:187], v155 offset:2048
	ds_read_b128 v[188:191], v155 offset:3072
	ds_read_b128 v[192:195], v155 offset:4096
	ds_read_b128 v[196:199], v155 offset:5120
	ds_read_b128 v[200:203], v155 offset:6144
	ds_read_b128 v[204:207], v155 offset:7168
	global_load_lds_dwordx4 v[152:153], off
	v_lshl_add_u64 v[152:153], s[18:19], 0, v[138:139]
	s_add_i32 m0, s63, 0xe000
	s_nop 0
	global_load_lds_dwordx4 v[152:153], off
	s_waitcnt vmcnt(8)
	s_waitcnt lgkmcnt(0)
	s_barrier
	s_setprio 1
	s_waitcnt lgkmcnt(0)
	v_mfma_f32_16x16x32_bf16 v[96:99], v[140:143], v[176:179], v[96:99]
	v_mfma_f32_16x16x32_bf16 v[96:99], v[144:147], v[180:183], v[96:99]
	v_mfma_f32_16x16x32_bf16 v[124:127], v[140:143], v[184:187], v[124:127]
	v_mfma_f32_16x16x32_bf16 v[124:127], v[144:147], v[188:191], v[124:127]
	v_mfma_f32_16x16x32_bf16 v[120:123], v[140:143], v[192:195], v[120:123]
	v_mfma_f32_16x16x32_bf16 v[120:123], v[144:147], v[196:199], v[120:123]
	v_mfma_f32_16x16x32_bf16 v[84:87], v[140:143], v[200:203], v[84:87]
	v_mfma_f32_16x16x32_bf16 v[84:87], v[144:147], v[204:207], v[84:87]
	v_mfma_f32_16x16x32_bf16 v[56:59], v[148:151], v[176:179], v[56:59]
	v_mfma_f32_16x16x32_bf16 v[56:59], v[156:159], v[180:183], v[56:59]
	v_mfma_f32_16x16x32_bf16 v[116:119], v[148:151], v[184:187], v[116:119]
	v_mfma_f32_16x16x32_bf16 v[116:119], v[156:159], v[188:191], v[116:119]
	v_mfma_f32_16x16x32_bf16 v[112:115], v[148:151], v[192:195], v[112:115]
	v_mfma_f32_16x16x32_bf16 v[112:115], v[156:159], v[196:199], v[112:115]
	v_mfma_f32_16x16x32_bf16 v[48:51], v[148:151], v[200:203], v[48:51]
	v_mfma_f32_16x16x32_bf16 v[48:51], v[156:159], v[204:207], v[48:51]
	s_setprio 0
	s_setprio 1
	v_mfma_f32_16x16x32_bf16 v[100:103], v[160:163], v[176:179], v[100:103]
	v_mfma_f32_16x16x32_bf16 v[100:103], v[164:167], v[180:183], v[100:103]
	v_mfma_f32_16x16x32_bf16 v[88:91], v[160:163], v[184:187], v[88:91]
	v_mfma_f32_16x16x32_bf16 v[88:91], v[164:167], v[188:191], v[88:91]
	v_mfma_f32_16x16x32_bf16 v[72:75], v[160:163], v[192:195], v[72:75]
	v_mfma_f32_16x16x32_bf16 v[72:75], v[164:167], v[196:199], v[72:75]
	v_mfma_f32_16x16x32_bf16 v[64:67], v[160:163], v[200:203], v[64:67]
	v_mfma_f32_16x16x32_bf16 v[64:67], v[164:167], v[204:207], v[64:67]
	v_mfma_f32_16x16x32_bf16 v[60:63], v[168:171], v[176:179], v[60:63]
	v_mfma_f32_16x16x32_bf16 v[60:63], v[172:175], v[180:183], v[60:63]
	v_mfma_f32_16x16x32_bf16 v[44:47], v[168:171], v[184:187], v[44:47]
	v_mfma_f32_16x16x32_bf16 v[44:47], v[172:175], v[188:191], v[44:47]
	v_mfma_f32_16x16x32_bf16 v[32:35], v[168:171], v[192:195], v[32:35]
	v_mfma_f32_16x16x32_bf16 v[32:35], v[172:175], v[196:199], v[32:35]
	v_mfma_f32_16x16x32_bf16 v[24:27], v[168:171], v[200:203], v[24:27]
	v_mfma_f32_16x16x32_bf16 v[24:27], v[172:175], v[204:207], v[24:27]
	s_setprio 0
	s_barrier
	s_nop 1
	s_add_i32 s2, s2, s69
	v_lshl_add_u64 v[152:153], s[28:29], 0, v[130:131]
	s_mov_b32 m0, s2
	ds_read_b128 v[176:179], v155 offset:16384
	ds_read_b128 v[180:183], v155 offset:17408
	ds_read_b128 v[184:187], v155 offset:18432
	ds_read_b128 v[188:191], v155 offset:19456
	ds_read_b128 v[192:195], v155 offset:20480
	ds_read_b128 v[196:199], v155 offset:21504
	ds_read_b128 v[200:203], v155 offset:22528
	ds_read_b128 v[204:207], v155 offset:23552
	global_load_lds_dwordx4 v[152:153], off
	s_add_i32 m0, s2, 0x2000
	s_add_u32 s2, s28, 0x80000
	v_lshl_add_u64 v[208:209], s[28:29], 0, v[134:135]
	s_addc_u32 s3, s29, 0
	s_add_i32 s18, vcc_lo, s69
	global_load_lds_dwordx4 v[208:209], off
	v_lshl_add_u64 v[210:211], s[2:3], 0, v[130:131]
	s_mov_b32 m0, s18
	v_lshl_add_u64 v[214:215], s[30:31], 0, v[132:133]
	global_load_lds_dwordx4 v[210:211], off
	v_lshl_add_u64 v[210:211], s[2:3], 0, v[134:135]
	s_add_i32 m0, s18, 0x2000
	s_nop 0
	global_load_lds_dwordx4 v[210:211], off
	v_lshl_add_u64 v[210:211], s[30:31], 0, v[128:129]
	s_mov_b32 m0, s63
	s_nop 0
	global_load_lds_dwordx4 v[210:211], off
	s_mov_b32 m0, s70
	s_nop 0
	global_load_lds_dwordx4 v[214:215], off
	s_waitcnt vmcnt(8)
	s_waitcnt lgkmcnt(0)
	s_barrier
	s_setprio 1
	s_waitcnt lgkmcnt(0)
	v_mfma_f32_16x16x32_bf16 v[92:95], v[140:143], v[176:179], v[92:95]
	v_mfma_f32_16x16x32_bf16 v[92:95], v[144:147], v[180:183], v[92:95]
	v_mfma_f32_16x16x32_bf16 v[108:111], v[140:143], v[184:187], v[108:111]
	v_mfma_f32_16x16x32_bf16 v[108:111], v[144:147], v[188:191], v[108:111]
	v_mfma_f32_16x16x32_bf16 v[104:107], v[140:143], v[192:195], v[104:107]
	v_mfma_f32_16x16x32_bf16 v[104:107], v[144:147], v[196:199], v[104:107]
	v_mfma_f32_16x16x32_bf16 v[76:79], v[140:143], v[200:203], v[76:79]
	v_mfma_f32_16x16x32_bf16 v[76:79], v[144:147], v[204:207], v[76:79]
	v_mfma_f32_16x16x32_bf16 v[52:55], v[148:151], v[176:179], v[52:55]
	v_mfma_f32_16x16x32_bf16 v[52:55], v[156:159], v[180:183], v[52:55]
	v_mfma_f32_16x16x32_bf16 v[80:83], v[148:151], v[184:187], v[80:83]
	v_mfma_f32_16x16x32_bf16 v[80:83], v[156:159], v[188:191], v[80:83]
	v_mfma_f32_16x16x32_bf16 v[68:71], v[148:151], v[192:195], v[68:71]
	v_mfma_f32_16x16x32_bf16 v[68:71], v[156:159], v[196:199], v[68:71]
	v_mfma_f32_16x16x32_bf16 v[36:39], v[148:151], v[200:203], v[36:39]
	v_mfma_f32_16x16x32_bf16 v[36:39], v[156:159], v[204:207], v[36:39]
	s_setprio 0
	s_setprio 1
	v_mfma_f32_16x16x32_bf16 v[40:43], v[160:163], v[176:179], v[40:43]
	v_mfma_f32_16x16x32_bf16 v[40:43], v[164:167], v[180:183], v[40:43]
	v_mfma_f32_16x16x32_bf16 v[28:31], v[160:163], v[184:187], v[28:31]
	v_mfma_f32_16x16x32_bf16 v[28:31], v[164:167], v[188:191], v[28:31]
	v_mfma_f32_16x16x32_bf16 v[20:23], v[160:163], v[192:195], v[20:23]
	v_mfma_f32_16x16x32_bf16 v[20:23], v[164:167], v[196:199], v[20:23]
	v_mfma_f32_16x16x32_bf16 v[16:19], v[160:163], v[200:203], v[16:19]
	v_mfma_f32_16x16x32_bf16 v[16:19], v[164:167], v[204:207], v[16:19]
	v_mfma_f32_16x16x32_bf16 v[12:15], v[168:171], v[176:179], v[12:15]
	v_mfma_f32_16x16x32_bf16 v[12:15], v[172:175], v[180:183], v[12:15]
	v_mfma_f32_16x16x32_bf16 v[8:11], v[168:171], v[184:187], v[8:11]
	v_mfma_f32_16x16x32_bf16 v[8:11], v[172:175], v[188:191], v[8:11]
	v_mfma_f32_16x16x32_bf16 v[4:7], v[168:171], v[192:195], v[4:7]
	v_mfma_f32_16x16x32_bf16 v[4:7], v[172:175], v[196:199], v[4:7]
	v_mfma_f32_16x16x32_bf16 v[0:3], v[168:171], v[200:203], v[0:3]
	v_mfma_f32_16x16x32_bf16 v[0:3], v[172:175], v[204:207], v[0:3]
	s_setprio 0
	s_barrier
	s_nop 1
	s_add_i32 s18, 0, 0x18000
	s_add_i32 s19, 0, 0x1c000
	v_add_u32_e32 v156, s18, v154
	v_add_u32_e32 v172, s19, v154
	ds_read_b128 v[140:143], v156
	ds_read_b128 v[144:147], v156 offset:1024
	ds_read_b128 v[148:151], v156 offset:2048
	ds_read_b128 v[156:159], v156 offset:3072
	ds_read_b128 v[160:163], v172
	ds_read_b128 v[164:167], v172 offset:1024
	ds_read_b128 v[168:171], v172 offset:2048
	ds_read_b128 v[172:175], v172 offset:3072
	s_add_u32 s2, s30, 0x80000
	s_addc_u32 s3, s31, 0
	s_mov_b32 m0, s71
	v_lshl_add_u64 v[216:217], s[2:3], 0, v[128:129]
	ds_read_b128 v[176:179], v155 offset:32768
	ds_read_b128 v[180:183], v155 offset:33792
	ds_read_b128 v[184:187], v155 offset:34816
	ds_read_b128 v[188:191], v155 offset:35840
	ds_read_b128 v[192:195], v155 offset:36864
	ds_read_b128 v[196:199], v155 offset:37888
	ds_read_b128 v[200:203], v155 offset:38912
	ds_read_b128 v[204:207], v155 offset:39936
	global_load_lds_dwordx4 v[216:217], off
	v_lshl_add_u64 v[216:217], s[2:3], 0, v[132:133]
	s_mov_b32 m0, s76
	s_nop 0
	global_load_lds_dwordx4 v[216:217], off
	s_waitcnt vmcnt(8)
	s_waitcnt lgkmcnt(0)
	s_barrier
	s_setprio 1
	s_waitcnt lgkmcnt(0)
	v_mfma_f32_16x16x32_bf16 v[96:99], v[140:143], v[176:179], v[96:99]
	v_mfma_f32_16x16x32_bf16 v[96:99], v[144:147], v[180:183], v[96:99]
	v_mfma_f32_16x16x32_bf16 v[124:127], v[140:143], v[184:187], v[124:127]
	v_mfma_f32_16x16x32_bf16 v[124:127], v[144:147], v[188:191], v[124:127]
	v_mfma_f32_16x16x32_bf16 v[120:123], v[140:143], v[192:195], v[120:123]
	v_mfma_f32_16x16x32_bf16 v[120:123], v[144:147], v[196:199], v[120:123]
	v_mfma_f32_16x16x32_bf16 v[84:87], v[140:143], v[200:203], v[84:87]
	v_mfma_f32_16x16x32_bf16 v[84:87], v[144:147], v[204:207], v[84:87]
	v_mfma_f32_16x16x32_bf16 v[56:59], v[148:151], v[176:179], v[56:59]
	v_mfma_f32_16x16x32_bf16 v[56:59], v[156:159], v[180:183], v[56:59]
	v_mfma_f32_16x16x32_bf16 v[116:119], v[148:151], v[184:187], v[116:119]
	v_mfma_f32_16x16x32_bf16 v[116:119], v[156:159], v[188:191], v[116:119]
	v_mfma_f32_16x16x32_bf16 v[112:115], v[148:151], v[192:195], v[112:115]
	v_mfma_f32_16x16x32_bf16 v[112:115], v[156:159], v[196:199], v[112:115]
	v_mfma_f32_16x16x32_bf16 v[48:51], v[148:151], v[200:203], v[48:51]
	v_mfma_f32_16x16x32_bf16 v[48:51], v[156:159], v[204:207], v[48:51]
	s_setprio 0
	s_setprio 1
	v_mfma_f32_16x16x32_bf16 v[100:103], v[160:163], v[176:179], v[100:103]
	v_mfma_f32_16x16x32_bf16 v[100:103], v[164:167], v[180:183], v[100:103]
	v_mfma_f32_16x16x32_bf16 v[88:91], v[160:163], v[184:187], v[88:91]
	v_mfma_f32_16x16x32_bf16 v[88:91], v[164:167], v[188:191], v[88:91]
	v_mfma_f32_16x16x32_bf16 v[72:75], v[160:163], v[192:195], v[72:75]
	v_mfma_f32_16x16x32_bf16 v[72:75], v[164:167], v[196:199], v[72:75]
	v_mfma_f32_16x16x32_bf16 v[64:67], v[160:163], v[200:203], v[64:67]
	v_mfma_f32_16x16x32_bf16 v[64:67], v[164:167], v[204:207], v[64:67]
	v_mfma_f32_16x16x32_bf16 v[60:63], v[168:171], v[176:179], v[60:63]
	v_mfma_f32_16x16x32_bf16 v[60:63], v[172:175], v[180:183], v[60:63]
	v_mfma_f32_16x16x32_bf16 v[44:47], v[168:171], v[184:187], v[44:47]
	v_mfma_f32_16x16x32_bf16 v[44:47], v[172:175], v[188:191], v[44:47]
	v_mfma_f32_16x16x32_bf16 v[32:35], v[168:171], v[192:195], v[32:35]
	v_mfma_f32_16x16x32_bf16 v[32:35], v[172:175], v[196:199], v[32:35]
	v_mfma_f32_16x16x32_bf16 v[24:27], v[168:171], v[200:203], v[24:27]
	v_mfma_f32_16x16x32_bf16 v[24:27], v[172:175], v[204:207], v[24:27]
	s_setprio 0
	s_barrier
	s_nop 1
	s_add_i32 s2, s18, s69
	v_lshl_add_u64 v[152:153], v[152:153], 0, s[72:73]
	s_mov_b32 m0, s2
	ds_read_b128 v[176:179], v155 offset:49152
	ds_read_b128 v[180:183], v155 offset:50176
	ds_read_b128 v[184:187], v155 offset:51200
	ds_read_b128 v[188:191], v155 offset:52224
	ds_read_b128 v[192:195], v155 offset:53248
	ds_read_b128 v[196:199], v155 offset:54272
	ds_read_b128 v[200:203], v155 offset:55296
	ds_read_b128 v[204:207], v155 offset:56320
	global_load_lds_dwordx4 v[152:153], off
	s_add_i32 m0, s2, 0x2000
	s_add_u32 s2, s28, 0x80080
	v_lshl_add_u64 v[152:153], v[208:209], 0, s[72:73]
	s_addc_u32 s3, s29, 0
	s_add_i32 s18, s19, s69
	global_load_lds_dwordx4 v[152:153], off
	v_lshl_add_u64 v[152:153], s[2:3], 0, v[130:131]
	s_mov_b32 m0, s18
	s_nop 0
	global_load_lds_dwordx4 v[152:153], off
	v_lshl_add_u64 v[152:153], s[2:3], 0, v[134:135]
	s_add_i32 m0, s18, 0x2000
	s_nop 0
	global_load_lds_dwordx4 v[152:153], off
	v_lshl_add_u64 v[152:153], v[210:211], 0, s[72:73]
	s_mov_b32 m0, s87
	s_nop 0
	global_load_lds_dwordx4 v[152:153], off
	v_lshl_add_u64 v[152:153], v[214:215], 0, s[72:73]
	s_mov_b32 m0, s88
	s_nop 0
	global_load_lds_dwordx4 v[152:153], off
	s_waitcnt vmcnt(8)
	s_waitcnt lgkmcnt(0)
	s_barrier
	s_setprio 1
	s_waitcnt lgkmcnt(0)
	v_mfma_f32_16x16x32_bf16 v[92:95], v[140:143], v[176:179], v[92:95]
	v_mfma_f32_16x16x32_bf16 v[92:95], v[144:147], v[180:183], v[92:95]
	v_mfma_f32_16x16x32_bf16 v[108:111], v[140:143], v[184:187], v[108:111]
	v_mfma_f32_16x16x32_bf16 v[108:111], v[144:147], v[188:191], v[108:111]
	v_mfma_f32_16x16x32_bf16 v[104:107], v[140:143], v[192:195], v[104:107]
	v_mfma_f32_16x16x32_bf16 v[104:107], v[144:147], v[196:199], v[104:107]
	v_mfma_f32_16x16x32_bf16 v[76:79], v[140:143], v[200:203], v[76:79]
	v_mfma_f32_16x16x32_bf16 v[76:79], v[144:147], v[204:207], v[76:79]
	v_mfma_f32_16x16x32_bf16 v[52:55], v[148:151], v[176:179], v[52:55]
	v_mfma_f32_16x16x32_bf16 v[52:55], v[156:159], v[180:183], v[52:55]
	v_mfma_f32_16x16x32_bf16 v[80:83], v[148:151], v[184:187], v[80:83]
	v_mfma_f32_16x16x32_bf16 v[80:83], v[156:159], v[188:191], v[80:83]
	v_mfma_f32_16x16x32_bf16 v[68:71], v[148:151], v[192:195], v[68:71]
	v_mfma_f32_16x16x32_bf16 v[68:71], v[156:159], v[196:199], v[68:71]
	v_mfma_f32_16x16x32_bf16 v[36:39], v[148:151], v[200:203], v[36:39]
	v_mfma_f32_16x16x32_bf16 v[36:39], v[156:159], v[204:207], v[36:39]
	s_setprio 0
	s_setprio 1
	v_mfma_f32_16x16x32_bf16 v[40:43], v[160:163], v[176:179], v[40:43]
	v_mfma_f32_16x16x32_bf16 v[40:43], v[164:167], v[180:183], v[40:43]
	v_mfma_f32_16x16x32_bf16 v[28:31], v[160:163], v[184:187], v[28:31]
	v_mfma_f32_16x16x32_bf16 v[28:31], v[164:167], v[188:191], v[28:31]
	v_mfma_f32_16x16x32_bf16 v[20:23], v[160:163], v[192:195], v[20:23]
	v_mfma_f32_16x16x32_bf16 v[20:23], v[164:167], v[196:199], v[20:23]
	v_mfma_f32_16x16x32_bf16 v[16:19], v[160:163], v[200:203], v[16:19]
	v_mfma_f32_16x16x32_bf16 v[16:19], v[164:167], v[204:207], v[16:19]
	v_mfma_f32_16x16x32_bf16 v[12:15], v[168:171], v[176:179], v[12:15]
	v_mfma_f32_16x16x32_bf16 v[12:15], v[172:175], v[180:183], v[12:15]
	v_mfma_f32_16x16x32_bf16 v[8:11], v[168:171], v[184:187], v[8:11]
	v_mfma_f32_16x16x32_bf16 v[8:11], v[172:175], v[188:191], v[8:11]
	v_mfma_f32_16x16x32_bf16 v[4:7], v[168:171], v[192:195], v[4:7]
	v_mfma_f32_16x16x32_bf16 v[4:7], v[172:175], v[196:199], v[4:7]
	v_mfma_f32_16x16x32_bf16 v[0:3], v[168:171], v[200:203], v[0:3]
	v_mfma_f32_16x16x32_bf16 v[0:3], v[172:175], v[204:207], v[0:3]
	s_setprio 0
	s_barrier
	s_nop 1
	s_add_i32 s2, s5, 2
	s_add_u32 s15, s15, 0x100
	s_addc_u32 s75, s75, 0
	s_cmp_gt_u32 s5, 29
	s_mov_b64 s[18:19], s[26:27]
	s_mov_b32 s5, s2
	s_cbranch_scc1 .LBB0_384

.LBB0_486:
	s_add_u32 s18, s16, 0xfff80080
	s_addc_u32 s19, s17, -1
	s_add_i32 s46, 0, 0x10000
	s_cmp_eq_u32 s37, 28
	s_cselect_b32 s21, s5, s19
	s_cselect_b32 s20, s4, s18
	v_add_u32_e32 v78, s46, v80
	s_cselect_b32 s19, s3, s36
	s_cselect_b32 s18, s7, s35
	s_add_i32 s49, 0, 0x14000
	ds_read_b128 v[84:87], v78
	ds_read_b128 v[88:91], v78 offset:1024
	ds_read_b128 v[92:95], v78 offset:2048
	ds_read_b128 v[96:99], v78 offset:3072
	v_add_u32_e32 v78, s49, v80
	ds_read_b128 v[100:103], v78
	ds_read_b128 v[104:107], v78 offset:1024
	ds_read_b128 v[108:111], v78 offset:2048
	ds_read_b128 v[112:115], v78 offset:3072
	v_lshl_add_u64 v[78:79], s[16:17], 0, v[74:75]
	s_add_i32 m0, s25, 0xc000
	ds_read_b128 v[116:119], v82
	ds_read_b128 v[120:123], v82 offset:1024
	ds_read_b128 v[124:127], v82 offset:2048
	ds_read_b128 v[128:131], v82 offset:3072
	ds_read_b128 v[132:135], v82 offset:4096
	ds_read_b128 v[136:139], v82 offset:5120
	ds_read_b128 v[140:143], v82 offset:6144
	ds_read_b128 v[144:147], v82 offset:7168
	global_load_lds_dwordx4 v[78:79], off
	v_lshl_add_u64 v[78:79], s[16:17], 0, v[76:77]
	s_add_i32 m0, s25, 0xe000
	s_nop 0
	global_load_lds_dwordx4 v[78:79], off
	s_waitcnt vmcnt(8)
	s_waitcnt lgkmcnt(0)
	s_barrier
	s_setprio 1
	s_waitcnt lgkmcnt(0)
	v_mfma_f32_16x16x32_bf16 v[60:63], v[84:87], v[116:119], v[60:63]
	v_mfma_f32_16x16x32_bf16 v[60:63], v[88:91], v[120:123], v[60:63]
	v_mfma_f32_16x16x32_bf16 v[52:55], v[84:87], v[124:127], v[52:55]
	v_mfma_f32_16x16x32_bf16 v[52:55], v[88:91], v[128:131], v[52:55]
	v_mfma_f32_16x16x32_bf16 v[36:39], v[84:87], v[132:135], v[36:39]
	v_mfma_f32_16x16x32_bf16 v[36:39], v[88:91], v[136:139], v[36:39]
	v_mfma_f32_16x16x32_bf16 v[20:23], v[84:87], v[140:143], v[20:23]
	v_mfma_f32_16x16x32_bf16 v[20:23], v[88:91], v[144:147], v[20:23]
	v_mfma_f32_16x16x32_bf16 v[56:59], v[92:95], v[116:119], v[56:59]
	v_mfma_f32_16x16x32_bf16 v[56:59], v[96:99], v[120:123], v[56:59]
	v_mfma_f32_16x16x32_bf16 v[48:51], v[92:95], v[124:127], v[48:51]
	v_mfma_f32_16x16x32_bf16 v[48:51], v[96:99], v[128:131], v[48:51]
	v_mfma_f32_16x16x32_bf16 v[32:35], v[92:95], v[132:135], v[32:35]
	v_mfma_f32_16x16x32_bf16 v[32:35], v[96:99], v[136:139], v[32:35]
	v_mfma_f32_16x16x32_bf16 v[16:19], v[92:95], v[140:143], v[16:19]
	v_mfma_f32_16x16x32_bf16 v[16:19], v[96:99], v[144:147], v[16:19]
	s_setprio 0
	s_setprio 1
	v_mfma_f32_16x16x32_bf16 v[44:47], v[100:103], v[116:119], v[44:47]
	v_mfma_f32_16x16x32_bf16 v[44:47], v[104:107], v[120:123], v[44:47]
	v_mfma_f32_16x16x32_bf16 v[28:31], v[100:103], v[124:127], v[28:31]
	v_mfma_f32_16x16x32_bf16 v[28:31], v[104:107], v[128:131], v[28:31]
	v_mfma_f32_16x16x32_bf16 v[12:15], v[100:103], v[132:135], v[12:15]
	v_mfma_f32_16x16x32_bf16 v[12:15], v[104:107], v[136:139], v[12:15]
	v_mfma_f32_16x16x32_bf16 v[4:7], v[100:103], v[140:143], v[4:7]
	v_mfma_f32_16x16x32_bf16 v[4:7], v[104:107], v[144:147], v[4:7]
	v_mfma_f32_16x16x32_bf16 v[40:43], v[108:111], v[116:119], v[40:43]
	v_mfma_f32_16x16x32_bf16 v[40:43], v[112:115], v[120:123], v[40:43]
	v_mfma_f32_16x16x32_bf16 v[24:27], v[108:111], v[124:127], v[24:27]
	v_mfma_f32_16x16x32_bf16 v[24:27], v[112:115], v[128:131], v[24:27]
	v_mfma_f32_16x16x32_bf16 v[8:11], v[108:111], v[132:135], v[8:11]
	v_mfma_f32_16x16x32_bf16 v[8:11], v[112:115], v[136:139], v[8:11]
	v_mfma_f32_16x16x32_bf16 v[0:3], v[108:111], v[140:143], v[0:3]
	v_mfma_f32_16x16x32_bf16 v[0:3], v[112:115], v[144:147], v[0:3]
	s_setprio 0
	s_barrier
	s_nop 1
	s_add_i32 s46, s46, s24
	v_lshl_add_u64 v[78:79], s[18:19], 0, v[212:213]
	s_mov_b32 m0, s46
	v_lshl_add_u64 v[148:149], s[18:19], 0, v[64:65]
	global_load_lds_dwordx4 v[78:79], off
	s_add_i32 m0, s46, 0x2000
	s_add_u32 s46, s18, 0x80000
	s_addc_u32 s47, s19, 0
	s_add_i32 s49, s49, s24
	global_load_lds_dwordx4 v[148:149], off
	v_lshl_add_u64 v[84:85], s[46:47], 0, v[212:213]
	s_mov_b32 m0, s49
	v_lshl_add_u64 v[150:151], s[20:21], 0, v[212:213]
	global_load_lds_dwordx4 v[84:85], off
	v_lshl_add_u64 v[84:85], s[46:47], 0, v[64:65]
	s_add_i32 m0, s49, 0x2000
	v_lshl_add_u64 v[152:153], s[20:21], 0, v[64:65]
	global_load_lds_dwordx4 v[84:85], off
	s_mov_b32 m0, s25
	s_nop 0
	global_load_lds_dwordx4 v[150:151], off
	s_mov_b32 m0, s28
	s_nop 0
	global_load_lds_dwordx4 v[152:153], off
	s_waitcnt vmcnt(8)
	s_waitcnt lgkmcnt(0)
	s_barrier
	s_setprio 1
	s_setprio 0
	s_setprio 1
	s_setprio 0
	s_barrier
	s_add_i32 s46, 0, 0x18000
	v_add_u32_e32 v83, s46, v80
	s_add_i32 s47, 0, 0x1c000
	ds_read_b128 v[84:87], v83
	ds_read_b128 v[88:91], v83 offset:1024
	ds_read_b128 v[92:95], v83 offset:2048
	ds_read_b128 v[96:99], v83 offset:3072
	v_add_u32_e32 v83, s47, v80
	ds_read_b128 v[100:103], v83
	ds_read_b128 v[104:107], v83 offset:1024
	ds_read_b128 v[108:111], v83 offset:2048
	ds_read_b128 v[112:115], v83 offset:3072
	s_add_u32 s20, s20, 0x80000
	s_addc_u32 s21, s21, 0
	s_mov_b32 m0, s29
	v_lshl_add_u64 v[154:155], s[20:21], 0, v[212:213]
	ds_read_b128 v[116:119], v82 offset:32768
	ds_read_b128 v[120:123], v82 offset:33792
	ds_read_b128 v[124:127], v82 offset:34816
	ds_read_b128 v[128:131], v82 offset:35840
	ds_read_b128 v[132:135], v82 offset:36864
	ds_read_b128 v[136:139], v82 offset:37888
	ds_read_b128 v[140:143], v82 offset:38912
	ds_read_b128 v[144:147], v82 offset:39936
	global_load_lds_dwordx4 v[154:155], off
	v_lshl_add_u64 v[154:155], s[20:21], 0, v[64:65]
	s_mov_b32 m0, s30
	s_nop 0
	global_load_lds_dwordx4 v[154:155], off
	s_waitcnt vmcnt(8)
	s_waitcnt lgkmcnt(0)
	s_barrier
	s_setprio 1
	s_waitcnt lgkmcnt(0)
	v_mfma_f32_16x16x32_bf16 v[60:63], v[84:87], v[116:119], v[60:63]
	v_mfma_f32_16x16x32_bf16 v[60:63], v[88:91], v[120:123], v[60:63]
	v_mfma_f32_16x16x32_bf16 v[52:55], v[84:87], v[124:127], v[52:55]
	v_mfma_f32_16x16x32_bf16 v[52:55], v[88:91], v[128:131], v[52:55]
	v_mfma_f32_16x16x32_bf16 v[36:39], v[84:87], v[132:135], v[36:39]
	v_mfma_f32_16x16x32_bf16 v[36:39], v[88:91], v[136:139], v[36:39]
	v_mfma_f32_16x16x32_bf16 v[20:23], v[84:87], v[140:143], v[20:23]
	v_mfma_f32_16x16x32_bf16 v[20:23], v[88:91], v[144:147], v[20:23]
	v_mfma_f32_16x16x32_bf16 v[56:59], v[92:95], v[116:119], v[56:59]
	v_mfma_f32_16x16x32_bf16 v[56:59], v[96:99], v[120:123], v[56:59]
	v_mfma_f32_16x16x32_bf16 v[48:51], v[92:95], v[124:127], v[48:51]
	v_mfma_f32_16x16x32_bf16 v[48:51], v[96:99], v[128:131], v[48:51]
	v_mfma_f32_16x16x32_bf16 v[32:35], v[92:95], v[132:135], v[32:35]
	v_mfma_f32_16x16x32_bf16 v[32:35], v[96:99], v[136:139], v[32:35]
	v_mfma_f32_16x16x32_bf16 v[16:19], v[92:95], v[140:143], v[16:19]
	v_mfma_f32_16x16x32_bf16 v[16:19], v[96:99], v[144:147], v[16:19]
	s_setprio 0
	s_setprio 1
	v_mfma_f32_16x16x32_bf16 v[44:47], v[100:103], v[116:119], v[44:47]
	v_mfma_f32_16x16x32_bf16 v[44:47], v[104:107], v[120:123], v[44:47]
	v_mfma_f32_16x16x32_bf16 v[28:31], v[100:103], v[124:127], v[28:31]
	v_mfma_f32_16x16x32_bf16 v[28:31], v[104:107], v[128:131], v[28:31]
	v_mfma_f32_16x16x32_bf16 v[12:15], v[100:103], v[132:135], v[12:15]
	v_mfma_f32_16x16x32_bf16 v[12:15], v[104:107], v[136:139], v[12:15]
	v_mfma_f32_16x16x32_bf16 v[4:7], v[100:103], v[140:143], v[4:7]
	v_mfma_f32_16x16x32_bf16 v[4:7], v[104:107], v[144:147], v[4:7]
	v_mfma_f32_16x16x32_bf16 v[40:43], v[108:111], v[116:119], v[40:43]
	v_mfma_f32_16x16x32_bf16 v[40:43], v[112:115], v[120:123], v[40:43]
	v_mfma_f32_16x16x32_bf16 v[24:27], v[108:111], v[124:127], v[24:27]
	v_mfma_f32_16x16x32_bf16 v[24:27], v[112:115], v[128:131], v[24:27]
	v_mfma_f32_16x16x32_bf16 v[8:11], v[108:111], v[132:135], v[8:11]
	v_mfma_f32_16x16x32_bf16 v[8:11], v[112:115], v[136:139], v[8:11]
	v_mfma_f32_16x16x32_bf16 v[0:3], v[108:111], v[140:143], v[0:3]
	v_mfma_f32_16x16x32_bf16 v[0:3], v[112:115], v[144:147], v[0:3]
	s_setprio 0
	s_barrier
	s_nop 1
	s_add_i32 s20, s46, s24
	v_lshl_add_u64 v[78:79], v[78:79], 0, s[72:73]
	s_mov_b32 m0, s20
	s_nop 0
	global_load_lds_dwordx4 v[78:79], off
	s_add_i32 m0, s20, 0x2000
	s_add_u32 s18, s18, 0x80080
	v_lshl_add_u64 v[78:79], v[148:149], 0, s[72:73]
	s_addc_u32 s19, s19, 0
	s_add_i32 s20, s47, s24
	global_load_lds_dwordx4 v[78:79], off
	v_lshl_add_u64 v[78:79], s[18:19], 0, v[212:213]
	s_mov_b32 m0, s20
	s_nop 0
	global_load_lds_dwordx4 v[78:79], off
	v_lshl_add_u64 v[78:79], s[18:19], 0, v[64:65]
	s_add_i32 m0, s20, 0x2000
	s_nop 0
	global_load_lds_dwordx4 v[78:79], off
	v_lshl_add_u64 v[78:79], v[150:151], 0, s[72:73]
	s_mov_b32 m0, s31
	s_nop 0
	global_load_lds_dwordx4 v[78:79], off
	v_lshl_add_u64 v[78:79], v[152:153], 0, s[72:73]
	s_mov_b32 m0, s33
	s_nop 0
	global_load_lds_dwordx4 v[78:79], off
	s_waitcnt vmcnt(8)
	s_waitcnt lgkmcnt(0)
	s_barrier
	s_setprio 1
	s_setprio 0
	s_setprio 1
	s_setprio 0
	s_barrier
	s_add_i32 s37, s37, 2
	s_add_u32 s16, s16, 0x100
	s_addc_u32 s17, s17, 0
	s_add_u32 s35, s35, 0x100
	s_addc_u32 s36, s36, 0
	s_cmp_gt_u32 s37, 29
	s_cbranch_scc0 .LBB0_486
	s_and_b64 vcc, exec, s[12:13]
	s_cbranch_vccz .LBB0_493
	s_barrier
	v_lshl_or_b32 v78, s2, 8, v81
	v_ashrrev_i32_e32 v79, 31, v78
	s_and_saveexec_b64 s[2:3], s[38:39]
	s_cbranch_execnz .LBB0_494

.LBB0_659:
	s_add_i32 s2, s41, 2
	s_add_u32 s3, s10, s34
	s_addc_u32 s50, s11, s35
	s_add_u32 s3, s3, 0x100
	s_addc_u32 s50, s50, 0
	s_add_u32 s51, s9, s34
	s_addc_u32 s75, s19, s35
	s_cmp_eq_u32 s45, s41
	s_cselect_b32 s89, s17, s50
	s_cselect_b32 s88, s16, s3
	s_cselect_b32 vcc_hi, s13, s75
	s_cselect_b32 vcc_lo, s12, s51
	s_add_i32 s3, 0, 0x10000
	s_add_i32 s41, 0, 0x14000
	v_add_u32_e32 v136, s3, v220
	v_add_u32_e32 v160, s41, v220
	ds_read_b128 v[108:111], v136
	ds_read_b128 v[120:123], v136 offset:1024
	ds_read_b128 v[132:135], v136 offset:2048
	ds_read_b128 v[136:139], v136 offset:3072
	ds_read_b128 v[140:143], v160
	ds_read_b128 v[144:147], v160 offset:1024
	ds_read_b128 v[148:151], v160 offset:2048
	ds_read_b128 v[160:163], v160 offset:3072
	v_lshl_add_u64 v[196:197], v[96:97], 0, s[34:35]
	s_add_i32 m0, s15, 0xc000
	ds_read_b128 v[164:167], v223
	ds_read_b128 v[168:171], v223 offset:1024
	ds_read_b128 v[172:175], v223 offset:2048
	ds_read_b128 v[176:179], v223 offset:3072
	ds_read_b128 v[180:183], v223 offset:4096
	ds_read_b128 v[184:187], v223 offset:5120
	ds_read_b128 v[188:191], v223 offset:6144
	ds_read_b128 v[192:195], v223 offset:7168
	global_load_lds_dwordx4 v[196:197], off
	v_lshl_add_u64 v[196:197], v[98:99], 0, s[34:35]
	s_add_i32 m0, s15, 0xe000
	s_nop 0
	global_load_lds_dwordx4 v[196:197], off
	s_waitcnt vmcnt(8)
	s_waitcnt lgkmcnt(0)
	s_barrier
	s_setprio 1
	s_waitcnt lgkmcnt(0)
	v_mfma_f32_16x16x32_bf16 v[156:159], v[108:111], v[164:167], v[156:159]
	v_mfma_f32_16x16x32_bf16 v[156:159], v[120:123], v[168:171], v[156:159]
	v_mfma_f32_16x16x32_bf16 v[128:131], v[108:111], v[172:175], v[128:131]
	v_mfma_f32_16x16x32_bf16 v[128:131], v[120:123], v[176:179], v[128:131]
	v_mfma_f32_16x16x32_bf16 v[116:119], v[108:111], v[180:183], v[116:119]
	v_mfma_f32_16x16x32_bf16 v[116:119], v[120:123], v[184:187], v[116:119]
	v_mfma_f32_16x16x32_bf16 v[104:107], v[108:111], v[188:191], v[104:107]
	v_mfma_f32_16x16x32_bf16 v[104:107], v[120:123], v[192:195], v[104:107]
	v_mfma_f32_16x16x32_bf16 v[152:155], v[132:135], v[164:167], v[152:155]
	v_mfma_f32_16x16x32_bf16 v[152:155], v[136:139], v[168:171], v[152:155]
	v_mfma_f32_16x16x32_bf16 v[124:127], v[132:135], v[172:175], v[124:127]
	v_mfma_f32_16x16x32_bf16 v[124:127], v[136:139], v[176:179], v[124:127]
	v_mfma_f32_16x16x32_bf16 v[112:115], v[132:135], v[180:183], v[112:115]
	v_mfma_f32_16x16x32_bf16 v[112:115], v[136:139], v[184:187], v[112:115]
	v_mfma_f32_16x16x32_bf16 v[100:103], v[132:135], v[188:191], v[100:103]
	v_mfma_f32_16x16x32_bf16 v[100:103], v[136:139], v[192:195], v[100:103]
	s_setprio 0
	s_setprio 1
	v_mfma_f32_16x16x32_bf16 v[92:95], v[140:143], v[164:167], v[92:95]
	v_mfma_f32_16x16x32_bf16 v[92:95], v[144:147], v[168:171], v[92:95]
	v_mfma_f32_16x16x32_bf16 v[84:87], v[140:143], v[172:175], v[84:87]
	v_mfma_f32_16x16x32_bf16 v[84:87], v[144:147], v[176:179], v[84:87]
	v_mfma_f32_16x16x32_bf16 v[76:79], v[140:143], v[180:183], v[76:79]
	v_mfma_f32_16x16x32_bf16 v[76:79], v[144:147], v[184:187], v[76:79]
	v_mfma_f32_16x16x32_bf16 v[68:71], v[140:143], v[188:191], v[68:71]
	v_mfma_f32_16x16x32_bf16 v[68:71], v[144:147], v[192:195], v[68:71]
	v_mfma_f32_16x16x32_bf16 v[88:91], v[148:151], v[164:167], v[88:91]
	v_mfma_f32_16x16x32_bf16 v[88:91], v[160:163], v[168:171], v[88:91]
	v_mfma_f32_16x16x32_bf16 v[80:83], v[148:151], v[172:175], v[80:83]
	v_mfma_f32_16x16x32_bf16 v[80:83], v[160:163], v[176:179], v[80:83]
	v_mfma_f32_16x16x32_bf16 v[72:75], v[148:151], v[180:183], v[72:75]
	v_mfma_f32_16x16x32_bf16 v[72:75], v[160:163], v[184:187], v[72:75]
	v_mfma_f32_16x16x32_bf16 v[64:67], v[148:151], v[188:191], v[64:67]
	v_mfma_f32_16x16x32_bf16 v[64:67], v[160:163], v[192:195], v[64:67]
	s_setprio 0
	s_barrier
	s_nop 1
	s_add_i32 s3, s3, s64
	v_lshl_add_u64 v[196:197], vcc, 0, v[212:213]
	s_mov_b32 m0, s3
	ds_read_b128 v[164:167], v223 offset:16384
	ds_read_b128 v[168:171], v223 offset:17408
	ds_read_b128 v[172:175], v223 offset:18432
	ds_read_b128 v[176:179], v223 offset:19456
	ds_read_b128 v[180:183], v223 offset:20480
	ds_read_b128 v[184:187], v223 offset:21504
	ds_read_b128 v[188:191], v223 offset:22528
	ds_read_b128 v[192:195], v223 offset:23552
	global_load_lds_dwordx4 v[196:197], off
	s_add_i32 m0, s3, 0x2000
	s_add_u32 s50, vcc_lo, 0x80000
	v_lshl_add_u64 v[198:199], vcc, 0, v[208:209]
	s_addc_u32 s51, vcc_hi, 0
	s_add_i32 s3, s41, s64
	global_load_lds_dwordx4 v[198:199], off
	v_lshl_add_u64 v[200:201], s[50:51], 0, v[212:213]
	s_mov_b32 m0, s3
	v_lshl_add_u64 v[202:203], s[88:89], 0, v[206:207]
	global_load_lds_dwordx4 v[200:201], off
	v_lshl_add_u64 v[200:201], s[50:51], 0, v[208:209]
	s_add_i32 m0, s3, 0x2000
	s_nop 0
	global_load_lds_dwordx4 v[200:201], off
	v_lshl_add_u64 v[200:201], s[88:89], 0, v[204:205]
	s_mov_b32 m0, s15
	s_nop 0
	global_load_lds_dwordx4 v[200:201], off
	s_mov_b32 m0, s43
	s_nop 0
	global_load_lds_dwordx4 v[202:203], off
	s_waitcnt vmcnt(8)
	s_waitcnt lgkmcnt(0)
	s_barrier
	s_setprio 1
	s_waitcnt lgkmcnt(0)
	v_mfma_f32_16x16x32_bf16 v[60:63], v[108:111], v[164:167], v[60:63]
	v_mfma_f32_16x16x32_bf16 v[60:63], v[120:123], v[168:171], v[60:63]
	v_mfma_f32_16x16x32_bf16 v[52:55], v[108:111], v[172:175], v[52:55]
	v_mfma_f32_16x16x32_bf16 v[52:55], v[120:123], v[176:179], v[52:55]
	v_mfma_f32_16x16x32_bf16 v[44:47], v[108:111], v[180:183], v[44:47]
	v_mfma_f32_16x16x32_bf16 v[44:47], v[120:123], v[184:187], v[44:47]
	v_mfma_f32_16x16x32_bf16 v[36:39], v[108:111], v[188:191], v[36:39]
	v_mfma_f32_16x16x32_bf16 v[36:39], v[120:123], v[192:195], v[36:39]
	v_mfma_f32_16x16x32_bf16 v[56:59], v[132:135], v[164:167], v[56:59]
	v_mfma_f32_16x16x32_bf16 v[56:59], v[136:139], v[168:171], v[56:59]
	v_mfma_f32_16x16x32_bf16 v[48:51], v[132:135], v[172:175], v[48:51]
	v_mfma_f32_16x16x32_bf16 v[48:51], v[136:139], v[176:179], v[48:51]
	v_mfma_f32_16x16x32_bf16 v[40:43], v[132:135], v[180:183], v[40:43]
	v_mfma_f32_16x16x32_bf16 v[40:43], v[136:139], v[184:187], v[40:43]
	v_mfma_f32_16x16x32_bf16 v[32:35], v[132:135], v[188:191], v[32:35]
	v_mfma_f32_16x16x32_bf16 v[32:35], v[136:139], v[192:195], v[32:35]
	s_setprio 0
	s_setprio 1
	v_mfma_f32_16x16x32_bf16 v[28:31], v[140:143], v[164:167], v[28:31]
	v_mfma_f32_16x16x32_bf16 v[28:31], v[144:147], v[168:171], v[28:31]
	v_mfma_f32_16x16x32_bf16 v[20:23], v[140:143], v[172:175], v[20:23]
	v_mfma_f32_16x16x32_bf16 v[20:23], v[144:147], v[176:179], v[20:23]
	v_mfma_f32_16x16x32_bf16 v[12:15], v[140:143], v[180:183], v[12:15]
	v_mfma_f32_16x16x32_bf16 v[12:15], v[144:147], v[184:187], v[12:15]
	v_mfma_f32_16x16x32_bf16 v[4:7], v[140:143], v[188:191], v[4:7]
	v_mfma_f32_16x16x32_bf16 v[4:7], v[144:147], v[192:195], v[4:7]
	v_mfma_f32_16x16x32_bf16 v[24:27], v[148:151], v[164:167], v[24:27]
	v_mfma_f32_16x16x32_bf16 v[24:27], v[160:163], v[168:171], v[24:27]
	v_mfma_f32_16x16x32_bf16 v[16:19], v[148:151], v[172:175], v[16:19]
	v_mfma_f32_16x16x32_bf16 v[16:19], v[160:163], v[176:179], v[16:19]
	v_mfma_f32_16x16x32_bf16 v[8:11], v[148:151], v[180:183], v[8:11]
	v_mfma_f32_16x16x32_bf16 v[8:11], v[160:163], v[184:187], v[8:11]
	v_mfma_f32_16x16x32_bf16 v[0:3], v[148:151], v[188:191], v[0:3]
	v_mfma_f32_16x16x32_bf16 v[0:3], v[160:163], v[192:195], v[0:3]
	s_setprio 0
	s_barrier
	s_nop 1
	s_add_i32 s3, 0, 0x18000
	s_add_i32 s41, 0, 0x1c000
	v_add_u32_e32 v136, s3, v220
	v_add_u32_e32 v160, s41, v220
	ds_read_b128 v[108:111], v136
	ds_read_b128 v[120:123], v136 offset:1024
	ds_read_b128 v[132:135], v136 offset:2048
	ds_read_b128 v[136:139], v136 offset:3072
	ds_read_b128 v[140:143], v160
	ds_read_b128 v[144:147], v160 offset:1024
	ds_read_b128 v[148:151], v160 offset:2048
	ds_read_b128 v[160:163], v160 offset:3072
	s_add_u32 s50, s88, 0x80000
	s_addc_u32 s51, s89, 0
	s_mov_b32 m0, s69
	v_lshl_add_u64 v[214:215], s[50:51], 0, v[204:205]
	ds_read_b128 v[164:167], v223 offset:32768
	ds_read_b128 v[168:171], v223 offset:33792
	ds_read_b128 v[172:175], v223 offset:34816
	ds_read_b128 v[176:179], v223 offset:35840
	ds_read_b128 v[180:183], v223 offset:36864
	ds_read_b128 v[184:187], v223 offset:37888
	ds_read_b128 v[188:191], v223 offset:38912
	ds_read_b128 v[192:195], v223 offset:39936
	global_load_lds_dwordx4 v[214:215], off
	v_lshl_add_u64 v[214:215], s[50:51], 0, v[206:207]
	s_mov_b32 m0, s70
	s_nop 0
	global_load_lds_dwordx4 v[214:215], off
	s_waitcnt vmcnt(8)
	s_waitcnt lgkmcnt(0)
	s_barrier
	s_setprio 1
	s_waitcnt lgkmcnt(0)
	v_mfma_f32_16x16x32_bf16 v[156:159], v[108:111], v[164:167], v[156:159]
	v_mfma_f32_16x16x32_bf16 v[156:159], v[120:123], v[168:171], v[156:159]
	v_mfma_f32_16x16x32_bf16 v[128:131], v[108:111], v[172:175], v[128:131]
	v_mfma_f32_16x16x32_bf16 v[128:131], v[120:123], v[176:179], v[128:131]
	v_mfma_f32_16x16x32_bf16 v[116:119], v[108:111], v[180:183], v[116:119]
	v_mfma_f32_16x16x32_bf16 v[116:119], v[120:123], v[184:187], v[116:119]
	v_mfma_f32_16x16x32_bf16 v[104:107], v[108:111], v[188:191], v[104:107]
	v_mfma_f32_16x16x32_bf16 v[104:107], v[120:123], v[192:195], v[104:107]
	v_mfma_f32_16x16x32_bf16 v[152:155], v[132:135], v[164:167], v[152:155]
	v_mfma_f32_16x16x32_bf16 v[152:155], v[136:139], v[168:171], v[152:155]
	v_mfma_f32_16x16x32_bf16 v[124:127], v[132:135], v[172:175], v[124:127]
	v_mfma_f32_16x16x32_bf16 v[124:127], v[136:139], v[176:179], v[124:127]
	v_mfma_f32_16x16x32_bf16 v[112:115], v[132:135], v[180:183], v[112:115]
	v_mfma_f32_16x16x32_bf16 v[112:115], v[136:139], v[184:187], v[112:115]
	v_mfma_f32_16x16x32_bf16 v[100:103], v[132:135], v[188:191], v[100:103]
	v_mfma_f32_16x16x32_bf16 v[100:103], v[136:139], v[192:195], v[100:103]
	s_setprio 0
	s_setprio 1
	v_mfma_f32_16x16x32_bf16 v[92:95], v[140:143], v[164:167], v[92:95]
	v_mfma_f32_16x16x32_bf16 v[92:95], v[144:147], v[168:171], v[92:95]
	v_mfma_f32_16x16x32_bf16 v[84:87], v[140:143], v[172:175], v[84:87]
	v_mfma_f32_16x16x32_bf16 v[84:87], v[144:147], v[176:179], v[84:87]
	v_mfma_f32_16x16x32_bf16 v[76:79], v[140:143], v[180:183], v[76:79]
	v_mfma_f32_16x16x32_bf16 v[76:79], v[144:147], v[184:187], v[76:79]
	v_mfma_f32_16x16x32_bf16 v[68:71], v[140:143], v[188:191], v[68:71]
	v_mfma_f32_16x16x32_bf16 v[68:71], v[144:147], v[192:195], v[68:71]
	v_mfma_f32_16x16x32_bf16 v[88:91], v[148:151], v[164:167], v[88:91]
	v_mfma_f32_16x16x32_bf16 v[88:91], v[160:163], v[168:171], v[88:91]
	v_mfma_f32_16x16x32_bf16 v[80:83], v[148:151], v[172:175], v[80:83]
	v_mfma_f32_16x16x32_bf16 v[80:83], v[160:163], v[176:179], v[80:83]
	v_mfma_f32_16x16x32_bf16 v[72:75], v[148:151], v[180:183], v[72:75]
	v_mfma_f32_16x16x32_bf16 v[72:75], v[160:163], v[184:187], v[72:75]
	v_mfma_f32_16x16x32_bf16 v[64:67], v[148:151], v[188:191], v[64:67]
	v_mfma_f32_16x16x32_bf16 v[64:67], v[160:163], v[192:195], v[64:67]
	s_setprio 0
	s_barrier
	s_nop 1
	s_add_i32 s3, s3, s64
	v_lshl_add_u64 v[196:197], v[196:197], 0, s[72:73]
	s_mov_b32 m0, s3
	ds_read_b128 v[164:167], v223 offset:49152
	ds_read_b128 v[168:171], v223 offset:50176
	ds_read_b128 v[172:175], v223 offset:51200
	ds_read_b128 v[176:179], v223 offset:52224
	ds_read_b128 v[180:183], v223 offset:53248
	ds_read_b128 v[184:187], v223 offset:54272
	ds_read_b128 v[188:191], v223 offset:55296
	ds_read_b128 v[192:195], v223 offset:56320
	global_load_lds_dwordx4 v[196:197], off
	s_add_i32 m0, s3, 0x2000
	s_add_u32 s50, vcc_lo, 0x80080
	v_lshl_add_u64 v[196:197], v[198:199], 0, s[72:73]
	s_addc_u32 s51, vcc_hi, 0
	s_add_i32 s3, s41, s64
	global_load_lds_dwordx4 v[196:197], off
	v_lshl_add_u64 v[196:197], s[50:51], 0, v[212:213]
	s_mov_b32 m0, s3
	s_nop 0
	global_load_lds_dwordx4 v[196:197], off
	v_lshl_add_u64 v[196:197], s[50:51], 0, v[208:209]
	s_add_i32 m0, s3, 0x2000
	s_nop 0
	global_load_lds_dwordx4 v[196:197], off
	v_lshl_add_u64 v[196:197], v[200:201], 0, s[72:73]
	s_mov_b32 m0, s83
	s_nop 0
	global_load_lds_dwordx4 v[196:197], off
	v_lshl_add_u64 v[196:197], v[202:203], 0, s[72:73]
	s_mov_b32 m0, s84
	s_nop 0
	global_load_lds_dwordx4 v[196:197], off
	s_waitcnt vmcnt(8)
	s_waitcnt lgkmcnt(0)
	s_barrier
	s_setprio 1
	s_waitcnt lgkmcnt(0)
	v_mfma_f32_16x16x32_bf16 v[60:63], v[108:111], v[164:167], v[60:63]
	v_mfma_f32_16x16x32_bf16 v[60:63], v[120:123], v[168:171], v[60:63]
	v_mfma_f32_16x16x32_bf16 v[52:55], v[108:111], v[172:175], v[52:55]
	v_mfma_f32_16x16x32_bf16 v[52:55], v[120:123], v[176:179], v[52:55]
	v_mfma_f32_16x16x32_bf16 v[44:47], v[108:111], v[180:183], v[44:47]
	v_mfma_f32_16x16x32_bf16 v[44:47], v[120:123], v[184:187], v[44:47]
	v_mfma_f32_16x16x32_bf16 v[36:39], v[108:111], v[188:191], v[36:39]
	v_mfma_f32_16x16x32_bf16 v[36:39], v[120:123], v[192:195], v[36:39]
	v_mfma_f32_16x16x32_bf16 v[56:59], v[132:135], v[164:167], v[56:59]
	v_mfma_f32_16x16x32_bf16 v[56:59], v[136:139], v[168:171], v[56:59]
	v_mfma_f32_16x16x32_bf16 v[48:51], v[132:135], v[172:175], v[48:51]
	v_mfma_f32_16x16x32_bf16 v[48:51], v[136:139], v[176:179], v[48:51]
	v_mfma_f32_16x16x32_bf16 v[40:43], v[132:135], v[180:183], v[40:43]
	v_mfma_f32_16x16x32_bf16 v[40:43], v[136:139], v[184:187], v[40:43]
	v_mfma_f32_16x16x32_bf16 v[32:35], v[132:135], v[188:191], v[32:35]
	v_mfma_f32_16x16x32_bf16 v[32:35], v[136:139], v[192:195], v[32:35]
	s_setprio 0
	s_setprio 1
	v_mfma_f32_16x16x32_bf16 v[28:31], v[140:143], v[164:167], v[28:31]
	v_mfma_f32_16x16x32_bf16 v[28:31], v[144:147], v[168:171], v[28:31]
	v_mfma_f32_16x16x32_bf16 v[20:23], v[140:143], v[172:175], v[20:23]
	v_mfma_f32_16x16x32_bf16 v[20:23], v[144:147], v[176:179], v[20:23]
	v_mfma_f32_16x16x32_bf16 v[12:15], v[140:143], v[180:183], v[12:15]
	v_mfma_f32_16x16x32_bf16 v[12:15], v[144:147], v[184:187], v[12:15]
	v_mfma_f32_16x16x32_bf16 v[4:7], v[140:143], v[188:191], v[4:7]
	v_mfma_f32_16x16x32_bf16 v[4:7], v[144:147], v[192:195], v[4:7]
	v_mfma_f32_16x16x32_bf16 v[24:27], v[148:151], v[164:167], v[24:27]
	v_mfma_f32_16x16x32_bf16 v[24:27], v[160:163], v[168:171], v[24:27]
	v_mfma_f32_16x16x32_bf16 v[16:19], v[148:151], v[172:175], v[16:19]
	v_mfma_f32_16x16x32_bf16 v[16:19], v[160:163], v[176:179], v[16:19]
	v_mfma_f32_16x16x32_bf16 v[8:11], v[148:151], v[180:183], v[8:11]
	v_mfma_f32_16x16x32_bf16 v[8:11], v[160:163], v[184:187], v[8:11]
	v_mfma_f32_16x16x32_bf16 v[0:3], v[148:151], v[188:191], v[0:3]
	v_mfma_f32_16x16x32_bf16 v[0:3], v[160:163], v[192:195], v[0:3]
	s_setprio 0
	s_barrier
	s_nop 1
	s_add_u32 s34, s34, 0x100
	s_addc_u32 s35, s35, 0
	s_cmp_ge_i32 s2, s21
	s_mov_b32 s41, s2
	s_cbranch_scc1 .LBB0_666

.LBB0_831:
	s_add_u32 s2, s24, 0xfff80080
	s_addc_u32 s3, s25, -1
	s_cmp_eq_u32 s17, 30
	s_cselect_b32 s29, s13, s3
	s_cselect_b32 s28, s63, s2
	s_cselect_b32 s27, s11, s65
	s_cselect_b32 s26, s64, s19
	s_add_i32 s2, 0, 0x10000
	v_add_u32_e32 v138, s2, v140
	s_add_i32 s66, 0, 0x14000
	ds_read_b128 v[142:145], v138
	ds_read_b128 v[146:149], v138 offset:1024
	ds_read_b128 v[150:153], v138 offset:2048
	ds_read_b128 v[154:157], v138 offset:3072
	v_add_u32_e32 v138, s66, v140
	ds_read_b128 v[158:161], v138
	ds_read_b128 v[162:165], v138 offset:1024
	ds_read_b128 v[166:169], v138 offset:2048
	ds_read_b128 v[170:173], v138 offset:3072
	v_lshl_add_u64 v[138:139], s[24:25], 0, v[134:135]
	s_add_i32 m0, s43, 0xc000
	ds_read_b128 v[174:177], v141
	ds_read_b128 v[178:181], v141 offset:1024
	ds_read_b128 v[182:185], v141 offset:2048
	ds_read_b128 v[186:189], v141 offset:3072
	ds_read_b128 v[190:193], v141 offset:4096
	ds_read_b128 v[194:197], v141 offset:5120
	ds_read_b128 v[198:201], v141 offset:6144
	ds_read_b128 v[202:205], v141 offset:7168
	global_load_lds_dwordx4 v[138:139], off
	v_lshl_add_u64 v[138:139], s[24:25], 0, v[136:137]
	s_add_i32 m0, s43, 0xe000
	s_nop 0
	global_load_lds_dwordx4 v[138:139], off
	s_waitcnt vmcnt(8)
	s_waitcnt lgkmcnt(0)
	s_barrier
	s_setprio 1
	s_waitcnt lgkmcnt(0)
	v_mfma_f32_16x16x32_bf16 v[124:127], v[142:145], v[174:177], v[124:127]
	v_mfma_f32_16x16x32_bf16 v[124:127], v[146:149], v[178:181], v[124:127]
	v_mfma_f32_16x16x32_bf16 v[120:123], v[142:145], v[182:185], v[120:123]
	v_mfma_f32_16x16x32_bf16 v[120:123], v[146:149], v[186:189], v[120:123]
	v_mfma_f32_16x16x32_bf16 v[116:119], v[142:145], v[190:193], v[116:119]
	v_mfma_f32_16x16x32_bf16 v[116:119], v[146:149], v[194:197], v[116:119]
	v_mfma_f32_16x16x32_bf16 v[112:115], v[142:145], v[198:201], v[112:115]
	v_mfma_f32_16x16x32_bf16 v[112:115], v[146:149], v[202:205], v[112:115]
	v_mfma_f32_16x16x32_bf16 v[108:111], v[150:153], v[174:177], v[108:111]
	v_mfma_f32_16x16x32_bf16 v[108:111], v[154:157], v[178:181], v[108:111]
	v_mfma_f32_16x16x32_bf16 v[104:107], v[150:153], v[182:185], v[104:107]
	v_mfma_f32_16x16x32_bf16 v[104:107], v[154:157], v[186:189], v[104:107]
	v_mfma_f32_16x16x32_bf16 v[100:103], v[150:153], v[190:193], v[100:103]
	v_mfma_f32_16x16x32_bf16 v[100:103], v[154:157], v[194:197], v[100:103]
	v_mfma_f32_16x16x32_bf16 v[96:99], v[150:153], v[198:201], v[96:99]
	v_mfma_f32_16x16x32_bf16 v[96:99], v[154:157], v[202:205], v[96:99]
	s_setprio 0
	s_setprio 1
	v_mfma_f32_16x16x32_bf16 v[84:87], v[158:161], v[174:177], v[84:87]
	v_mfma_f32_16x16x32_bf16 v[84:87], v[162:165], v[178:181], v[84:87]
	v_mfma_f32_16x16x32_bf16 v[76:79], v[158:161], v[182:185], v[76:79]
	v_mfma_f32_16x16x32_bf16 v[76:79], v[162:165], v[186:189], v[76:79]
	v_mfma_f32_16x16x32_bf16 v[64:67], v[158:161], v[190:193], v[64:67]
	v_mfma_f32_16x16x32_bf16 v[64:67], v[162:165], v[194:197], v[64:67]
	v_mfma_f32_16x16x32_bf16 v[56:59], v[158:161], v[198:201], v[56:59]
	v_mfma_f32_16x16x32_bf16 v[56:59], v[162:165], v[202:205], v[56:59]
	v_mfma_f32_16x16x32_bf16 v[52:55], v[166:169], v[174:177], v[52:55]
	v_mfma_f32_16x16x32_bf16 v[52:55], v[170:173], v[178:181], v[52:55]
	v_mfma_f32_16x16x32_bf16 v[44:47], v[166:169], v[182:185], v[44:47]
	v_mfma_f32_16x16x32_bf16 v[44:47], v[170:173], v[186:189], v[44:47]
	v_mfma_f32_16x16x32_bf16 v[36:39], v[166:169], v[190:193], v[36:39]
	v_mfma_f32_16x16x32_bf16 v[36:39], v[170:173], v[194:197], v[36:39]
	v_mfma_f32_16x16x32_bf16 v[32:35], v[166:169], v[198:201], v[32:35]
	v_mfma_f32_16x16x32_bf16 v[32:35], v[170:173], v[202:205], v[32:35]
	s_setprio 0
	s_barrier
	s_nop 1
	s_add_i32 s2, s2, s41
	v_lshl_add_u64 v[138:139], s[26:27], 0, v[212:213]
	s_mov_b32 m0, s2
	ds_read_b128 v[174:177], v141 offset:16384
	ds_read_b128 v[178:181], v141 offset:17408
	ds_read_b128 v[182:185], v141 offset:18432
	ds_read_b128 v[186:189], v141 offset:19456
	ds_read_b128 v[190:193], v141 offset:20480
	ds_read_b128 v[194:197], v141 offset:21504
	ds_read_b128 v[198:201], v141 offset:22528
	ds_read_b128 v[202:205], v141 offset:23552
	global_load_lds_dwordx4 v[138:139], off
	s_add_i32 m0, s2, 0x2000
	s_add_u32 s2, s26, 0x80000
	v_lshl_add_u64 v[206:207], s[26:27], 0, v[128:129]
	s_addc_u32 s3, s27, 0
	s_add_i32 s66, s66, s41
	global_load_lds_dwordx4 v[206:207], off
	v_lshl_add_u64 v[208:209], s[2:3], 0, v[212:213]
	s_mov_b32 m0, s66
	v_lshl_add_u64 v[210:211], s[28:29], 0, v[130:131]
	global_load_lds_dwordx4 v[208:209], off
	v_lshl_add_u64 v[208:209], s[2:3], 0, v[128:129]
	s_add_i32 m0, s66, 0x2000
	s_nop 0
	global_load_lds_dwordx4 v[208:209], off
	v_lshl_add_u64 v[208:209], s[28:29], 0, v[132:133]
	s_mov_b32 m0, s43
	s_nop 0
	global_load_lds_dwordx4 v[208:209], off
	s_mov_b32 m0, s44
	s_nop 0
	global_load_lds_dwordx4 v[210:211], off
	s_waitcnt vmcnt(8)
	s_waitcnt lgkmcnt(0)
	s_barrier
	s_setprio 1
	s_waitcnt lgkmcnt(0)
	v_mfma_f32_16x16x32_bf16 v[92:95], v[142:145], v[174:177], v[92:95]
	v_mfma_f32_16x16x32_bf16 v[92:95], v[146:149], v[178:181], v[92:95]
	v_mfma_f32_16x16x32_bf16 v[88:91], v[142:145], v[182:185], v[88:91]
	v_mfma_f32_16x16x32_bf16 v[88:91], v[146:149], v[186:189], v[88:91]
	v_mfma_f32_16x16x32_bf16 v[80:83], v[142:145], v[190:193], v[80:83]
	v_mfma_f32_16x16x32_bf16 v[80:83], v[146:149], v[194:197], v[80:83]
	v_mfma_f32_16x16x32_bf16 v[72:75], v[142:145], v[198:201], v[72:75]
	v_mfma_f32_16x16x32_bf16 v[72:75], v[146:149], v[202:205], v[72:75]
	v_mfma_f32_16x16x32_bf16 v[68:71], v[150:153], v[174:177], v[68:71]
	v_mfma_f32_16x16x32_bf16 v[68:71], v[154:157], v[178:181], v[68:71]
	v_mfma_f32_16x16x32_bf16 v[60:63], v[150:153], v[182:185], v[60:63]
	v_mfma_f32_16x16x32_bf16 v[60:63], v[154:157], v[186:189], v[60:63]
	v_mfma_f32_16x16x32_bf16 v[48:51], v[150:153], v[190:193], v[48:51]
	v_mfma_f32_16x16x32_bf16 v[48:51], v[154:157], v[194:197], v[48:51]
	v_mfma_f32_16x16x32_bf16 v[40:43], v[150:153], v[198:201], v[40:43]
	v_mfma_f32_16x16x32_bf16 v[40:43], v[154:157], v[202:205], v[40:43]
	s_setprio 0
	s_setprio 1
	v_mfma_f32_16x16x32_bf16 v[28:31], v[158:161], v[174:177], v[28:31]
	v_mfma_f32_16x16x32_bf16 v[28:31], v[162:165], v[178:181], v[28:31]
	v_mfma_f32_16x16x32_bf16 v[24:27], v[158:161], v[182:185], v[24:27]
	v_mfma_f32_16x16x32_bf16 v[24:27], v[162:165], v[186:189], v[24:27]
	v_mfma_f32_16x16x32_bf16 v[20:23], v[158:161], v[190:193], v[20:23]
	v_mfma_f32_16x16x32_bf16 v[20:23], v[162:165], v[194:197], v[20:23]
	v_mfma_f32_16x16x32_bf16 v[16:19], v[158:161], v[198:201], v[16:19]
	v_mfma_f32_16x16x32_bf16 v[16:19], v[162:165], v[202:205], v[16:19]
	v_mfma_f32_16x16x32_bf16 v[12:15], v[166:169], v[174:177], v[12:15]
	v_mfma_f32_16x16x32_bf16 v[12:15], v[170:173], v[178:181], v[12:15]
	v_mfma_f32_16x16x32_bf16 v[8:11], v[166:169], v[182:185], v[8:11]
	v_mfma_f32_16x16x32_bf16 v[8:11], v[170:173], v[186:189], v[8:11]
	v_mfma_f32_16x16x32_bf16 v[4:7], v[166:169], v[190:193], v[4:7]
	v_mfma_f32_16x16x32_bf16 v[4:7], v[170:173], v[194:197], v[4:7]
	v_mfma_f32_16x16x32_bf16 v[0:3], v[166:169], v[198:201], v[0:3]
	v_mfma_f32_16x16x32_bf16 v[0:3], v[170:173], v[202:205], v[0:3]
	s_setprio 0
	s_barrier
	s_nop 1
	s_add_i32 s66, 0, 0x18000
	s_add_i32 s67, 0, 0x1c000
	v_add_u32_e32 v154, s66, v140
	v_add_u32_e32 v170, s67, v140
	ds_read_b128 v[142:145], v154
	ds_read_b128 v[146:149], v154 offset:1024
	ds_read_b128 v[150:153], v154 offset:2048
	ds_read_b128 v[154:157], v154 offset:3072
	ds_read_b128 v[158:161], v170
	ds_read_b128 v[162:165], v170 offset:1024
	ds_read_b128 v[166:169], v170 offset:2048
	ds_read_b128 v[170:173], v170 offset:3072
	s_add_u32 s2, s28, 0x80000
	s_addc_u32 s3, s29, 0
	s_mov_b32 m0, s45
	v_lshl_add_u64 v[214:215], s[2:3], 0, v[132:133]
	ds_read_b128 v[174:177], v141 offset:32768
	ds_read_b128 v[178:181], v141 offset:33792
	ds_read_b128 v[182:185], v141 offset:34816
	ds_read_b128 v[186:189], v141 offset:35840
	ds_read_b128 v[190:193], v141 offset:36864
	ds_read_b128 v[194:197], v141 offset:37888
	ds_read_b128 v[198:201], v141 offset:38912
	ds_read_b128 v[202:205], v141 offset:39936
	global_load_lds_dwordx4 v[214:215], off
	v_lshl_add_u64 v[214:215], s[2:3], 0, v[130:131]
	s_mov_b32 m0, s46
	s_nop 0
	global_load_lds_dwordx4 v[214:215], off
	s_waitcnt vmcnt(8)
	s_waitcnt lgkmcnt(0)
	s_barrier
	s_setprio 1
	s_waitcnt lgkmcnt(0)
	v_mfma_f32_16x16x32_bf16 v[124:127], v[142:145], v[174:177], v[124:127]
	v_mfma_f32_16x16x32_bf16 v[124:127], v[146:149], v[178:181], v[124:127]
	v_mfma_f32_16x16x32_bf16 v[120:123], v[142:145], v[182:185], v[120:123]
	v_mfma_f32_16x16x32_bf16 v[120:123], v[146:149], v[186:189], v[120:123]
	v_mfma_f32_16x16x32_bf16 v[116:119], v[142:145], v[190:193], v[116:119]
	v_mfma_f32_16x16x32_bf16 v[116:119], v[146:149], v[194:197], v[116:119]
	v_mfma_f32_16x16x32_bf16 v[112:115], v[142:145], v[198:201], v[112:115]
	v_mfma_f32_16x16x32_bf16 v[112:115], v[146:149], v[202:205], v[112:115]
	v_mfma_f32_16x16x32_bf16 v[108:111], v[150:153], v[174:177], v[108:111]
	v_mfma_f32_16x16x32_bf16 v[108:111], v[154:157], v[178:181], v[108:111]
	v_mfma_f32_16x16x32_bf16 v[104:107], v[150:153], v[182:185], v[104:107]
	v_mfma_f32_16x16x32_bf16 v[104:107], v[154:157], v[186:189], v[104:107]
	v_mfma_f32_16x16x32_bf16 v[100:103], v[150:153], v[190:193], v[100:103]
	v_mfma_f32_16x16x32_bf16 v[100:103], v[154:157], v[194:197], v[100:103]
	v_mfma_f32_16x16x32_bf16 v[96:99], v[150:153], v[198:201], v[96:99]
	v_mfma_f32_16x16x32_bf16 v[96:99], v[154:157], v[202:205], v[96:99]
	s_setprio 0
	s_setprio 1
	v_mfma_f32_16x16x32_bf16 v[84:87], v[158:161], v[174:177], v[84:87]
	v_mfma_f32_16x16x32_bf16 v[84:87], v[162:165], v[178:181], v[84:87]
	v_mfma_f32_16x16x32_bf16 v[76:79], v[158:161], v[182:185], v[76:79]
	v_mfma_f32_16x16x32_bf16 v[76:79], v[162:165], v[186:189], v[76:79]
	v_mfma_f32_16x16x32_bf16 v[64:67], v[158:161], v[190:193], v[64:67]
	v_mfma_f32_16x16x32_bf16 v[64:67], v[162:165], v[194:197], v[64:67]
	v_mfma_f32_16x16x32_bf16 v[56:59], v[158:161], v[198:201], v[56:59]
	v_mfma_f32_16x16x32_bf16 v[56:59], v[162:165], v[202:205], v[56:59]
	v_mfma_f32_16x16x32_bf16 v[52:55], v[166:169], v[174:177], v[52:55]
	v_mfma_f32_16x16x32_bf16 v[52:55], v[170:173], v[178:181], v[52:55]
	v_mfma_f32_16x16x32_bf16 v[44:47], v[166:169], v[182:185], v[44:47]
	v_mfma_f32_16x16x32_bf16 v[44:47], v[170:173], v[186:189], v[44:47]
	v_mfma_f32_16x16x32_bf16 v[36:39], v[166:169], v[190:193], v[36:39]
	v_mfma_f32_16x16x32_bf16 v[36:39], v[170:173], v[194:197], v[36:39]
	v_mfma_f32_16x16x32_bf16 v[32:35], v[166:169], v[198:201], v[32:35]
	v_mfma_f32_16x16x32_bf16 v[32:35], v[170:173], v[202:205], v[32:35]
	s_setprio 0
	s_barrier
	s_nop 1
	s_add_i32 s2, s66, s41
	v_lshl_add_u64 v[138:139], v[138:139], 0, s[72:73]
	s_mov_b32 m0, s2
	ds_read_b128 v[174:177], v141 offset:49152
	ds_read_b128 v[178:181], v141 offset:50176
	ds_read_b128 v[182:185], v141 offset:51200
	ds_read_b128 v[186:189], v141 offset:52224
	ds_read_b128 v[190:193], v141 offset:53248
	ds_read_b128 v[194:197], v141 offset:54272
	ds_read_b128 v[198:201], v141 offset:55296
	ds_read_b128 v[202:205], v141 offset:56320
	global_load_lds_dwordx4 v[138:139], off
	s_add_i32 m0, s2, 0x2000
	s_add_u32 s2, s26, 0x80080
	v_lshl_add_u64 v[138:139], v[206:207], 0, s[72:73]
	s_addc_u32 s3, s27, 0
	s_add_i32 s26, s67, s41
	global_load_lds_dwordx4 v[138:139], off
	v_lshl_add_u64 v[138:139], s[2:3], 0, v[212:213]
	s_mov_b32 m0, s26
	s_nop 0
	global_load_lds_dwordx4 v[138:139], off
	v_lshl_add_u64 v[138:139], s[2:3], 0, v[128:129]
	s_add_i32 m0, s26, 0x2000
	s_nop 0
	global_load_lds_dwordx4 v[138:139], off
	v_lshl_add_u64 v[138:139], v[208:209], 0, s[72:73]
	s_mov_b32 m0, s54
	s_nop 0
	global_load_lds_dwordx4 v[138:139], off
	v_lshl_add_u64 v[138:139], v[210:211], 0, s[72:73]
	s_mov_b32 m0, s55
	s_nop 0
	global_load_lds_dwordx4 v[138:139], off
	s_waitcnt vmcnt(8)
	s_waitcnt lgkmcnt(0)
	s_barrier
	s_setprio 1
	s_waitcnt lgkmcnt(0)
	v_mfma_f32_16x16x32_bf16 v[92:95], v[142:145], v[174:177], v[92:95]
	v_mfma_f32_16x16x32_bf16 v[92:95], v[146:149], v[178:181], v[92:95]
	v_mfma_f32_16x16x32_bf16 v[88:91], v[142:145], v[182:185], v[88:91]
	v_mfma_f32_16x16x32_bf16 v[88:91], v[146:149], v[186:189], v[88:91]
	v_mfma_f32_16x16x32_bf16 v[80:83], v[142:145], v[190:193], v[80:83]
	v_mfma_f32_16x16x32_bf16 v[80:83], v[146:149], v[194:197], v[80:83]
	v_mfma_f32_16x16x32_bf16 v[72:75], v[142:145], v[198:201], v[72:75]
	v_mfma_f32_16x16x32_bf16 v[72:75], v[146:149], v[202:205], v[72:75]
	v_mfma_f32_16x16x32_bf16 v[68:71], v[150:153], v[174:177], v[68:71]
	v_mfma_f32_16x16x32_bf16 v[68:71], v[154:157], v[178:181], v[68:71]
	v_mfma_f32_16x16x32_bf16 v[60:63], v[150:153], v[182:185], v[60:63]
	v_mfma_f32_16x16x32_bf16 v[60:63], v[154:157], v[186:189], v[60:63]
	v_mfma_f32_16x16x32_bf16 v[48:51], v[150:153], v[190:193], v[48:51]
	v_mfma_f32_16x16x32_bf16 v[48:51], v[154:157], v[194:197], v[48:51]
	v_mfma_f32_16x16x32_bf16 v[40:43], v[150:153], v[198:201], v[40:43]
	v_mfma_f32_16x16x32_bf16 v[40:43], v[154:157], v[202:205], v[40:43]
	s_setprio 0
	s_setprio 1
	v_mfma_f32_16x16x32_bf16 v[28:31], v[158:161], v[174:177], v[28:31]
	v_mfma_f32_16x16x32_bf16 v[28:31], v[162:165], v[178:181], v[28:31]
	v_mfma_f32_16x16x32_bf16 v[24:27], v[158:161], v[182:185], v[24:27]
	v_mfma_f32_16x16x32_bf16 v[24:27], v[162:165], v[186:189], v[24:27]
	v_mfma_f32_16x16x32_bf16 v[20:23], v[158:161], v[190:193], v[20:23]
	v_mfma_f32_16x16x32_bf16 v[20:23], v[162:165], v[194:197], v[20:23]
	v_mfma_f32_16x16x32_bf16 v[16:19], v[158:161], v[198:201], v[16:19]
	v_mfma_f32_16x16x32_bf16 v[16:19], v[162:165], v[202:205], v[16:19]
	v_mfma_f32_16x16x32_bf16 v[12:15], v[166:169], v[174:177], v[12:15]
	v_mfma_f32_16x16x32_bf16 v[12:15], v[170:173], v[178:181], v[12:15]
	v_mfma_f32_16x16x32_bf16 v[8:11], v[166:169], v[182:185], v[8:11]
	v_mfma_f32_16x16x32_bf16 v[8:11], v[170:173], v[186:189], v[8:11]
	v_mfma_f32_16x16x32_bf16 v[4:7], v[166:169], v[190:193], v[4:7]
	v_mfma_f32_16x16x32_bf16 v[4:7], v[170:173], v[194:197], v[4:7]
	v_mfma_f32_16x16x32_bf16 v[0:3], v[166:169], v[198:201], v[0:3]
	v_mfma_f32_16x16x32_bf16 v[0:3], v[170:173], v[202:205], v[0:3]
	s_setprio 0
	s_barrier
	s_nop 1
	s_add_i32 s2, s17, 2
	s_add_u32 s24, s24, 0x100
	s_addc_u32 s25, s25, 0
	s_add_u32 s19, s19, 0x100
	s_addc_u32 s65, s65, 0
	s_cmp_gt_u32 s17, 29
	s_mov_b32 s17, s2
	s_cbranch_scc1 .LBB0_842

.LBB0_997:
	s_add_u32 s20, s18, 0xfffe0080
	s_addc_u32 s21, s19, -1
	s_add_i32 s63, 0, 0x10000
	s_cmp_eq_u32 s62, 4
	s_cselect_b32 s23, s2, s21
	s_cselect_b32 s22, s3, s20
	s_cselect_b32 s21, s39, s61
	s_cselect_b32 s20, s43, s60
	s_add_i32 s66, 0, 0x14000
	v_add_u32_e32 v152, s63, v142
	v_add_u32_e32 v168, s66, v142
	ds_read_b128 v[138:141], v152
	ds_read_b128 v[144:147], v152 offset:1024
	ds_read_b128 v[148:151], v152 offset:2048
	ds_read_b128 v[152:155], v152 offset:3072
	ds_read_b128 v[156:159], v168
	ds_read_b128 v[160:163], v168 offset:1024
	ds_read_b128 v[164:167], v168 offset:2048
	ds_read_b128 v[168:171], v168 offset:3072
	v_lshl_add_u64 v[204:205], s[18:19], 0, v[134:135]
	s_add_i32 m0, s41, 0xc000
	ds_read_b128 v[172:175], v143
	ds_read_b128 v[176:179], v143 offset:1024
	ds_read_b128 v[180:183], v143 offset:2048
	ds_read_b128 v[184:187], v143 offset:3072
	ds_read_b128 v[188:191], v143 offset:4096
	ds_read_b128 v[192:195], v143 offset:5120
	ds_read_b128 v[196:199], v143 offset:6144
	ds_read_b128 v[200:203], v143 offset:7168
	global_load_lds_dwordx4 v[204:205], off
	v_lshl_add_u64 v[204:205], s[18:19], 0, v[136:137]
	s_add_i32 m0, s41, 0xe000
	s_nop 0
	global_load_lds_dwordx4 v[204:205], off
	s_waitcnt vmcnt(8)
	s_waitcnt lgkmcnt(0)
	s_barrier
	s_setprio 1
	s_waitcnt lgkmcnt(0)
	v_mfma_f32_16x16x32_bf16 v[124:127], v[138:141], v[172:175], v[124:127]
	v_mfma_f32_16x16x32_bf16 v[124:127], v[144:147], v[176:179], v[124:127]
	v_mfma_f32_16x16x32_bf16 v[116:119], v[138:141], v[180:183], v[116:119]
	v_mfma_f32_16x16x32_bf16 v[116:119], v[144:147], v[184:187], v[116:119]
	v_mfma_f32_16x16x32_bf16 v[100:103], v[138:141], v[188:191], v[100:103]
	v_mfma_f32_16x16x32_bf16 v[100:103], v[144:147], v[192:195], v[100:103]
	v_mfma_f32_16x16x32_bf16 v[84:87], v[138:141], v[196:199], v[84:87]
	v_mfma_f32_16x16x32_bf16 v[84:87], v[144:147], v[200:203], v[84:87]
	v_mfma_f32_16x16x32_bf16 v[120:123], v[148:151], v[172:175], v[120:123]
	v_mfma_f32_16x16x32_bf16 v[120:123], v[152:155], v[176:179], v[120:123]
	v_mfma_f32_16x16x32_bf16 v[108:111], v[148:151], v[180:183], v[108:111]
	v_mfma_f32_16x16x32_bf16 v[108:111], v[152:155], v[184:187], v[108:111]
	v_mfma_f32_16x16x32_bf16 v[92:95], v[148:151], v[188:191], v[92:95]
	v_mfma_f32_16x16x32_bf16 v[92:95], v[152:155], v[192:195], v[92:95]
	v_mfma_f32_16x16x32_bf16 v[76:79], v[148:151], v[196:199], v[76:79]
	v_mfma_f32_16x16x32_bf16 v[76:79], v[152:155], v[200:203], v[76:79]
	s_setprio 0
	s_setprio 1
	v_mfma_f32_16x16x32_bf16 v[112:115], v[156:159], v[172:175], v[112:115]
	v_mfma_f32_16x16x32_bf16 v[112:115], v[160:163], v[176:179], v[112:115]
	v_mfma_f32_16x16x32_bf16 v[96:99], v[156:159], v[180:183], v[96:99]
	v_mfma_f32_16x16x32_bf16 v[96:99], v[160:163], v[184:187], v[96:99]
	v_mfma_f32_16x16x32_bf16 v[80:83], v[156:159], v[188:191], v[80:83]
	v_mfma_f32_16x16x32_bf16 v[80:83], v[160:163], v[192:195], v[80:83]
	v_mfma_f32_16x16x32_bf16 v[68:71], v[156:159], v[196:199], v[68:71]
	v_mfma_f32_16x16x32_bf16 v[68:71], v[160:163], v[200:203], v[68:71]
	v_mfma_f32_16x16x32_bf16 v[104:107], v[164:167], v[172:175], v[104:107]
	v_mfma_f32_16x16x32_bf16 v[104:107], v[168:171], v[176:179], v[104:107]
	v_mfma_f32_16x16x32_bf16 v[88:91], v[164:167], v[180:183], v[88:91]
	v_mfma_f32_16x16x32_bf16 v[88:91], v[168:171], v[184:187], v[88:91]
	v_mfma_f32_16x16x32_bf16 v[72:75], v[164:167], v[188:191], v[72:75]
	v_mfma_f32_16x16x32_bf16 v[72:75], v[168:171], v[192:195], v[72:75]
	v_mfma_f32_16x16x32_bf16 v[64:67], v[164:167], v[196:199], v[64:67]
	v_mfma_f32_16x16x32_bf16 v[64:67], v[168:171], v[200:203], v[64:67]
	s_setprio 0
	s_barrier
	s_nop 1
	s_add_i32 s63, s63, s33
	v_lshl_add_u64 v[204:205], s[20:21], 0, v[212:213]
	s_mov_b32 m0, s63
	ds_read_b128 v[172:175], v143 offset:16384
	ds_read_b128 v[176:179], v143 offset:17408
	ds_read_b128 v[180:183], v143 offset:18432
	ds_read_b128 v[184:187], v143 offset:19456
	ds_read_b128 v[188:191], v143 offset:20480
	ds_read_b128 v[192:195], v143 offset:21504
	ds_read_b128 v[196:199], v143 offset:22528
	ds_read_b128 v[200:203], v143 offset:23552
	global_load_lds_dwordx4 v[204:205], off
	s_add_i32 m0, s63, 0x2000
	s_add_u32 s64, s20, 0x20000
	v_lshl_add_u64 v[206:207], s[20:21], 0, v[128:129]
	s_addc_u32 s65, s21, 0
	s_add_i32 s63, s66, s33
	global_load_lds_dwordx4 v[206:207], off
	v_lshl_add_u64 v[208:209], s[64:65], 0, v[212:213]
	s_mov_b32 m0, s63
	v_lshl_add_u64 v[210:211], s[22:23], 0, v[130:131]
	global_load_lds_dwordx4 v[208:209], off
	v_lshl_add_u64 v[208:209], s[64:65], 0, v[128:129]
	s_add_i32 m0, s63, 0x2000
	s_nop 0
	global_load_lds_dwordx4 v[208:209], off
	v_lshl_add_u64 v[208:209], s[22:23], 0, v[132:133]
	s_mov_b32 m0, s41
	s_nop 0
	global_load_lds_dwordx4 v[208:209], off
	s_mov_b32 m0, s47
	s_nop 0
	global_load_lds_dwordx4 v[210:211], off
	s_waitcnt vmcnt(8)
	s_waitcnt lgkmcnt(0)
	s_barrier
	s_setprio 1
	s_waitcnt lgkmcnt(0)
	v_mfma_f32_16x16x32_bf16 v[60:63], v[138:141], v[172:175], v[60:63]
	v_mfma_f32_16x16x32_bf16 v[60:63], v[144:147], v[176:179], v[60:63]
	v_mfma_f32_16x16x32_bf16 v[52:55], v[138:141], v[180:183], v[52:55]
	v_mfma_f32_16x16x32_bf16 v[52:55], v[144:147], v[184:187], v[52:55]
	v_mfma_f32_16x16x32_bf16 v[36:39], v[138:141], v[188:191], v[36:39]
	v_mfma_f32_16x16x32_bf16 v[36:39], v[144:147], v[192:195], v[36:39]
	v_mfma_f32_16x16x32_bf16 v[20:23], v[138:141], v[196:199], v[20:23]
	v_mfma_f32_16x16x32_bf16 v[20:23], v[144:147], v[200:203], v[20:23]
	v_mfma_f32_16x16x32_bf16 v[56:59], v[148:151], v[172:175], v[56:59]
	v_mfma_f32_16x16x32_bf16 v[56:59], v[152:155], v[176:179], v[56:59]
	v_mfma_f32_16x16x32_bf16 v[44:47], v[148:151], v[180:183], v[44:47]
	v_mfma_f32_16x16x32_bf16 v[44:47], v[152:155], v[184:187], v[44:47]
	v_mfma_f32_16x16x32_bf16 v[28:31], v[148:151], v[188:191], v[28:31]
	v_mfma_f32_16x16x32_bf16 v[28:31], v[152:155], v[192:195], v[28:31]
	v_mfma_f32_16x16x32_bf16 v[12:15], v[148:151], v[196:199], v[12:15]
	v_mfma_f32_16x16x32_bf16 v[12:15], v[152:155], v[200:203], v[12:15]
	s_setprio 0
	s_setprio 1
	v_mfma_f32_16x16x32_bf16 v[48:51], v[156:159], v[172:175], v[48:51]
	v_mfma_f32_16x16x32_bf16 v[48:51], v[160:163], v[176:179], v[48:51]
	v_mfma_f32_16x16x32_bf16 v[32:35], v[156:159], v[180:183], v[32:35]
	v_mfma_f32_16x16x32_bf16 v[32:35], v[160:163], v[184:187], v[32:35]
	v_mfma_f32_16x16x32_bf16 v[16:19], v[156:159], v[188:191], v[16:19]
	v_mfma_f32_16x16x32_bf16 v[16:19], v[160:163], v[192:195], v[16:19]
	v_mfma_f32_16x16x32_bf16 v[4:7], v[156:159], v[196:199], v[4:7]
	v_mfma_f32_16x16x32_bf16 v[4:7], v[160:163], v[200:203], v[4:7]
	v_mfma_f32_16x16x32_bf16 v[40:43], v[164:167], v[172:175], v[40:43]
	v_mfma_f32_16x16x32_bf16 v[40:43], v[168:171], v[176:179], v[40:43]
	v_mfma_f32_16x16x32_bf16 v[24:27], v[164:167], v[180:183], v[24:27]
	v_mfma_f32_16x16x32_bf16 v[24:27], v[168:171], v[184:187], v[24:27]
	v_mfma_f32_16x16x32_bf16 v[8:11], v[164:167], v[188:191], v[8:11]
	v_mfma_f32_16x16x32_bf16 v[8:11], v[168:171], v[192:195], v[8:11]
	v_mfma_f32_16x16x32_bf16 v[0:3], v[164:167], v[196:199], v[0:3]
	v_mfma_f32_16x16x32_bf16 v[0:3], v[168:171], v[200:203], v[0:3]
	s_setprio 0
	s_barrier
	s_nop 1
	s_add_i32 s63, 0, 0x18000
	s_add_i32 s64, 0, 0x1c000
	v_add_u32_e32 v152, s63, v142
	v_add_u32_e32 v168, s64, v142
	ds_read_b128 v[138:141], v152
	ds_read_b128 v[144:147], v152 offset:1024
	ds_read_b128 v[148:151], v152 offset:2048
	ds_read_b128 v[152:155], v152 offset:3072
	ds_read_b128 v[156:159], v168
	ds_read_b128 v[160:163], v168 offset:1024
	ds_read_b128 v[164:167], v168 offset:2048
	ds_read_b128 v[168:171], v168 offset:3072
	s_add_u32 s22, s22, 0x20000
	s_addc_u32 s23, s23, 0
	s_mov_b32 m0, s49
	v_lshl_add_u64 v[214:215], s[22:23], 0, v[132:133]
	ds_read_b128 v[172:175], v143 offset:32768
	ds_read_b128 v[176:179], v143 offset:33792
	ds_read_b128 v[180:183], v143 offset:34816
	ds_read_b128 v[184:187], v143 offset:35840
	ds_read_b128 v[188:191], v143 offset:36864
	ds_read_b128 v[192:195], v143 offset:37888
	ds_read_b128 v[196:199], v143 offset:38912
	ds_read_b128 v[200:203], v143 offset:39936
	global_load_lds_dwordx4 v[214:215], off
	v_lshl_add_u64 v[214:215], s[22:23], 0, v[130:131]
	s_mov_b32 m0, s52
	s_nop 0
	global_load_lds_dwordx4 v[214:215], off
	s_waitcnt vmcnt(8)
	s_waitcnt lgkmcnt(0)
	s_barrier
	s_setprio 1
	s_waitcnt lgkmcnt(0)
	v_mfma_f32_16x16x32_bf16 v[124:127], v[138:141], v[172:175], v[124:127]
	v_mfma_f32_16x16x32_bf16 v[124:127], v[144:147], v[176:179], v[124:127]
	v_mfma_f32_16x16x32_bf16 v[116:119], v[138:141], v[180:183], v[116:119]
	v_mfma_f32_16x16x32_bf16 v[116:119], v[144:147], v[184:187], v[116:119]
	v_mfma_f32_16x16x32_bf16 v[100:103], v[138:141], v[188:191], v[100:103]
	v_mfma_f32_16x16x32_bf16 v[100:103], v[144:147], v[192:195], v[100:103]
	v_mfma_f32_16x16x32_bf16 v[84:87], v[138:141], v[196:199], v[84:87]
	v_mfma_f32_16x16x32_bf16 v[84:87], v[144:147], v[200:203], v[84:87]
	v_mfma_f32_16x16x32_bf16 v[120:123], v[148:151], v[172:175], v[120:123]
	v_mfma_f32_16x16x32_bf16 v[120:123], v[152:155], v[176:179], v[120:123]
	v_mfma_f32_16x16x32_bf16 v[108:111], v[148:151], v[180:183], v[108:111]
	v_mfma_f32_16x16x32_bf16 v[108:111], v[152:155], v[184:187], v[108:111]
	v_mfma_f32_16x16x32_bf16 v[92:95], v[148:151], v[188:191], v[92:95]
	v_mfma_f32_16x16x32_bf16 v[92:95], v[152:155], v[192:195], v[92:95]
	v_mfma_f32_16x16x32_bf16 v[76:79], v[148:151], v[196:199], v[76:79]
	v_mfma_f32_16x16x32_bf16 v[76:79], v[152:155], v[200:203], v[76:79]
	s_setprio 0
	s_setprio 1
	v_mfma_f32_16x16x32_bf16 v[112:115], v[156:159], v[172:175], v[112:115]
	v_mfma_f32_16x16x32_bf16 v[112:115], v[160:163], v[176:179], v[112:115]
	v_mfma_f32_16x16x32_bf16 v[96:99], v[156:159], v[180:183], v[96:99]
	v_mfma_f32_16x16x32_bf16 v[96:99], v[160:163], v[184:187], v[96:99]
	v_mfma_f32_16x16x32_bf16 v[80:83], v[156:159], v[188:191], v[80:83]
	v_mfma_f32_16x16x32_bf16 v[80:83], v[160:163], v[192:195], v[80:83]
	v_mfma_f32_16x16x32_bf16 v[68:71], v[156:159], v[196:199], v[68:71]
	v_mfma_f32_16x16x32_bf16 v[68:71], v[160:163], v[200:203], v[68:71]
	v_mfma_f32_16x16x32_bf16 v[104:107], v[164:167], v[172:175], v[104:107]
	v_mfma_f32_16x16x32_bf16 v[104:107], v[168:171], v[176:179], v[104:107]
	v_mfma_f32_16x16x32_bf16 v[88:91], v[164:167], v[180:183], v[88:91]
	v_mfma_f32_16x16x32_bf16 v[88:91], v[168:171], v[184:187], v[88:91]
	v_mfma_f32_16x16x32_bf16 v[72:75], v[164:167], v[188:191], v[72:75]
	v_mfma_f32_16x16x32_bf16 v[72:75], v[168:171], v[192:195], v[72:75]
	v_mfma_f32_16x16x32_bf16 v[64:67], v[164:167], v[196:199], v[64:67]
	v_mfma_f32_16x16x32_bf16 v[64:67], v[168:171], v[200:203], v[64:67]
	s_setprio 0
	s_barrier
	s_nop 1
	s_add_i32 s22, s63, s33
	v_lshl_add_u64 v[204:205], v[204:205], 0, s[72:73]
	s_mov_b32 m0, s22
	ds_read_b128 v[172:175], v143 offset:49152
	ds_read_b128 v[176:179], v143 offset:50176
	ds_read_b128 v[180:183], v143 offset:51200
	ds_read_b128 v[184:187], v143 offset:52224
	ds_read_b128 v[188:191], v143 offset:53248
	ds_read_b128 v[192:195], v143 offset:54272
	ds_read_b128 v[196:199], v143 offset:55296
	ds_read_b128 v[200:203], v143 offset:56320
	global_load_lds_dwordx4 v[204:205], off
	s_add_i32 m0, s22, 0x2000
	s_add_u32 s20, s20, 0x20080
	v_lshl_add_u64 v[204:205], v[206:207], 0, s[72:73]
	s_addc_u32 s21, s21, 0
	s_add_i32 s22, s64, s33
	global_load_lds_dwordx4 v[204:205], off
	v_lshl_add_u64 v[204:205], s[20:21], 0, v[212:213]
	s_mov_b32 m0, s22
	s_nop 0
	global_load_lds_dwordx4 v[204:205], off
	v_lshl_add_u64 v[204:205], s[20:21], 0, v[128:129]
	s_add_i32 m0, s22, 0x2000
	s_nop 0
	global_load_lds_dwordx4 v[204:205], off
	v_lshl_add_u64 v[204:205], v[208:209], 0, s[72:73]
	s_mov_b32 m0, s55
	s_nop 0
	global_load_lds_dwordx4 v[204:205], off
	v_lshl_add_u64 v[204:205], v[210:211], 0, s[72:73]
	s_mov_b32 m0, s56
	s_nop 0
	global_load_lds_dwordx4 v[204:205], off
	s_waitcnt vmcnt(8)
	s_waitcnt lgkmcnt(0)
	s_barrier
	s_setprio 1
	s_waitcnt lgkmcnt(0)
	v_mfma_f32_16x16x32_bf16 v[60:63], v[138:141], v[172:175], v[60:63]
	v_mfma_f32_16x16x32_bf16 v[60:63], v[144:147], v[176:179], v[60:63]
	v_mfma_f32_16x16x32_bf16 v[52:55], v[138:141], v[180:183], v[52:55]
	v_mfma_f32_16x16x32_bf16 v[52:55], v[144:147], v[184:187], v[52:55]
	v_mfma_f32_16x16x32_bf16 v[36:39], v[138:141], v[188:191], v[36:39]
	v_mfma_f32_16x16x32_bf16 v[36:39], v[144:147], v[192:195], v[36:39]
	v_mfma_f32_16x16x32_bf16 v[20:23], v[138:141], v[196:199], v[20:23]
	v_mfma_f32_16x16x32_bf16 v[20:23], v[144:147], v[200:203], v[20:23]
	v_mfma_f32_16x16x32_bf16 v[56:59], v[148:151], v[172:175], v[56:59]
	v_mfma_f32_16x16x32_bf16 v[56:59], v[152:155], v[176:179], v[56:59]
	v_mfma_f32_16x16x32_bf16 v[44:47], v[148:151], v[180:183], v[44:47]
	v_mfma_f32_16x16x32_bf16 v[44:47], v[152:155], v[184:187], v[44:47]
	v_mfma_f32_16x16x32_bf16 v[28:31], v[148:151], v[188:191], v[28:31]
	v_mfma_f32_16x16x32_bf16 v[28:31], v[152:155], v[192:195], v[28:31]
	v_mfma_f32_16x16x32_bf16 v[12:15], v[148:151], v[196:199], v[12:15]
	v_mfma_f32_16x16x32_bf16 v[12:15], v[152:155], v[200:203], v[12:15]
	s_setprio 0
	s_setprio 1
	v_mfma_f32_16x16x32_bf16 v[48:51], v[156:159], v[172:175], v[48:51]
	v_mfma_f32_16x16x32_bf16 v[48:51], v[160:163], v[176:179], v[48:51]
	v_mfma_f32_16x16x32_bf16 v[32:35], v[156:159], v[180:183], v[32:35]
	v_mfma_f32_16x16x32_bf16 v[32:35], v[160:163], v[184:187], v[32:35]
	v_mfma_f32_16x16x32_bf16 v[16:19], v[156:159], v[188:191], v[16:19]
	v_mfma_f32_16x16x32_bf16 v[16:19], v[160:163], v[192:195], v[16:19]
	v_mfma_f32_16x16x32_bf16 v[4:7], v[156:159], v[196:199], v[4:7]
	v_mfma_f32_16x16x32_bf16 v[4:7], v[160:163], v[200:203], v[4:7]
	v_mfma_f32_16x16x32_bf16 v[40:43], v[164:167], v[172:175], v[40:43]
	v_mfma_f32_16x16x32_bf16 v[40:43], v[168:171], v[176:179], v[40:43]
	v_mfma_f32_16x16x32_bf16 v[24:27], v[164:167], v[180:183], v[24:27]
	v_mfma_f32_16x16x32_bf16 v[24:27], v[168:171], v[184:187], v[24:27]
	v_mfma_f32_16x16x32_bf16 v[8:11], v[164:167], v[188:191], v[8:11]
	v_mfma_f32_16x16x32_bf16 v[8:11], v[168:171], v[192:195], v[8:11]
	v_mfma_f32_16x16x32_bf16 v[0:3], v[164:167], v[196:199], v[0:3]
	v_mfma_f32_16x16x32_bf16 v[0:3], v[168:171], v[200:203], v[0:3]
	s_setprio 0
	s_barrier
	s_nop 1
	s_add_i32 s62, s62, 2
	s_add_u32 s18, s18, 0x100
	s_addc_u32 s19, s19, 0
	s_add_u32 s60, s60, 0x100
	s_addc_u32 s61, s61, 0
	s_cmp_gt_u32 s62, 5
	s_cbranch_scc0 .LBB0_997
	s_and_b64 vcc, exec, s[16:17]
	s_cbranch_vccz .LBB0_1000
	s_barrier

.LBB0_1012:
	s_ashr_i32 s15, s14, 31
	s_lshl_b64 s[16:17], s[14:15], 17
	s_add_u32 s16, s31, s16
	s_addc_u32 s17, s33, s17
	s_and_b64 s[18:19], s[36:37], exec
	s_cselect_b32 s29, s17, s23
	s_cselect_b32 s28, s16, s22
	s_ashr_i32 s13, s12, 31
	s_lshl_b64 s[18:19], s[12:13], 17
	s_add_u32 s18, s34, s18
	s_addc_u32 s19, s35, s19
	s_and_b64 s[26:27], s[36:37], exec
	s_cselect_b32 s27, s19, s25
	s_cselect_b32 s26, s18, s24
	s_add_i32 s49, 0, 0x10000
	s_add_i32 s15, 0, 0x14000
	v_add_u32_e32 v210, s49, v136
	v_add_u32_e32 v211, s15, v136
	ds_read_b128 v[0:3], v210
	ds_read_b128 v[4:7], v210 offset:1024
	ds_read_b128 v[8:11], v210 offset:2048
	ds_read_b128 v[12:15], v210 offset:3072
	ds_read_b128 v[16:19], v211
	ds_read_b128 v[20:23], v211 offset:1024
	ds_read_b128 v[24:27], v211 offset:2048
	ds_read_b128 v[28:31], v211 offset:3072
	s_add_u32 s52, s22, 0x10080
	s_addc_u32 s53, s23, 0
	s_add_i32 s51, s21, 0xc000
	v_lshl_add_u64 v[64:65], s[52:53], 0, v[132:133]
	s_mov_b32 m0, s51
	s_add_i32 s3, s21, 0xe000
	ds_read_b128 v[32:35], v137
	ds_read_b128 v[36:39], v137 offset:1024
	ds_read_b128 v[40:43], v137 offset:2048
	ds_read_b128 v[44:47], v137 offset:3072
	ds_read_b128 v[48:51], v137 offset:4096
	ds_read_b128 v[52:55], v137 offset:5120
	ds_read_b128 v[56:59], v137 offset:6144
	ds_read_b128 v[60:63], v137 offset:7168
	global_load_lds_dwordx4 v[64:65], off
	v_lshl_add_u64 v[64:65], s[52:53], 0, v[130:131]
	s_mov_b32 m0, s3
	s_nop 0
	global_load_lds_dwordx4 v[64:65], off
	s_waitcnt vmcnt(8)
	s_waitcnt lgkmcnt(0)
	s_barrier
	s_setprio 1
	s_waitcnt lgkmcnt(0)
	v_mfma_f32_16x16x32_bf16 v[64:67], v[0:3], v[32:35], 0
	v_mfma_f32_16x16x32_bf16 v[68:71], v[8:11], v[32:35], 0
	v_mfma_f32_16x16x32_bf16 v[72:75], v[0:3], v[40:43], 0
	v_mfma_f32_16x16x32_bf16 v[76:79], v[8:11], v[40:43], 0
	v_mfma_f32_16x16x32_bf16 v[80:83], v[0:3], v[48:51], 0
	v_mfma_f32_16x16x32_bf16 v[84:87], v[8:11], v[48:51], 0
	v_mfma_f32_16x16x32_bf16 v[88:91], v[0:3], v[56:59], 0
	v_mfma_f32_16x16x32_bf16 v[92:95], v[8:11], v[56:59], 0
	v_mfma_f32_16x16x32_bf16 v[64:67], v[4:7], v[36:39], v[64:67]
	v_mfma_f32_16x16x32_bf16 v[72:75], v[4:7], v[44:47], v[72:75]
	v_mfma_f32_16x16x32_bf16 v[80:83], v[4:7], v[52:55], v[80:83]
	v_mfma_f32_16x16x32_bf16 v[88:91], v[4:7], v[60:63], v[88:91]
	v_mfma_f32_16x16x32_bf16 v[68:71], v[12:15], v[36:39], v[68:71]
	v_mfma_f32_16x16x32_bf16 v[76:79], v[12:15], v[44:47], v[76:79]
	v_mfma_f32_16x16x32_bf16 v[84:87], v[12:15], v[52:55], v[84:87]
	v_mfma_f32_16x16x32_bf16 v[92:95], v[12:15], v[60:63], v[92:95]
	s_setprio 0
	s_setprio 1
	v_mfma_f32_16x16x32_bf16 v[96:99], v[16:19], v[32:35], 0
	v_mfma_f32_16x16x32_bf16 v[32:35], v[24:27], v[32:35], 0
	v_mfma_f32_16x16x32_bf16 v[96:99], v[20:23], v[36:39], v[96:99]
	v_mfma_f32_16x16x32_bf16 v[32:35], v[28:31], v[36:39], v[32:35]
	v_mfma_f32_16x16x32_bf16 v[36:39], v[16:19], v[40:43], 0
	v_mfma_f32_16x16x32_bf16 v[40:43], v[24:27], v[40:43], 0
	v_mfma_f32_16x16x32_bf16 v[36:39], v[20:23], v[44:47], v[36:39]
	v_mfma_f32_16x16x32_bf16 v[40:43], v[28:31], v[44:47], v[40:43]
	v_mfma_f32_16x16x32_bf16 v[44:47], v[16:19], v[48:51], 0
	v_mfma_f32_16x16x32_bf16 v[48:51], v[24:27], v[48:51], 0
	v_mfma_f32_16x16x32_bf16 v[44:47], v[20:23], v[52:55], v[44:47]
	v_mfma_f32_16x16x32_bf16 v[48:51], v[28:31], v[52:55], v[48:51]
	v_mfma_f32_16x16x32_bf16 v[52:55], v[16:19], v[56:59], 0
	v_mfma_f32_16x16x32_bf16 v[56:59], v[24:27], v[56:59], 0
	v_mfma_f32_16x16x32_bf16 v[52:55], v[20:23], v[60:63], v[52:55]
	v_mfma_f32_16x16x32_bf16 v[56:59], v[28:31], v[60:63], v[56:59]
	s_setprio 0
	s_barrier
	s_nop 1
	s_add_i32 s49, s49, s38
	v_lshl_add_u64 v[134:135], s[24:25], 0, v[212:213]
	s_mov_b64 s[54:55], 0x100
	s_add_i32 s13, s49, 0x2000
	v_lshl_add_u64 v[138:139], v[134:135], 0, s[54:55]
	s_mov_b32 m0, s49
	v_lshl_add_u64 v[202:203], s[24:25], 0, v[128:129]
	s_add_u32 s52, s24, 0x10100
	ds_read_b128 v[60:63], v137 offset:16384
	ds_read_b128 v[100:103], v137 offset:17408
	ds_read_b128 v[104:107], v137 offset:18432
	ds_read_b128 v[108:111], v137 offset:19456
	ds_read_b128 v[112:115], v137 offset:20480
	ds_read_b128 v[116:119], v137 offset:21504
	ds_read_b128 v[120:123], v137 offset:22528
	ds_read_b128 v[124:127], v137 offset:23552
	global_load_lds_dwordx4 v[138:139], off
	v_lshl_add_u64 v[138:139], v[202:203], 0, s[54:55]
	s_mov_b32 m0, s13
	s_addc_u32 s53, s25, 0
	s_add_i32 s15, s15, s38
	global_load_lds_dwordx4 v[138:139], off
	v_lshl_add_u64 v[138:139], s[52:53], 0, v[212:213]
	s_mov_b32 m0, s15
	s_add_i32 s47, s15, 0x2000
	global_load_lds_dwordx4 v[138:139], off
	v_lshl_add_u64 v[138:139], s[52:53], 0, v[128:129]
	s_mov_b32 m0, s47
	v_lshl_add_u64 v[204:205], s[22:23], 0, v[132:133]
	global_load_lds_dwordx4 v[138:139], off
	v_lshl_add_u64 v[138:139], v[204:205], 0, s[54:55]
	s_mov_b32 m0, s21
	v_lshl_add_u64 v[206:207], s[22:23], 0, v[130:131]
	global_load_lds_dwordx4 v[138:139], off
	v_lshl_add_u64 v[138:139], v[206:207], 0, s[54:55]
	s_mov_b32 m0, s39
	s_nop 0
	global_load_lds_dwordx4 v[138:139], off
	s_waitcnt vmcnt(8)
	s_waitcnt lgkmcnt(0)
	s_barrier
	s_setprio 1
	s_waitcnt lgkmcnt(0)
	v_mfma_f32_16x16x32_bf16 v[138:141], v[0:3], v[60:63], 0
	v_mfma_f32_16x16x32_bf16 v[146:149], v[0:3], v[104:107], 0
	v_mfma_f32_16x16x32_bf16 v[154:157], v[0:3], v[112:115], 0
	v_mfma_f32_16x16x32_bf16 v[0:3], v[0:3], v[120:123], 0
	v_mfma_f32_16x16x32_bf16 v[138:141], v[4:7], v[100:103], v[138:141]
	v_mfma_f32_16x16x32_bf16 v[146:149], v[4:7], v[108:111], v[146:149]
	v_mfma_f32_16x16x32_bf16 v[154:157], v[4:7], v[116:119], v[154:157]
	v_mfma_f32_16x16x32_bf16 v[0:3], v[4:7], v[124:127], v[0:3]
	v_mfma_f32_16x16x32_bf16 v[4:7], v[8:11], v[120:123], 0
	v_mfma_f32_16x16x32_bf16 v[142:145], v[8:11], v[60:63], 0
	v_mfma_f32_16x16x32_bf16 v[150:153], v[8:11], v[104:107], 0
	v_mfma_f32_16x16x32_bf16 v[158:161], v[8:11], v[112:115], 0
	v_mfma_f32_16x16x32_bf16 v[4:7], v[12:15], v[124:127], v[4:7]
	v_mfma_f32_16x16x32_bf16 v[142:145], v[12:15], v[100:103], v[142:145]
	v_mfma_f32_16x16x32_bf16 v[150:153], v[12:15], v[108:111], v[150:153]
	v_mfma_f32_16x16x32_bf16 v[158:161], v[12:15], v[116:119], v[158:161]
	s_setprio 0
	s_setprio 1
	v_mfma_f32_16x16x32_bf16 v[8:11], v[16:19], v[60:63], 0
	v_mfma_f32_16x16x32_bf16 v[12:15], v[24:27], v[60:63], 0
	v_mfma_f32_16x16x32_bf16 v[8:11], v[20:23], v[100:103], v[8:11]
	v_mfma_f32_16x16x32_bf16 v[12:15], v[28:31], v[100:103], v[12:15]
	v_mfma_f32_16x16x32_bf16 v[60:63], v[16:19], v[104:107], 0
	v_mfma_f32_16x16x32_bf16 v[100:103], v[24:27], v[104:107], 0
	v_mfma_f32_16x16x32_bf16 v[104:107], v[16:19], v[112:115], 0
	v_mfma_f32_16x16x32_bf16 v[16:19], v[16:19], v[120:123], 0
	v_mfma_f32_16x16x32_bf16 v[60:63], v[20:23], v[108:111], v[60:63]
	v_mfma_f32_16x16x32_bf16 v[100:103], v[28:31], v[108:111], v[100:103]
	v_mfma_f32_16x16x32_bf16 v[104:107], v[20:23], v[116:119], v[104:107]
	v_mfma_f32_16x16x32_bf16 v[108:111], v[24:27], v[112:115], 0
	v_mfma_f32_16x16x32_bf16 v[16:19], v[20:23], v[124:127], v[16:19]
	v_mfma_f32_16x16x32_bf16 v[20:23], v[24:27], v[120:123], 0
	v_mfma_f32_16x16x32_bf16 v[108:111], v[28:31], v[116:119], v[108:111]
	v_mfma_f32_16x16x32_bf16 v[20:23], v[28:31], v[124:127], v[20:23]
	s_setprio 0
	s_barrier
	s_nop 1
	s_add_i32 s50, 0, 0x18000
	s_add_i32 s56, 0, 0x1c000
	v_add_u32_e32 v214, s50, v136
	v_add_u32_e32 v215, s56, v136
	ds_read_b128 v[24:27], v214
	ds_read_b128 v[28:31], v214 offset:1024
	ds_read_b128 v[112:115], v214 offset:2048
	ds_read_b128 v[116:119], v214 offset:3072
	ds_read_b128 v[120:123], v215
	ds_read_b128 v[124:127], v215 offset:1024
	ds_read_b128 v[162:165], v215 offset:2048
	ds_read_b128 v[166:169], v215 offset:3072
	s_add_u32 s52, s22, 0x10100
	s_addc_u32 s53, s23, 0
	s_mov_b32 m0, s40
	v_lshl_add_u64 v[208:209], s[52:53], 0, v[132:133]
	ds_read_b128 v[170:173], v137 offset:32768
	ds_read_b128 v[174:177], v137 offset:33792
	ds_read_b128 v[178:181], v137 offset:34816
	ds_read_b128 v[182:185], v137 offset:35840
	ds_read_b128 v[186:189], v137 offset:36864
	ds_read_b128 v[190:193], v137 offset:37888
	ds_read_b128 v[194:197], v137 offset:38912
	ds_read_b128 v[198:201], v137 offset:39936
	global_load_lds_dwordx4 v[208:209], off
	v_lshl_add_u64 v[208:209], s[52:53], 0, v[130:131]
	s_mov_b32 m0, s41
	s_nop 0
	global_load_lds_dwordx4 v[208:209], off
	s_waitcnt vmcnt(8)
	s_waitcnt lgkmcnt(0)
	s_barrier
	s_setprio 1
	s_waitcnt lgkmcnt(0)
	v_mfma_f32_16x16x32_bf16 v[64:67], v[24:27], v[170:173], v[64:67]
	v_mfma_f32_16x16x32_bf16 v[64:67], v[28:31], v[174:177], v[64:67]
	v_mfma_f32_16x16x32_bf16 v[72:75], v[24:27], v[178:181], v[72:75]
	v_mfma_f32_16x16x32_bf16 v[72:75], v[28:31], v[182:185], v[72:75]
	v_mfma_f32_16x16x32_bf16 v[80:83], v[24:27], v[186:189], v[80:83]
	v_mfma_f32_16x16x32_bf16 v[80:83], v[28:31], v[190:193], v[80:83]
	v_mfma_f32_16x16x32_bf16 v[88:91], v[24:27], v[194:197], v[88:91]
	v_mfma_f32_16x16x32_bf16 v[88:91], v[28:31], v[198:201], v[88:91]
	v_mfma_f32_16x16x32_bf16 v[68:71], v[112:115], v[170:173], v[68:71]
	v_mfma_f32_16x16x32_bf16 v[68:71], v[116:119], v[174:177], v[68:71]
	v_mfma_f32_16x16x32_bf16 v[76:79], v[112:115], v[178:181], v[76:79]
	v_mfma_f32_16x16x32_bf16 v[76:79], v[116:119], v[182:185], v[76:79]
	v_mfma_f32_16x16x32_bf16 v[84:87], v[112:115], v[186:189], v[84:87]
	v_mfma_f32_16x16x32_bf16 v[84:87], v[116:119], v[190:193], v[84:87]
	v_mfma_f32_16x16x32_bf16 v[92:95], v[112:115], v[194:197], v[92:95]
	v_mfma_f32_16x16x32_bf16 v[92:95], v[116:119], v[198:201], v[92:95]
	s_setprio 0
	s_setprio 1
	v_mfma_f32_16x16x32_bf16 v[96:99], v[120:123], v[170:173], v[96:99]
	v_mfma_f32_16x16x32_bf16 v[96:99], v[124:127], v[174:177], v[96:99]
	v_mfma_f32_16x16x32_bf16 v[36:39], v[120:123], v[178:181], v[36:39]
	v_mfma_f32_16x16x32_bf16 v[36:39], v[124:127], v[182:185], v[36:39]
	v_mfma_f32_16x16x32_bf16 v[44:47], v[120:123], v[186:189], v[44:47]
	v_mfma_f32_16x16x32_bf16 v[44:47], v[124:127], v[190:193], v[44:47]
	v_mfma_f32_16x16x32_bf16 v[52:55], v[120:123], v[194:197], v[52:55]
	v_mfma_f32_16x16x32_bf16 v[52:55], v[124:127], v[198:201], v[52:55]
	v_mfma_f32_16x16x32_bf16 v[32:35], v[162:165], v[170:173], v[32:35]
	v_mfma_f32_16x16x32_bf16 v[32:35], v[166:169], v[174:177], v[32:35]
	v_mfma_f32_16x16x32_bf16 v[40:43], v[162:165], v[178:181], v[40:43]
	v_mfma_f32_16x16x32_bf16 v[40:43], v[166:169], v[182:185], v[40:43]
	v_mfma_f32_16x16x32_bf16 v[48:51], v[162:165], v[186:189], v[48:51]
	v_mfma_f32_16x16x32_bf16 v[48:51], v[166:169], v[190:193], v[48:51]
	v_mfma_f32_16x16x32_bf16 v[56:59], v[162:165], v[194:197], v[56:59]
	v_mfma_f32_16x16x32_bf16 v[56:59], v[166:169], v[198:201], v[56:59]
	s_setprio 0
	s_barrier
	s_nop 1
	s_add_i32 s52, s50, s38
	s_mov_b64 s[60:61], 0x180
	s_add_i32 s50, s52, 0x2000
	v_lshl_add_u64 v[134:135], v[134:135], 0, s[60:61]
	s_mov_b32 m0, s52
	s_add_u32 s54, s24, 0x10180
	ds_read_b128 v[170:173], v137 offset:49152
	ds_read_b128 v[174:177], v137 offset:50176
	ds_read_b128 v[178:181], v137 offset:51200
	ds_read_b128 v[182:185], v137 offset:52224
	ds_read_b128 v[186:189], v137 offset:53248
	ds_read_b128 v[190:193], v137 offset:54272
	ds_read_b128 v[194:197], v137 offset:55296
	ds_read_b128 v[198:201], v137 offset:56320
	global_load_lds_dwordx4 v[134:135], off
	v_lshl_add_u64 v[134:135], v[202:203], 0, s[60:61]
	s_mov_b32 m0, s50
	s_addc_u32 s55, s25, 0
	s_add_i32 s24, s56, s38
	global_load_lds_dwordx4 v[134:135], off
	v_lshl_add_u64 v[134:135], s[54:55], 0, v[212:213]
	s_mov_b32 m0, s24
	s_add_i32 s25, s24, 0x2000
	global_load_lds_dwordx4 v[134:135], off
	v_lshl_add_u64 v[134:135], s[54:55], 0, v[128:129]
	s_mov_b32 m0, s25
	s_nop 0
	global_load_lds_dwordx4 v[134:135], off
	v_lshl_add_u64 v[134:135], v[204:205], 0, s[60:61]
	s_mov_b32 m0, s44
	s_nop 0
	global_load_lds_dwordx4 v[134:135], off
	v_lshl_add_u64 v[134:135], v[206:207], 0, s[60:61]
	s_mov_b32 m0, s45
	s_nop 0
	global_load_lds_dwordx4 v[134:135], off
	s_waitcnt vmcnt(8)
	s_waitcnt lgkmcnt(0)
	s_barrier
	s_setprio 1
	s_waitcnt lgkmcnt(0)
	v_mfma_f32_16x16x32_bf16 v[0:3], v[24:27], v[194:197], v[0:3]
	v_mfma_f32_16x16x32_bf16 v[0:3], v[28:31], v[198:201], v[0:3]
	v_mfma_f32_16x16x32_bf16 v[138:141], v[24:27], v[170:173], v[138:141]
	v_mfma_f32_16x16x32_bf16 v[138:141], v[28:31], v[174:177], v[138:141]
	v_mfma_f32_16x16x32_bf16 v[146:149], v[24:27], v[178:181], v[146:149]
	v_mfma_f32_16x16x32_bf16 v[146:149], v[28:31], v[182:185], v[146:149]
	v_mfma_f32_16x16x32_bf16 v[154:157], v[24:27], v[186:189], v[154:157]
	v_mfma_f32_16x16x32_bf16 v[154:157], v[28:31], v[190:193], v[154:157]
	v_mfma_f32_16x16x32_bf16 v[4:7], v[112:115], v[194:197], v[4:7]
	v_mfma_f32_16x16x32_bf16 v[4:7], v[116:119], v[198:201], v[4:7]
	v_mfma_f32_16x16x32_bf16 v[142:145], v[112:115], v[170:173], v[142:145]
	v_mfma_f32_16x16x32_bf16 v[142:145], v[116:119], v[174:177], v[142:145]
	v_mfma_f32_16x16x32_bf16 v[150:153], v[112:115], v[178:181], v[150:153]
	v_mfma_f32_16x16x32_bf16 v[150:153], v[116:119], v[182:185], v[150:153]
	v_mfma_f32_16x16x32_bf16 v[158:161], v[112:115], v[186:189], v[158:161]
	v_mfma_f32_16x16x32_bf16 v[158:161], v[116:119], v[190:193], v[158:161]
	s_setprio 0
	s_setprio 1
	v_mfma_f32_16x16x32_bf16 v[8:11], v[120:123], v[170:173], v[8:11]
	v_mfma_f32_16x16x32_bf16 v[8:11], v[124:127], v[174:177], v[8:11]
	v_mfma_f32_16x16x32_bf16 v[24:27], v[120:123], v[178:181], v[60:63]
	v_mfma_f32_16x16x32_bf16 v[24:27], v[124:127], v[182:185], v[24:27]
	v_mfma_f32_16x16x32_bf16 v[16:19], v[120:123], v[194:197], v[16:19]
	v_mfma_f32_16x16x32_bf16 v[16:19], v[124:127], v[198:201], v[16:19]
	v_mfma_f32_16x16x32_bf16 v[12:15], v[162:165], v[170:173], v[12:15]
	v_mfma_f32_16x16x32_bf16 v[12:15], v[166:169], v[174:177], v[12:15]
	v_mfma_f32_16x16x32_bf16 v[28:31], v[162:165], v[178:181], v[100:103]
	v_mfma_f32_16x16x32_bf16 v[28:31], v[166:169], v[182:185], v[28:31]
	v_mfma_f32_16x16x32_bf16 v[60:63], v[120:123], v[186:189], v[104:107]
	v_mfma_f32_16x16x32_bf16 v[60:63], v[124:127], v[190:193], v[60:63]
	v_mfma_f32_16x16x32_bf16 v[100:103], v[162:165], v[186:189], v[108:111]
	v_mfma_f32_16x16x32_bf16 v[100:103], v[166:169], v[190:193], v[100:103]
	v_mfma_f32_16x16x32_bf16 v[20:23], v[162:165], v[194:197], v[20:23]
	v_mfma_f32_16x16x32_bf16 v[20:23], v[166:169], v[198:201], v[20:23]
	s_setprio 0
	s_barrier
	s_nop 1
	ds_read_b128 v[104:107], v210
	ds_read_b128 v[108:111], v210 offset:1024
	ds_read_b128 v[112:115], v210 offset:2048
	ds_read_b128 v[116:119], v210 offset:3072
	ds_read_b128 v[120:123], v211
	ds_read_b128 v[124:127], v211 offset:1024
	ds_read_b128 v[162:165], v211 offset:2048
	ds_read_b128 v[166:169], v211 offset:3072
	s_add_u32 s22, s22, 0x10180
	s_addc_u32 s23, s23, 0
	s_mov_b32 m0, s51
	v_lshl_add_u64 v[134:135], s[22:23], 0, v[132:133]
	ds_read_b128 v[170:173], v137
	ds_read_b128 v[174:177], v137 offset:1024
	ds_read_b128 v[178:181], v137 offset:2048
	ds_read_b128 v[182:185], v137 offset:3072
	ds_read_b128 v[186:189], v137 offset:4096
	ds_read_b128 v[190:193], v137 offset:5120
	ds_read_b128 v[194:197], v137 offset:6144
	ds_read_b128 v[198:201], v137 offset:7168
	global_load_lds_dwordx4 v[134:135], off
	v_lshl_add_u64 v[134:135], s[22:23], 0, v[130:131]
	s_mov_b32 m0, s3
	s_nop 0
	global_load_lds_dwordx4 v[134:135], off
	s_waitcnt vmcnt(8)
	s_waitcnt lgkmcnt(0)
	s_barrier
	s_setprio 1
	s_waitcnt lgkmcnt(0)
	v_mfma_f32_16x16x32_bf16 v[64:67], v[104:107], v[170:173], v[64:67]
	v_mfma_f32_16x16x32_bf16 v[64:67], v[108:111], v[174:177], v[64:67]
	v_mfma_f32_16x16x32_bf16 v[72:75], v[104:107], v[178:181], v[72:75]
	v_mfma_f32_16x16x32_bf16 v[72:75], v[108:111], v[182:185], v[72:75]
	v_mfma_f32_16x16x32_bf16 v[80:83], v[104:107], v[186:189], v[80:83]
	v_mfma_f32_16x16x32_bf16 v[80:83], v[108:111], v[190:193], v[80:83]
	v_mfma_f32_16x16x32_bf16 v[88:91], v[104:107], v[194:197], v[88:91]
	v_mfma_f32_16x16x32_bf16 v[202:205], v[108:111], v[198:201], v[88:91]
	v_mfma_f32_16x16x32_bf16 v[68:71], v[112:115], v[170:173], v[68:71]
	v_mfma_f32_16x16x32_bf16 v[68:71], v[116:119], v[174:177], v[68:71]
	v_mfma_f32_16x16x32_bf16 v[76:79], v[112:115], v[178:181], v[76:79]
	v_mfma_f32_16x16x32_bf16 v[76:79], v[116:119], v[182:185], v[76:79]
	v_mfma_f32_16x16x32_bf16 v[84:87], v[112:115], v[186:189], v[84:87]
	v_mfma_f32_16x16x32_bf16 v[84:87], v[116:119], v[190:193], v[84:87]
	v_mfma_f32_16x16x32_bf16 v[88:91], v[112:115], v[194:197], v[92:95]
	v_mfma_f32_16x16x32_bf16 v[92:95], v[116:119], v[198:201], v[88:91]
	s_setprio 0
	s_setprio 1
	v_mfma_f32_16x16x32_bf16 v[48:51], v[162:165], v[186:189], v[48:51]
	v_mfma_f32_16x16x32_bf16 v[88:91], v[120:123], v[170:173], v[96:99]
	v_mfma_f32_16x16x32_bf16 v[206:209], v[124:127], v[174:177], v[88:91]
	v_mfma_f32_16x16x32_bf16 v[36:39], v[120:123], v[178:181], v[36:39]
	v_mfma_f32_16x16x32_bf16 v[36:39], v[124:127], v[182:185], v[36:39]
	v_mfma_f32_16x16x32_bf16 v[32:35], v[162:165], v[170:173], v[32:35]
	v_mfma_f32_16x16x32_bf16 v[32:35], v[166:169], v[174:177], v[32:35]
	v_mfma_f32_16x16x32_bf16 v[40:43], v[162:165], v[178:181], v[40:43]
	v_mfma_f32_16x16x32_bf16 v[40:43], v[166:169], v[182:185], v[40:43]
	v_mfma_f32_16x16x32_bf16 v[44:47], v[120:123], v[186:189], v[44:47]
	v_mfma_f32_16x16x32_bf16 v[44:47], v[124:127], v[190:193], v[44:47]
	v_mfma_f32_16x16x32_bf16 v[170:173], v[166:169], v[190:193], v[48:51]
	v_mfma_f32_16x16x32_bf16 v[48:51], v[120:123], v[194:197], v[52:55]
	v_mfma_f32_16x16x32_bf16 v[52:55], v[124:127], v[198:201], v[48:51]
	v_mfma_f32_16x16x32_bf16 v[48:51], v[162:165], v[194:197], v[56:59]
	v_mfma_f32_16x16x32_bf16 v[174:177], v[166:169], v[198:201], v[48:51]
	s_setprio 0
	s_barrier
	s_nop 1
	s_mov_b32 m0, s49
	v_lshl_add_u64 v[134:135], s[26:27], 0, v[212:213]
	s_add_u32 s22, s26, 0x10000
	s_nop 0
	ds_read_b128 v[48:51], v137 offset:16384
	ds_read_b128 v[56:59], v137 offset:17408
	ds_read_b128 v[88:91], v137 offset:18432
	ds_read_b128 v[96:99], v137 offset:19456
	ds_read_b128 v[178:181], v137 offset:20480
	ds_read_b128 v[182:185], v137 offset:21504
	ds_read_b128 v[186:189], v137 offset:22528
	ds_read_b128 v[190:193], v137 offset:23552
	global_load_lds_dwordx4 v[134:135], off
	v_lshl_add_u64 v[210:211], s[26:27], 0, v[128:129]
	s_mov_b32 m0, s13
	s_addc_u32 s23, s27, 0
	global_load_lds_dwordx4 v[210:211], off
	v_lshl_add_u64 v[194:195], s[22:23], 0, v[212:213]
	s_mov_b32 m0, s15
	v_lshl_add_u64 v[226:227], s[28:29], 0, v[132:133]
	global_load_lds_dwordx4 v[194:195], off
	v_lshl_add_u64 v[194:195], s[22:23], 0, v[128:129]
	s_mov_b32 m0, s47
	v_lshl_add_u64 v[234:235], s[28:29], 0, v[130:131]
	global_load_lds_dwordx4 v[194:195], off
	s_mov_b32 m0, s21
	s_nop 0
	global_load_lds_dwordx4 v[226:227], off
	s_mov_b32 m0, s39
	s_nop 0
	global_load_lds_dwordx4 v[234:235], off
	s_waitcnt vmcnt(8)
	s_waitcnt lgkmcnt(0)
	s_barrier
	s_setprio 1
	s_waitcnt lgkmcnt(0)
	v_mfma_f32_16x16x32_bf16 v[0:3], v[104:107], v[186:189], v[0:3]
	v_mfma_f32_16x16x32_bf16 v[0:3], v[108:111], v[190:193], v[0:3]
	v_mfma_f32_16x16x32_bf16 v[138:141], v[104:107], v[48:51], v[138:141]
	v_mfma_f32_16x16x32_bf16 v[138:141], v[108:111], v[56:59], v[138:141]
	v_mfma_f32_16x16x32_bf16 v[146:149], v[104:107], v[88:91], v[146:149]
	v_mfma_f32_16x16x32_bf16 v[146:149], v[108:111], v[96:99], v[146:149]
	v_mfma_f32_16x16x32_bf16 v[154:157], v[104:107], v[178:181], v[154:157]
	v_mfma_f32_16x16x32_bf16 v[154:157], v[108:111], v[182:185], v[154:157]
	v_mfma_f32_16x16x32_bf16 v[4:7], v[112:115], v[186:189], v[4:7]
	v_mfma_f32_16x16x32_bf16 v[4:7], v[116:119], v[190:193], v[4:7]
	v_mfma_f32_16x16x32_bf16 v[142:145], v[112:115], v[48:51], v[142:145]
	v_mfma_f32_16x16x32_bf16 v[142:145], v[116:119], v[56:59], v[142:145]
	v_mfma_f32_16x16x32_bf16 v[150:153], v[112:115], v[88:91], v[150:153]
	v_mfma_f32_16x16x32_bf16 v[150:153], v[116:119], v[96:99], v[150:153]
	v_mfma_f32_16x16x32_bf16 v[158:161], v[112:115], v[178:181], v[158:161]
	v_mfma_f32_16x16x32_bf16 v[158:161], v[116:119], v[182:185], v[158:161]
	s_setprio 0
	s_setprio 1
	v_mfma_f32_16x16x32_bf16 v[12:15], v[162:165], v[48:51], v[12:15]
	v_mfma_f32_16x16x32_bf16 v[194:197], v[166:169], v[56:59], v[12:15]
	v_mfma_f32_16x16x32_bf16 v[12:15], v[120:123], v[88:91], v[24:27]
	v_mfma_f32_16x16x32_bf16 v[24:27], v[124:127], v[96:99], v[12:15]
	v_mfma_f32_16x16x32_bf16 v[12:15], v[162:165], v[88:91], v[28:31]
	v_mfma_f32_16x16x32_bf16 v[198:201], v[166:169], v[96:99], v[12:15]
	v_mfma_f32_16x16x32_bf16 v[12:15], v[120:123], v[178:181], v[60:63]
	v_mfma_f32_16x16x32_bf16 v[218:221], v[124:127], v[182:185], v[12:15]
	v_mfma_f32_16x16x32_bf16 v[12:15], v[162:165], v[178:181], v[100:103]
	v_mfma_f32_16x16x32_bf16 v[178:181], v[166:169], v[182:185], v[12:15]
	v_mfma_f32_16x16x32_bf16 v[8:11], v[120:123], v[48:51], v[8:11]
	v_mfma_f32_16x16x32_bf16 v[8:11], v[124:127], v[56:59], v[8:11]
	v_mfma_f32_16x16x32_bf16 v[12:15], v[120:123], v[186:189], v[16:19]
	v_mfma_f32_16x16x32_bf16 v[182:185], v[124:127], v[190:193], v[12:15]
	v_mfma_f32_16x16x32_bf16 v[12:15], v[162:165], v[186:189], v[20:23]
	v_mfma_f32_16x16x32_bf16 v[162:165], v[166:169], v[190:193], v[12:15]
	s_setprio 0
	s_barrier
	s_nop 1
	s_nop 4
	ds_read_b128 v[12:15], v214
	ds_read_b128 v[16:19], v214 offset:1024
	ds_read_b128 v[166:169], v214 offset:2048
	ds_read_b128 v[186:189], v214 offset:3072
	ds_read_b128 v[190:193], v215
	ds_read_b128 v[222:225], v215 offset:1024
	ds_read_b128 v[238:241], v215 offset:2048
	ds_read_b128 v[242:245], v215 offset:3072
	s_add_u32 s22, s28, 0x10000
	s_addc_u32 s23, s29, 0
	s_mov_b32 m0, s40
	v_lshl_add_u64 v[48:49], s[22:23], 0, v[132:133]
	ds_read_b128 v[20:23], v137 offset:32768
	ds_read_b128 v[28:31], v137 offset:33792
	ds_read_b128 v[60:63], v137 offset:34816
	ds_read_b128 v[100:103], v137 offset:35840
	ds_read_b128 v[246:249], v137 offset:36864
	ds_read_b128 v[250:253], v137 offset:37888
	ds_read_b128 v[230:233], v137 offset:38912
	ds_read_b128 v[214:217], v137 offset:39936
	global_load_lds_dwordx4 v[48:49], off
	v_lshl_add_u64 v[48:49], s[22:23], 0, v[130:131]
	s_mov_b32 m0, s41
	s_nop 0
	global_load_lds_dwordx4 v[48:49], off
	s_waitcnt vmcnt(8)
	s_waitcnt lgkmcnt(0)
	s_barrier
	s_setprio 1
	s_waitcnt lgkmcnt(0)
	v_mfma_f32_16x16x32_bf16 v[48:51], v[12:15], v[20:23], v[64:67]
	v_mfma_f32_16x16x32_bf16 v[120:123], v[16:19], v[28:31], v[48:51]
	v_mfma_f32_16x16x32_bf16 v[48:51], v[166:169], v[20:23], v[68:71]
	v_mfma_f32_16x16x32_bf16 v[112:115], v[186:189], v[28:31], v[48:51]
	v_mfma_f32_16x16x32_bf16 v[48:51], v[12:15], v[60:63], v[72:75]
	v_mfma_f32_16x16x32_bf16 v[104:107], v[16:19], v[100:103], v[48:51]
	v_mfma_f32_16x16x32_bf16 v[48:51], v[166:169], v[60:63], v[76:79]
	v_mfma_f32_16x16x32_bf16 v[96:99], v[186:189], v[100:103], v[48:51]
	v_mfma_f32_16x16x32_bf16 v[48:51], v[12:15], v[246:249], v[80:83]
	v_mfma_f32_16x16x32_bf16 v[88:91], v[16:19], v[250:253], v[48:51]
	v_mfma_f32_16x16x32_bf16 v[48:51], v[166:169], v[246:249], v[84:87]
	v_mfma_f32_16x16x32_bf16 v[80:83], v[186:189], v[250:253], v[48:51]
	v_mfma_f32_16x16x32_bf16 v[48:51], v[12:15], v[230:233], v[202:205]
	v_mfma_f32_16x16x32_bf16 v[56:59], v[16:19], v[214:217], v[48:51]
	v_mfma_f32_16x16x32_bf16 v[48:51], v[166:169], v[230:233], v[92:95]
	v_mfma_f32_16x16x32_bf16 v[48:51], v[186:189], v[214:217], v[48:51]
	s_setprio 0
	s_setprio 1
	v_mfma_f32_16x16x32_bf16 v[64:67], v[190:193], v[20:23], v[206:209]
	v_mfma_f32_16x16x32_bf16 v[124:127], v[222:225], v[28:31], v[64:67]
	v_mfma_f32_16x16x32_bf16 v[20:23], v[238:241], v[20:23], v[32:35]
	v_mfma_f32_16x16x32_bf16 v[116:119], v[242:245], v[28:31], v[20:23]
	v_mfma_f32_16x16x32_bf16 v[20:23], v[190:193], v[60:63], v[36:39]
	v_mfma_f32_16x16x32_bf16 v[108:111], v[222:225], v[100:103], v[20:23]
	v_mfma_f32_16x16x32_bf16 v[20:23], v[238:241], v[60:63], v[40:43]
	v_mfma_f32_16x16x32_bf16 v[100:103], v[242:245], v[100:103], v[20:23]
	v_mfma_f32_16x16x32_bf16 v[20:23], v[190:193], v[246:249], v[44:47]
	v_mfma_f32_16x16x32_bf16 v[92:95], v[222:225], v[250:253], v[20:23]
	v_mfma_f32_16x16x32_bf16 v[20:23], v[238:241], v[246:249], v[170:173]
	v_mfma_f32_16x16x32_bf16 v[84:87], v[242:245], v[250:253], v[20:23]
	v_mfma_f32_16x16x32_bf16 v[20:23], v[190:193], v[230:233], v[52:55]
	v_mfma_f32_16x16x32_bf16 v[60:63], v[222:225], v[214:217], v[20:23]
	v_mfma_f32_16x16x32_bf16 v[20:23], v[238:241], v[230:233], v[174:177]
	v_mfma_f32_16x16x32_bf16 v[52:55], v[242:245], v[214:217], v[20:23]
	s_setprio 0
	s_barrier
	s_nop 1
	s_mov_b32 m0, s52
	s_nop 2
	v_lshl_add_u64 v[20:21], v[134:135], 0, s[72:73]
	s_add_u32 s22, s26, 0x10080
	ds_read_b128 v[32:35], v137 offset:49152
	ds_read_b128 v[40:43], v137 offset:50176
	ds_read_b128 v[170:173], v137 offset:51200
	ds_read_b128 v[174:177], v137 offset:52224
	ds_read_b128 v[202:205], v137 offset:53248
	ds_read_b128 v[206:209], v137 offset:54272
	ds_read_b128 v[214:217], v137 offset:55296
	ds_read_b128 v[230:233], v137 offset:56320
	global_load_lds_dwordx4 v[20:21], off
	v_lshl_add_u64 v[20:21], v[210:211], 0, s[72:73]
	s_mov_b32 m0, s50
	s_addc_u32 s23, s27, 0
	global_load_lds_dwordx4 v[20:21], off
	v_lshl_add_u64 v[20:21], s[22:23], 0, v[212:213]
	s_mov_b32 m0, s24
	s_nop 0
	global_load_lds_dwordx4 v[20:21], off
	v_lshl_add_u64 v[20:21], s[22:23], 0, v[128:129]
	s_mov_b32 m0, s25
	s_nop 0
	global_load_lds_dwordx4 v[20:21], off
	v_lshl_add_u64 v[20:21], v[226:227], 0, s[72:73]
	s_mov_b32 m0, s44
	s_nop 0
	global_load_lds_dwordx4 v[20:21], off
	v_lshl_add_u64 v[20:21], v[234:235], 0, s[72:73]
	s_mov_b32 m0, s45
	s_nop 0
	global_load_lds_dwordx4 v[20:21], off
	s_waitcnt vmcnt(8)
	s_waitcnt lgkmcnt(0)
	s_barrier
	s_setprio 1
	s_waitcnt lgkmcnt(0)
	v_mfma_f32_16x16x32_bf16 v[20:23], v[12:15], v[32:35], v[138:141]
	v_mfma_f32_16x16x32_bf16 v[76:79], v[16:19], v[40:43], v[20:23]
	v_mfma_f32_16x16x32_bf16 v[20:23], v[166:169], v[32:35], v[142:145]
	v_mfma_f32_16x16x32_bf16 v[68:71], v[186:189], v[40:43], v[20:23]
	v_mfma_f32_16x16x32_bf16 v[20:23], v[12:15], v[170:173], v[146:149]
	v_mfma_f32_16x16x32_bf16 v[44:47], v[16:19], v[174:177], v[20:23]
	v_mfma_f32_16x16x32_bf16 v[20:23], v[166:169], v[170:173], v[150:153]
	v_mfma_f32_16x16x32_bf16 v[36:39], v[186:189], v[174:177], v[20:23]
	v_mfma_f32_16x16x32_bf16 v[20:23], v[12:15], v[202:205], v[154:157]
	v_mfma_f32_16x16x32_bf16 v[28:31], v[16:19], v[206:209], v[20:23]
	v_mfma_f32_16x16x32_bf16 v[0:3], v[12:15], v[214:217], v[0:3]
	v_mfma_f32_16x16x32_bf16 v[12:15], v[16:19], v[230:233], v[0:3]
	v_mfma_f32_16x16x32_bf16 v[20:23], v[166:169], v[202:205], v[158:161]
	v_mfma_f32_16x16x32_bf16 v[20:23], v[186:189], v[206:209], v[20:23]
	v_mfma_f32_16x16x32_bf16 v[0:3], v[166:169], v[214:217], v[4:7]
	v_mfma_f32_16x16x32_bf16 v[4:7], v[186:189], v[230:233], v[0:3]
	s_setprio 0
	s_setprio 1
	v_mfma_f32_16x16x32_bf16 v[0:3], v[190:193], v[32:35], v[8:11]
	v_mfma_f32_16x16x32_bf16 v[72:75], v[222:225], v[40:43], v[0:3]
	v_mfma_f32_16x16x32_bf16 v[0:3], v[238:241], v[32:35], v[194:197]
	v_mfma_f32_16x16x32_bf16 v[64:67], v[242:245], v[40:43], v[0:3]
	v_mfma_f32_16x16x32_bf16 v[0:3], v[190:193], v[170:173], v[24:27]
	v_mfma_f32_16x16x32_bf16 v[40:43], v[222:225], v[174:177], v[0:3]
	v_mfma_f32_16x16x32_bf16 v[0:3], v[238:241], v[170:173], v[198:201]
	v_mfma_f32_16x16x32_bf16 v[32:35], v[242:245], v[174:177], v[0:3]
	v_mfma_f32_16x16x32_bf16 v[0:3], v[190:193], v[202:205], v[218:221]
	v_mfma_f32_16x16x32_bf16 v[24:27], v[222:225], v[206:209], v[0:3]
	v_mfma_f32_16x16x32_bf16 v[0:3], v[238:241], v[202:205], v[178:181]
	v_mfma_f32_16x16x32_bf16 v[16:19], v[242:245], v[206:209], v[0:3]
	v_mfma_f32_16x16x32_bf16 v[0:3], v[190:193], v[214:217], v[182:185]
	v_mfma_f32_16x16x32_bf16 v[8:11], v[222:225], v[230:233], v[0:3]
	v_mfma_f32_16x16x32_bf16 v[0:3], v[238:241], v[214:217], v[162:165]
	v_mfma_f32_16x16x32_bf16 v[0:3], v[242:245], v[230:233], v[0:3]
	s_setprio 0
	s_barrier
	s_nop 1
	s_andn2_b64 vcc, exec, s[8:9]
	s_cbranch_vccnz .LBB0_1014
	s_barrier

.LBB0_1239:
	s_add_i32 s2, s34, 2
	s_add_u32 s3, s74, s30
	s_addc_u32 s35, s75, s31
	s_add_u32 s3, s3, 0x100
	s_addc_u32 s35, s35, 0
	s_add_u32 s39, s9, s30
	s_addc_u32 s63, s17, s31
	s_cmp_eq_u32 s45, s34
	s_cselect_b32 s89, s11, s35
	s_cselect_b32 s88, s10, s3
	s_cselect_b32 s35, s13, s63
	s_cselect_b32 s34, s12, s39
	s_add_i32 s3, 0, 0x10000
	s_add_i32 s39, 0, 0x14000
	v_add_u32_e32 v136, s3, v220
	v_add_u32_e32 v160, s39, v220
	ds_read_b128 v[108:111], v136
	ds_read_b128 v[120:123], v136 offset:1024
	ds_read_b128 v[132:135], v136 offset:2048
	ds_read_b128 v[136:139], v136 offset:3072
	ds_read_b128 v[140:143], v160
	ds_read_b128 v[144:147], v160 offset:1024
	ds_read_b128 v[148:151], v160 offset:2048
	ds_read_b128 v[160:163], v160 offset:3072
	v_lshl_add_u64 v[196:197], v[96:97], 0, s[30:31]
	s_add_i32 m0, s15, 0xc000
	ds_read_b128 v[164:167], v223
	ds_read_b128 v[168:171], v223 offset:1024
	ds_read_b128 v[172:175], v223 offset:2048
	ds_read_b128 v[176:179], v223 offset:3072
	ds_read_b128 v[180:183], v223 offset:4096
	ds_read_b128 v[184:187], v223 offset:5120
	ds_read_b128 v[188:191], v223 offset:6144
	ds_read_b128 v[192:195], v223 offset:7168
	global_load_lds_dwordx4 v[196:197], off
	v_lshl_add_u64 v[196:197], v[98:99], 0, s[30:31]
	s_add_i32 m0, s15, 0xe000
	s_nop 0
	global_load_lds_dwordx4 v[196:197], off
	s_waitcnt vmcnt(8)
	s_waitcnt lgkmcnt(0)
	s_barrier
	s_setprio 1
	s_waitcnt lgkmcnt(0)
	v_mfma_f32_16x16x32_bf16 v[156:159], v[108:111], v[164:167], v[156:159]
	v_mfma_f32_16x16x32_bf16 v[156:159], v[120:123], v[168:171], v[156:159]
	v_mfma_f32_16x16x32_bf16 v[128:131], v[108:111], v[172:175], v[128:131]
	v_mfma_f32_16x16x32_bf16 v[128:131], v[120:123], v[176:179], v[128:131]
	v_mfma_f32_16x16x32_bf16 v[116:119], v[108:111], v[180:183], v[116:119]
	v_mfma_f32_16x16x32_bf16 v[116:119], v[120:123], v[184:187], v[116:119]
	v_mfma_f32_16x16x32_bf16 v[104:107], v[108:111], v[188:191], v[104:107]
	v_mfma_f32_16x16x32_bf16 v[104:107], v[120:123], v[192:195], v[104:107]
	v_mfma_f32_16x16x32_bf16 v[152:155], v[132:135], v[164:167], v[152:155]
	v_mfma_f32_16x16x32_bf16 v[152:155], v[136:139], v[168:171], v[152:155]
	v_mfma_f32_16x16x32_bf16 v[124:127], v[132:135], v[172:175], v[124:127]
	v_mfma_f32_16x16x32_bf16 v[124:127], v[136:139], v[176:179], v[124:127]
	v_mfma_f32_16x16x32_bf16 v[112:115], v[132:135], v[180:183], v[112:115]
	v_mfma_f32_16x16x32_bf16 v[112:115], v[136:139], v[184:187], v[112:115]
	v_mfma_f32_16x16x32_bf16 v[100:103], v[132:135], v[188:191], v[100:103]
	v_mfma_f32_16x16x32_bf16 v[100:103], v[136:139], v[192:195], v[100:103]
	s_setprio 0
	s_setprio 1
	v_mfma_f32_16x16x32_bf16 v[92:95], v[140:143], v[164:167], v[92:95]
	v_mfma_f32_16x16x32_bf16 v[92:95], v[144:147], v[168:171], v[92:95]
	v_mfma_f32_16x16x32_bf16 v[84:87], v[140:143], v[172:175], v[84:87]
	v_mfma_f32_16x16x32_bf16 v[84:87], v[144:147], v[176:179], v[84:87]
	v_mfma_f32_16x16x32_bf16 v[76:79], v[140:143], v[180:183], v[76:79]
	v_mfma_f32_16x16x32_bf16 v[76:79], v[144:147], v[184:187], v[76:79]
	v_mfma_f32_16x16x32_bf16 v[68:71], v[140:143], v[188:191], v[68:71]
	v_mfma_f32_16x16x32_bf16 v[68:71], v[144:147], v[192:195], v[68:71]
	v_mfma_f32_16x16x32_bf16 v[88:91], v[148:151], v[164:167], v[88:91]
	v_mfma_f32_16x16x32_bf16 v[88:91], v[160:163], v[168:171], v[88:91]
	v_mfma_f32_16x16x32_bf16 v[80:83], v[148:151], v[172:175], v[80:83]
	v_mfma_f32_16x16x32_bf16 v[80:83], v[160:163], v[176:179], v[80:83]
	v_mfma_f32_16x16x32_bf16 v[72:75], v[148:151], v[180:183], v[72:75]
	v_mfma_f32_16x16x32_bf16 v[72:75], v[160:163], v[184:187], v[72:75]
	v_mfma_f32_16x16x32_bf16 v[64:67], v[148:151], v[188:191], v[64:67]
	v_mfma_f32_16x16x32_bf16 v[64:67], v[160:163], v[192:195], v[64:67]
	s_setprio 0
	s_barrier
	s_nop 1
	s_add_i32 s3, s3, s64
	v_lshl_add_u64 v[196:197], s[34:35], 0, v[212:213]
	s_mov_b32 m0, s3
	ds_read_b128 v[164:167], v223 offset:16384
	ds_read_b128 v[168:171], v223 offset:17408
	ds_read_b128 v[172:175], v223 offset:18432
	ds_read_b128 v[176:179], v223 offset:19456
	ds_read_b128 v[180:183], v223 offset:20480
	ds_read_b128 v[184:187], v223 offset:21504
	ds_read_b128 v[188:191], v223 offset:22528
	ds_read_b128 v[192:195], v223 offset:23552
	global_load_lds_dwordx4 v[196:197], off
	s_add_i32 m0, s3, 0x2000
	s_add_u32 vcc_lo, s34, 0x80000
	v_lshl_add_u64 v[198:199], s[34:35], 0, v[208:209]
	s_addc_u32 vcc_hi, s35, 0
	s_add_i32 s3, s39, s64
	global_load_lds_dwordx4 v[198:199], off
	v_lshl_add_u64 v[200:201], vcc, 0, v[212:213]
	s_mov_b32 m0, s3
	v_lshl_add_u64 v[202:203], s[88:89], 0, v[206:207]
	global_load_lds_dwordx4 v[200:201], off
	v_lshl_add_u64 v[200:201], vcc, 0, v[208:209]
	s_add_i32 m0, s3, 0x2000
	s_nop 0
	global_load_lds_dwordx4 v[200:201], off
	v_lshl_add_u64 v[200:201], s[88:89], 0, v[204:205]
	s_mov_b32 m0, s15
	s_nop 0
	global_load_lds_dwordx4 v[200:201], off
	s_mov_b32 m0, s43
	s_nop 0
	global_load_lds_dwordx4 v[202:203], off
	s_waitcnt vmcnt(8)
	s_waitcnt lgkmcnt(0)
	s_barrier
	s_setprio 1
	s_waitcnt lgkmcnt(0)
	v_mfma_f32_16x16x32_bf16 v[60:63], v[108:111], v[164:167], v[60:63]
	v_mfma_f32_16x16x32_bf16 v[60:63], v[120:123], v[168:171], v[60:63]
	v_mfma_f32_16x16x32_bf16 v[52:55], v[108:111], v[172:175], v[52:55]
	v_mfma_f32_16x16x32_bf16 v[52:55], v[120:123], v[176:179], v[52:55]
	v_mfma_f32_16x16x32_bf16 v[44:47], v[108:111], v[180:183], v[44:47]
	v_mfma_f32_16x16x32_bf16 v[44:47], v[120:123], v[184:187], v[44:47]
	v_mfma_f32_16x16x32_bf16 v[36:39], v[108:111], v[188:191], v[36:39]
	v_mfma_f32_16x16x32_bf16 v[36:39], v[120:123], v[192:195], v[36:39]
	v_mfma_f32_16x16x32_bf16 v[56:59], v[132:135], v[164:167], v[56:59]
	v_mfma_f32_16x16x32_bf16 v[56:59], v[136:139], v[168:171], v[56:59]
	v_mfma_f32_16x16x32_bf16 v[48:51], v[132:135], v[172:175], v[48:51]
	v_mfma_f32_16x16x32_bf16 v[48:51], v[136:139], v[176:179], v[48:51]
	v_mfma_f32_16x16x32_bf16 v[40:43], v[132:135], v[180:183], v[40:43]
	v_mfma_f32_16x16x32_bf16 v[40:43], v[136:139], v[184:187], v[40:43]
	v_mfma_f32_16x16x32_bf16 v[32:35], v[132:135], v[188:191], v[32:35]
	v_mfma_f32_16x16x32_bf16 v[32:35], v[136:139], v[192:195], v[32:35]
	s_setprio 0
	s_setprio 1
	v_mfma_f32_16x16x32_bf16 v[28:31], v[140:143], v[164:167], v[28:31]
	v_mfma_f32_16x16x32_bf16 v[28:31], v[144:147], v[168:171], v[28:31]
	v_mfma_f32_16x16x32_bf16 v[20:23], v[140:143], v[172:175], v[20:23]
	v_mfma_f32_16x16x32_bf16 v[20:23], v[144:147], v[176:179], v[20:23]
	v_mfma_f32_16x16x32_bf16 v[12:15], v[140:143], v[180:183], v[12:15]
	v_mfma_f32_16x16x32_bf16 v[12:15], v[144:147], v[184:187], v[12:15]
	v_mfma_f32_16x16x32_bf16 v[4:7], v[140:143], v[188:191], v[4:7]
	v_mfma_f32_16x16x32_bf16 v[4:7], v[144:147], v[192:195], v[4:7]
	v_mfma_f32_16x16x32_bf16 v[24:27], v[148:151], v[164:167], v[24:27]
	v_mfma_f32_16x16x32_bf16 v[24:27], v[160:163], v[168:171], v[24:27]
	v_mfma_f32_16x16x32_bf16 v[16:19], v[148:151], v[172:175], v[16:19]
	v_mfma_f32_16x16x32_bf16 v[16:19], v[160:163], v[176:179], v[16:19]
	v_mfma_f32_16x16x32_bf16 v[8:11], v[148:151], v[180:183], v[8:11]
	v_mfma_f32_16x16x32_bf16 v[8:11], v[160:163], v[184:187], v[8:11]
	v_mfma_f32_16x16x32_bf16 v[0:3], v[148:151], v[188:191], v[0:3]
	v_mfma_f32_16x16x32_bf16 v[0:3], v[160:163], v[192:195], v[0:3]
	s_setprio 0
	s_barrier
	s_nop 1
	s_add_i32 s3, 0, 0x18000
	s_add_i32 s39, 0, 0x1c000
	v_add_u32_e32 v136, s3, v220
	v_add_u32_e32 v160, s39, v220
	ds_read_b128 v[108:111], v136
	ds_read_b128 v[120:123], v136 offset:1024
	ds_read_b128 v[132:135], v136 offset:2048
	ds_read_b128 v[136:139], v136 offset:3072
	ds_read_b128 v[140:143], v160
	ds_read_b128 v[144:147], v160 offset:1024
	ds_read_b128 v[148:151], v160 offset:2048
	ds_read_b128 v[160:163], v160 offset:3072
	s_add_u32 s88, s88, 0x80000
	s_addc_u32 s89, s89, 0
	s_mov_b32 m0, s69
	v_lshl_add_u64 v[214:215], s[88:89], 0, v[204:205]
	ds_read_b128 v[164:167], v223 offset:32768
	ds_read_b128 v[168:171], v223 offset:33792
	ds_read_b128 v[172:175], v223 offset:34816
	ds_read_b128 v[176:179], v223 offset:35840
	ds_read_b128 v[180:183], v223 offset:36864
	ds_read_b128 v[184:187], v223 offset:37888
	ds_read_b128 v[188:191], v223 offset:38912
	ds_read_b128 v[192:195], v223 offset:39936
	global_load_lds_dwordx4 v[214:215], off
	v_lshl_add_u64 v[214:215], s[88:89], 0, v[206:207]
	s_mov_b32 m0, s70
	s_nop 0
	global_load_lds_dwordx4 v[214:215], off
	s_waitcnt vmcnt(8)
	s_waitcnt lgkmcnt(0)
	s_barrier
	s_setprio 1
	s_waitcnt lgkmcnt(0)
	v_mfma_f32_16x16x32_bf16 v[156:159], v[108:111], v[164:167], v[156:159]
	v_mfma_f32_16x16x32_bf16 v[156:159], v[120:123], v[168:171], v[156:159]
	v_mfma_f32_16x16x32_bf16 v[128:131], v[108:111], v[172:175], v[128:131]
	v_mfma_f32_16x16x32_bf16 v[128:131], v[120:123], v[176:179], v[128:131]
	v_mfma_f32_16x16x32_bf16 v[116:119], v[108:111], v[180:183], v[116:119]
	v_mfma_f32_16x16x32_bf16 v[116:119], v[120:123], v[184:187], v[116:119]
	v_mfma_f32_16x16x32_bf16 v[104:107], v[108:111], v[188:191], v[104:107]
	v_mfma_f32_16x16x32_bf16 v[104:107], v[120:123], v[192:195], v[104:107]
	v_mfma_f32_16x16x32_bf16 v[152:155], v[132:135], v[164:167], v[152:155]
	v_mfma_f32_16x16x32_bf16 v[152:155], v[136:139], v[168:171], v[152:155]
	v_mfma_f32_16x16x32_bf16 v[124:127], v[132:135], v[172:175], v[124:127]
	v_mfma_f32_16x16x32_bf16 v[124:127], v[136:139], v[176:179], v[124:127]
	v_mfma_f32_16x16x32_bf16 v[112:115], v[132:135], v[180:183], v[112:115]
	v_mfma_f32_16x16x32_bf16 v[112:115], v[136:139], v[184:187], v[112:115]
	v_mfma_f32_16x16x32_bf16 v[100:103], v[132:135], v[188:191], v[100:103]
	v_mfma_f32_16x16x32_bf16 v[100:103], v[136:139], v[192:195], v[100:103]
	s_setprio 0
	s_setprio 1
	v_mfma_f32_16x16x32_bf16 v[92:95], v[140:143], v[164:167], v[92:95]
	v_mfma_f32_16x16x32_bf16 v[92:95], v[144:147], v[168:171], v[92:95]
	v_mfma_f32_16x16x32_bf16 v[84:87], v[140:143], v[172:175], v[84:87]
	v_mfma_f32_16x16x32_bf16 v[84:87], v[144:147], v[176:179], v[84:87]
	v_mfma_f32_16x16x32_bf16 v[76:79], v[140:143], v[180:183], v[76:79]
	v_mfma_f32_16x16x32_bf16 v[76:79], v[144:147], v[184:187], v[76:79]
	v_mfma_f32_16x16x32_bf16 v[68:71], v[140:143], v[188:191], v[68:71]
	v_mfma_f32_16x16x32_bf16 v[68:71], v[144:147], v[192:195], v[68:71]
	v_mfma_f32_16x16x32_bf16 v[88:91], v[148:151], v[164:167], v[88:91]
	v_mfma_f32_16x16x32_bf16 v[88:91], v[160:163], v[168:171], v[88:91]
	v_mfma_f32_16x16x32_bf16 v[80:83], v[148:151], v[172:175], v[80:83]
	v_mfma_f32_16x16x32_bf16 v[80:83], v[160:163], v[176:179], v[80:83]
	v_mfma_f32_16x16x32_bf16 v[72:75], v[148:151], v[180:183], v[72:75]
	v_mfma_f32_16x16x32_bf16 v[72:75], v[160:163], v[184:187], v[72:75]
	v_mfma_f32_16x16x32_bf16 v[64:67], v[148:151], v[188:191], v[64:67]
	v_mfma_f32_16x16x32_bf16 v[64:67], v[160:163], v[192:195], v[64:67]
	s_setprio 0
	s_barrier
	s_nop 1
	s_add_i32 s3, s3, s64
	v_lshl_add_u64 v[196:197], v[196:197], 0, s[72:73]
	s_mov_b32 m0, s3
	ds_read_b128 v[164:167], v223 offset:49152
	ds_read_b128 v[168:171], v223 offset:50176
	ds_read_b128 v[172:175], v223 offset:51200
	ds_read_b128 v[176:179], v223 offset:52224
	ds_read_b128 v[180:183], v223 offset:53248
	ds_read_b128 v[184:187], v223 offset:54272
	ds_read_b128 v[188:191], v223 offset:55296
	ds_read_b128 v[192:195], v223 offset:56320
	global_load_lds_dwordx4 v[196:197], off
	s_add_i32 m0, s3, 0x2000
	s_add_u32 s34, s34, 0x80080
	v_lshl_add_u64 v[196:197], v[198:199], 0, s[72:73]
	s_addc_u32 s35, s35, 0
	s_add_i32 s3, s39, s64
	global_load_lds_dwordx4 v[196:197], off
	v_lshl_add_u64 v[196:197], s[34:35], 0, v[212:213]
	s_mov_b32 m0, s3
	s_nop 0
	global_load_lds_dwordx4 v[196:197], off
	v_lshl_add_u64 v[196:197], s[34:35], 0, v[208:209]
	s_add_i32 m0, s3, 0x2000
	s_nop 0
	global_load_lds_dwordx4 v[196:197], off
	v_lshl_add_u64 v[196:197], v[200:201], 0, s[72:73]
	s_mov_b32 m0, s83
	s_nop 0
	global_load_lds_dwordx4 v[196:197], off
	v_lshl_add_u64 v[196:197], v[202:203], 0, s[72:73]
	s_mov_b32 m0, s84
	s_nop 0
	global_load_lds_dwordx4 v[196:197], off
	s_waitcnt vmcnt(8)
	s_waitcnt lgkmcnt(0)
	s_barrier
	s_setprio 1
	s_waitcnt lgkmcnt(0)
	v_mfma_f32_16x16x32_bf16 v[60:63], v[108:111], v[164:167], v[60:63]
	v_mfma_f32_16x16x32_bf16 v[60:63], v[120:123], v[168:171], v[60:63]
	v_mfma_f32_16x16x32_bf16 v[52:55], v[108:111], v[172:175], v[52:55]
	v_mfma_f32_16x16x32_bf16 v[52:55], v[120:123], v[176:179], v[52:55]
	v_mfma_f32_16x16x32_bf16 v[44:47], v[108:111], v[180:183], v[44:47]
	v_mfma_f32_16x16x32_bf16 v[44:47], v[120:123], v[184:187], v[44:47]
	v_mfma_f32_16x16x32_bf16 v[36:39], v[108:111], v[188:191], v[36:39]
	v_mfma_f32_16x16x32_bf16 v[36:39], v[120:123], v[192:195], v[36:39]
	v_mfma_f32_16x16x32_bf16 v[56:59], v[132:135], v[164:167], v[56:59]
	v_mfma_f32_16x16x32_bf16 v[56:59], v[136:139], v[168:171], v[56:59]
	v_mfma_f32_16x16x32_bf16 v[48:51], v[132:135], v[172:175], v[48:51]
	v_mfma_f32_16x16x32_bf16 v[48:51], v[136:139], v[176:179], v[48:51]
	v_mfma_f32_16x16x32_bf16 v[40:43], v[132:135], v[180:183], v[40:43]
	v_mfma_f32_16x16x32_bf16 v[40:43], v[136:139], v[184:187], v[40:43]
	v_mfma_f32_16x16x32_bf16 v[32:35], v[132:135], v[188:191], v[32:35]
	v_mfma_f32_16x16x32_bf16 v[32:35], v[136:139], v[192:195], v[32:35]
	s_setprio 0
	s_setprio 1
	v_mfma_f32_16x16x32_bf16 v[28:31], v[140:143], v[164:167], v[28:31]
	v_mfma_f32_16x16x32_bf16 v[28:31], v[144:147], v[168:171], v[28:31]
	v_mfma_f32_16x16x32_bf16 v[20:23], v[140:143], v[172:175], v[20:23]
	v_mfma_f32_16x16x32_bf16 v[20:23], v[144:147], v[176:179], v[20:23]
	v_mfma_f32_16x16x32_bf16 v[12:15], v[140:143], v[180:183], v[12:15]
	v_mfma_f32_16x16x32_bf16 v[12:15], v[144:147], v[184:187], v[12:15]
	v_mfma_f32_16x16x32_bf16 v[4:7], v[140:143], v[188:191], v[4:7]
	v_mfma_f32_16x16x32_bf16 v[4:7], v[144:147], v[192:195], v[4:7]
	v_mfma_f32_16x16x32_bf16 v[24:27], v[148:151], v[164:167], v[24:27]
	v_mfma_f32_16x16x32_bf16 v[24:27], v[160:163], v[168:171], v[24:27]
	v_mfma_f32_16x16x32_bf16 v[16:19], v[148:151], v[172:175], v[16:19]
	v_mfma_f32_16x16x32_bf16 v[16:19], v[160:163], v[176:179], v[16:19]
	v_mfma_f32_16x16x32_bf16 v[8:11], v[148:151], v[180:183], v[8:11]
	v_mfma_f32_16x16x32_bf16 v[8:11], v[160:163], v[184:187], v[8:11]
	v_mfma_f32_16x16x32_bf16 v[0:3], v[148:151], v[188:191], v[0:3]
	v_mfma_f32_16x16x32_bf16 v[0:3], v[160:163], v[192:195], v[0:3]
	s_setprio 0
	s_barrier
	s_nop 1
	s_add_u32 s30, s30, 0x100
	s_addc_u32 s31, s31, 0
	s_cmp_ge_i32 s2, s19
	s_mov_b32 s34, s2
	s_cbranch_scc1 .LBB0_1246

.LBB0_1413:
	s_lshl_b32 s2, s9, 7
	s_add_u32 s3, s74, s2
	s_addc_u32 s24, s75, 0
	s_add_u32 s20, s3, 0x100
	s_addc_u32 s21, s24, 0
	s_add_u32 s2, s14, s2
	s_addc_u32 s22, s15, 0
	s_add_u32 s2, s2, 0x100
	s_addc_u32 s25, s22, 0
	s_cmp_eq_u32 s9, 30
	s_cselect_b32 s23, s5, s21
	s_cselect_b32 s22, s59, s20
	s_cselect_b32 s21, s57, s25
	s_cselect_b32 s20, s30, s2
	s_add_i32 s25, 0, 0x10000
	s_add_i32 s26, 0, 0x14000
	v_add_u32_e32 v28, s25, v226
	v_add_u32_e32 v44, s26, v226
	ds_read_b128 v[16:19], v28
	ds_read_b128 v[20:23], v28 offset:1024
	ds_read_b128 v[24:27], v28 offset:2048
	ds_read_b128 v[28:31], v28 offset:3072
	ds_read_b128 v[32:35], v44
	ds_read_b128 v[36:39], v44 offset:1024
	ds_read_b128 v[40:43], v44 offset:2048
	ds_read_b128 v[44:47], v44 offset:3072
	s_add_u32 s2, s3, 0x80080
	s_addc_u32 s3, s24, 0
	v_lshl_add_u64 v[152:153], s[2:3], 0, v[218:219]
	s_add_i32 m0, s11, 0xc000
	ds_read_b128 v[48:51], v227
	ds_read_b128 v[52:55], v227 offset:1024
	ds_read_b128 v[56:59], v227 offset:2048
	ds_read_b128 v[60:63], v227 offset:3072
	ds_read_b128 v[136:139], v227 offset:4096
	ds_read_b128 v[140:143], v227 offset:5120
	ds_read_b128 v[144:147], v227 offset:6144
	ds_read_b128 v[148:151], v227 offset:7168
	global_load_lds_dwordx4 v[152:153], off
	v_lshl_add_u64 v[152:153], s[2:3], 0, v[222:223]
	s_add_i32 m0, s11, 0xe000
	s_nop 0
	global_load_lds_dwordx4 v[152:153], off
	s_waitcnt vmcnt(8)
	s_waitcnt lgkmcnt(0)
	s_barrier
	s_setprio 1
	s_waitcnt lgkmcnt(0)
	v_mfma_f32_16x16x32_bf16 v[152:155], v[16:19], v[48:51], v[164:167]
	v_mfma_f32_16x16x32_bf16 v[152:155], v[20:23], v[52:55], v[152:155]
	v_mfma_f32_16x16x32_bf16 v[160:163], v[16:19], v[56:59], v[160:163]
	v_mfma_f32_16x16x32_bf16 v[160:163], v[20:23], v[60:63], v[160:163]
	v_mfma_f32_16x16x32_bf16 v[108:111], v[16:19], v[136:139], v[108:111]
	v_mfma_f32_16x16x32_bf16 v[108:111], v[20:23], v[140:143], v[108:111]
	v_mfma_f32_16x16x32_bf16 v[164:167], v[16:19], v[144:147], v[168:171]
	v_mfma_f32_16x16x32_bf16 v[168:171], v[20:23], v[148:151], v[164:167]
	v_mfma_f32_16x16x32_bf16 v[64:67], v[24:27], v[48:51], v[64:67]
	v_mfma_f32_16x16x32_bf16 v[64:67], v[28:31], v[52:55], v[64:67]
	v_mfma_f32_16x16x32_bf16 v[156:159], v[24:27], v[56:59], v[156:159]
	v_mfma_f32_16x16x32_bf16 v[156:159], v[28:31], v[60:63], v[156:159]
	v_mfma_f32_16x16x32_bf16 v[104:107], v[24:27], v[136:139], v[104:107]
	v_mfma_f32_16x16x32_bf16 v[104:107], v[28:31], v[140:143], v[104:107]
	v_mfma_f32_16x16x32_bf16 v[68:71], v[24:27], v[144:147], v[68:71]
	v_mfma_f32_16x16x32_bf16 v[68:71], v[28:31], v[148:151], v[68:71]
	s_setprio 0
	s_setprio 1
	v_mfma_f32_16x16x32_bf16 v[88:91], v[32:35], v[48:51], v[88:91]
	v_mfma_f32_16x16x32_bf16 v[88:91], v[36:39], v[52:55], v[88:91]
	v_mfma_f32_16x16x32_bf16 v[48:51], v[40:43], v[48:51], v[72:75]
	v_mfma_f32_16x16x32_bf16 v[48:51], v[44:47], v[52:55], v[48:51]
	v_mfma_f32_16x16x32_bf16 v[72:75], v[40:43], v[136:139], v[96:99]
	v_mfma_f32_16x16x32_bf16 v[96:99], v[44:47], v[140:143], v[72:75]
	v_mfma_f32_16x16x32_bf16 v[72:75], v[32:35], v[144:147], v[92:95]
	v_mfma_f32_16x16x32_bf16 v[92:95], v[36:39], v[148:151], v[72:75]
	v_mfma_f32_16x16x32_bf16 v[52:55], v[32:35], v[56:59], v[132:135]
	v_mfma_f32_16x16x32_bf16 v[52:55], v[36:39], v[60:63], v[52:55]
	v_mfma_f32_16x16x32_bf16 v[56:59], v[40:43], v[56:59], v[128:131]
	v_mfma_f32_16x16x32_bf16 v[56:59], v[44:47], v[60:63], v[56:59]
	v_mfma_f32_16x16x32_bf16 v[72:75], v[40:43], v[144:147], v[76:79]
	v_mfma_f32_16x16x32_bf16 v[76:79], v[44:47], v[148:151], v[72:75]
	v_mfma_f32_16x16x32_bf16 v[60:63], v[32:35], v[136:139], v[100:103]
	v_mfma_f32_16x16x32_bf16 v[60:63], v[36:39], v[140:143], v[60:63]
	s_setprio 0
	s_barrier
	s_nop 1
	s_add_i32 s2, s25, s79
	v_lshl_add_u64 v[214:215], s[20:21], 0, v[220:221]
	s_mov_b32 m0, s2
	ds_read_b128 v[72:75], v227 offset:16384
	ds_read_b128 v[100:103], v227 offset:17408
	ds_read_b128 v[128:131], v227 offset:18432
	ds_read_b128 v[132:135], v227 offset:19456
	ds_read_b128 v[136:139], v227 offset:20480
	ds_read_b128 v[140:143], v227 offset:21504
	ds_read_b128 v[144:147], v227 offset:22528
	ds_read_b128 v[148:151], v227 offset:23552
	global_load_lds_dwordx4 v[214:215], off
	s_add_i32 m0, s2, 0x2000
	s_add_u32 s2, s20, 0x80000
	v_lshl_add_u64 v[216:217], s[20:21], 0, v[224:225]
	s_addc_u32 s3, s21, 0
	s_add_i32 s24, s26, s79
	global_load_lds_dwordx4 v[216:217], off
	v_lshl_add_u64 v[164:165], s[2:3], 0, v[220:221]
	s_mov_b32 m0, s24
	v_lshl_add_u64 v[230:231], s[22:23], 0, v[218:219]
	global_load_lds_dwordx4 v[164:165], off
	v_lshl_add_u64 v[164:165], s[2:3], 0, v[224:225]
	s_add_i32 m0, s24, 0x2000
	v_lshl_add_u64 v[232:233], s[22:23], 0, v[222:223]
	global_load_lds_dwordx4 v[164:165], off
	s_mov_b32 m0, s11
	s_nop 0
	global_load_lds_dwordx4 v[230:231], off
	s_mov_b32 m0, s88
	s_nop 0
	global_load_lds_dwordx4 v[232:233], off
	s_waitcnt vmcnt(8)
	s_waitcnt lgkmcnt(0)
	s_barrier
	s_setprio 1
	s_waitcnt lgkmcnt(0)
	v_mfma_f32_16x16x32_bf16 v[80:83], v[16:19], v[72:75], v[80:83]
	v_mfma_f32_16x16x32_bf16 v[80:83], v[20:23], v[100:103], v[80:83]
	v_mfma_f32_16x16x32_bf16 v[12:15], v[16:19], v[128:131], v[12:15]
	v_mfma_f32_16x16x32_bf16 v[12:15], v[20:23], v[132:135], v[12:15]
	v_mfma_f32_16x16x32_bf16 v[124:127], v[16:19], v[136:139], v[124:127]
	v_mfma_f32_16x16x32_bf16 v[124:127], v[20:23], v[140:143], v[124:127]
	v_mfma_f32_16x16x32_bf16 v[8:11], v[24:27], v[128:131], v[8:11]
	v_mfma_f32_16x16x32_bf16 v[8:11], v[28:31], v[132:135], v[8:11]
	v_mfma_f32_16x16x32_bf16 v[120:123], v[24:27], v[136:139], v[120:123]
	v_mfma_f32_16x16x32_bf16 v[120:123], v[28:31], v[140:143], v[120:123]
	v_mfma_f32_16x16x32_bf16 v[16:19], v[16:19], v[144:147], v[84:87]
	v_mfma_f32_16x16x32_bf16 v[16:19], v[20:23], v[148:151], v[16:19]
	v_mfma_f32_16x16x32_bf16 v[164:167], v[24:27], v[72:75], v[196:199]
	v_mfma_f32_16x16x32_bf16 v[176:179], v[28:31], v[100:103], v[164:167]
	v_mfma_f32_16x16x32_bf16 v[20:23], v[24:27], v[144:147], v[200:203]
	v_mfma_f32_16x16x32_bf16 v[20:23], v[28:31], v[148:151], v[20:23]
	s_setprio 0
	s_setprio 1
	v_mfma_f32_16x16x32_bf16 v[24:27], v[32:35], v[72:75], v[172:175]
	v_mfma_f32_16x16x32_bf16 v[24:27], v[36:39], v[100:103], v[24:27]
	v_mfma_f32_16x16x32_bf16 v[4:7], v[32:35], v[128:131], v[4:7]
	v_mfma_f32_16x16x32_bf16 v[4:7], v[36:39], v[132:135], v[4:7]
	v_mfma_f32_16x16x32_bf16 v[28:31], v[40:43], v[72:75], v[188:191]
	v_mfma_f32_16x16x32_bf16 v[28:31], v[44:47], v[100:103], v[28:31]
	v_mfma_f32_16x16x32_bf16 v[72:75], v[32:35], v[136:139], v[116:119]
	v_mfma_f32_16x16x32_bf16 v[116:119], v[36:39], v[140:143], v[72:75]
	v_mfma_f32_16x16x32_bf16 v[0:3], v[40:43], v[128:131], v[0:3]
	v_mfma_f32_16x16x32_bf16 v[0:3], v[44:47], v[132:135], v[0:3]
	v_mfma_f32_16x16x32_bf16 v[72:75], v[40:43], v[136:139], v[112:115]
	v_mfma_f32_16x16x32_bf16 v[112:115], v[44:47], v[140:143], v[72:75]
	v_mfma_f32_16x16x32_bf16 v[32:35], v[32:35], v[144:147], v[180:183]
	v_mfma_f32_16x16x32_bf16 v[32:35], v[36:39], v[148:151], v[32:35]
	v_mfma_f32_16x16x32_bf16 v[36:39], v[40:43], v[144:147], v[192:195]
	v_mfma_f32_16x16x32_bf16 v[36:39], v[44:47], v[148:151], v[36:39]
	s_setprio 0
	s_barrier
	s_nop 1
	s_add_i32 s24, 0, 0x18000
	v_add_u32_e32 v72, s24, v226
	s_add_i32 s25, 0, 0x1c000
	ds_read_b128 v[40:43], v72
	ds_read_b128 v[44:47], v72 offset:1024
	ds_read_b128 v[136:139], v72 offset:2048
	ds_read_b128 v[140:143], v72 offset:3072
	v_add_u32_e32 v72, s25, v226
	ds_read_b128 v[144:147], v72
	ds_read_b128 v[148:151], v72 offset:1024
	ds_read_b128 v[184:187], v72 offset:2048
	ds_read_b128 v[192:195], v72 offset:3072
	s_add_u32 s2, s22, 0x80000
	s_addc_u32 s3, s23, 0
	s_mov_b32 m0, s89
	v_lshl_add_u64 v[132:133], s[2:3], 0, v[218:219]
	ds_read_b128 v[72:75], v227 offset:32768
	ds_read_b128 v[84:87], v227 offset:33792
	ds_read_b128 v[100:103], v227 offset:34816
	ds_read_b128 v[128:131], v227 offset:35840
	ds_read_b128 v[172:175], v227 offset:36864
	ds_read_b128 v[180:183], v227 offset:37888
	ds_read_b128 v[188:191], v227 offset:38912
	ds_read_b128 v[196:199], v227 offset:39936
	global_load_lds_dwordx4 v[132:133], off
	v_lshl_add_u64 v[132:133], s[2:3], 0, v[222:223]
	s_mov_b32 m0, s76
	s_nop 0
	global_load_lds_dwordx4 v[132:133], off
	s_waitcnt vmcnt(8)
	s_waitcnt lgkmcnt(0)
	s_barrier
	s_setprio 1
	s_waitcnt lgkmcnt(0)
	v_mfma_f32_16x16x32_bf16 v[132:135], v[40:43], v[72:75], v[152:155]
	v_mfma_f32_16x16x32_bf16 v[164:167], v[44:47], v[84:87], v[132:135]
	v_mfma_f32_16x16x32_bf16 v[108:111], v[40:43], v[172:175], v[108:111]
	v_mfma_f32_16x16x32_bf16 v[108:111], v[44:47], v[180:183], v[108:111]
	v_mfma_f32_16x16x32_bf16 v[132:135], v[40:43], v[100:103], v[160:163]
	v_mfma_f32_16x16x32_bf16 v[160:163], v[44:47], v[128:131], v[132:135]
	v_mfma_f32_16x16x32_bf16 v[132:135], v[136:139], v[100:103], v[156:159]
	v_mfma_f32_16x16x32_bf16 v[156:159], v[140:143], v[128:131], v[132:135]
	v_mfma_f32_16x16x32_bf16 v[132:135], v[40:43], v[188:191], v[168:171]
	v_mfma_f32_16x16x32_bf16 v[168:171], v[44:47], v[196:199], v[132:135]
	v_mfma_f32_16x16x32_bf16 v[64:67], v[136:139], v[72:75], v[64:67]
	v_mfma_f32_16x16x32_bf16 v[64:67], v[140:143], v[84:87], v[64:67]
	v_mfma_f32_16x16x32_bf16 v[104:107], v[136:139], v[172:175], v[104:107]
	v_mfma_f32_16x16x32_bf16 v[104:107], v[140:143], v[180:183], v[104:107]
	v_mfma_f32_16x16x32_bf16 v[68:71], v[136:139], v[188:191], v[68:71]
	v_mfma_f32_16x16x32_bf16 v[68:71], v[140:143], v[196:199], v[68:71]
	s_setprio 0
	s_setprio 1
	v_mfma_f32_16x16x32_bf16 v[48:51], v[184:187], v[72:75], v[48:51]
	v_mfma_f32_16x16x32_bf16 v[88:91], v[144:147], v[72:75], v[88:91]
	v_mfma_f32_16x16x32_bf16 v[88:91], v[148:151], v[84:87], v[88:91]
	v_mfma_f32_16x16x32_bf16 v[72:75], v[192:195], v[84:87], v[48:51]
	v_mfma_f32_16x16x32_bf16 v[48:51], v[144:147], v[100:103], v[52:55]
	v_mfma_f32_16x16x32_bf16 v[132:135], v[148:151], v[128:131], v[48:51]
	v_mfma_f32_16x16x32_bf16 v[48:51], v[184:187], v[100:103], v[56:59]
	v_mfma_f32_16x16x32_bf16 v[128:131], v[192:195], v[128:131], v[48:51]
	v_mfma_f32_16x16x32_bf16 v[48:51], v[144:147], v[172:175], v[60:63]
	v_mfma_f32_16x16x32_bf16 v[100:103], v[148:151], v[180:183], v[48:51]
	v_mfma_f32_16x16x32_bf16 v[48:51], v[184:187], v[172:175], v[96:99]
	v_mfma_f32_16x16x32_bf16 v[96:99], v[192:195], v[180:183], v[48:51]
	v_mfma_f32_16x16x32_bf16 v[48:51], v[144:147], v[188:191], v[92:95]
	v_mfma_f32_16x16x32_bf16 v[92:95], v[148:151], v[196:199], v[48:51]
	v_mfma_f32_16x16x32_bf16 v[48:51], v[184:187], v[188:191], v[76:79]
	v_mfma_f32_16x16x32_bf16 v[76:79], v[192:195], v[196:199], v[48:51]
	s_setprio 0
	s_barrier
	s_nop 1
	s_add_i32 s2, s24, s79
	v_lshl_add_u64 v[84:85], v[214:215], 0, s[72:73]
	s_mov_b32 m0, s2
	s_nop 0
	ds_read_b128 v[48:51], v227 offset:49152
	ds_read_b128 v[52:55], v227 offset:50176
	ds_read_b128 v[56:59], v227 offset:51200
	ds_read_b128 v[60:63], v227 offset:52224
	ds_read_b128 v[152:155], v227 offset:53248
	ds_read_b128 v[180:183], v227 offset:54272
	ds_read_b128 v[204:207], v227 offset:55296
	ds_read_b128 v[208:211], v227 offset:56320
	global_load_lds_dwordx4 v[84:85], off
	s_add_i32 m0, s2, 0x2000
	s_add_u32 s2, s20, 0x80080
	v_lshl_add_u64 v[84:85], v[216:217], 0, s[72:73]
	s_addc_u32 s3, s21, 0
	s_add_i32 s20, s25, s79
	global_load_lds_dwordx4 v[84:85], off
	v_lshl_add_u64 v[84:85], s[2:3], 0, v[220:221]
	s_mov_b32 m0, s20
	s_nop 0
	global_load_lds_dwordx4 v[84:85], off
	v_lshl_add_u64 v[84:85], s[2:3], 0, v[224:225]
	s_add_i32 m0, s20, 0x2000
	s_nop 0
	global_load_lds_dwordx4 v[84:85], off
	v_lshl_add_u64 v[84:85], v[230:231], 0, s[72:73]
	s_mov_b32 m0, s67
	s_nop 0
	global_load_lds_dwordx4 v[84:85], off
	v_lshl_add_u64 v[84:85], v[232:233], 0, s[72:73]
	s_mov_b32 m0, s84
	s_nop 0
	global_load_lds_dwordx4 v[84:85], off
	s_waitcnt vmcnt(8)
	s_waitcnt lgkmcnt(0)
	s_barrier
	s_setprio 1
	s_waitcnt lgkmcnt(0)
	v_mfma_f32_16x16x32_bf16 v[84:87], v[136:139], v[48:51], v[176:179]
	v_mfma_f32_16x16x32_bf16 v[196:199], v[140:143], v[52:55], v[84:87]
	v_mfma_f32_16x16x32_bf16 v[12:15], v[40:43], v[56:59], v[12:15]
	v_mfma_f32_16x16x32_bf16 v[12:15], v[44:47], v[60:63], v[12:15]
	v_mfma_f32_16x16x32_bf16 v[84:87], v[40:43], v[152:155], v[124:127]
	v_mfma_f32_16x16x32_bf16 v[124:127], v[44:47], v[180:183], v[84:87]
	v_mfma_f32_16x16x32_bf16 v[84:87], v[136:139], v[152:155], v[120:123]
	v_mfma_f32_16x16x32_bf16 v[120:123], v[140:143], v[180:183], v[84:87]
	v_mfma_f32_16x16x32_bf16 v[16:19], v[40:43], v[204:207], v[16:19]
	v_mfma_f32_16x16x32_bf16 v[84:87], v[44:47], v[208:211], v[16:19]
	v_mfma_f32_16x16x32_bf16 v[80:83], v[40:43], v[48:51], v[80:83]
	v_mfma_f32_16x16x32_bf16 v[80:83], v[44:47], v[52:55], v[80:83]
	v_mfma_f32_16x16x32_bf16 v[8:11], v[136:139], v[56:59], v[8:11]
	v_mfma_f32_16x16x32_bf16 v[8:11], v[140:143], v[60:63], v[8:11]
	v_mfma_f32_16x16x32_bf16 v[16:19], v[136:139], v[204:207], v[20:23]
	v_mfma_f32_16x16x32_bf16 v[200:203], v[140:143], v[208:211], v[16:19]
	s_setprio 0
	s_setprio 1
	v_mfma_f32_16x16x32_bf16 v[4:7], v[144:147], v[56:59], v[4:7]
	v_mfma_f32_16x16x32_bf16 v[4:7], v[148:151], v[60:63], v[4:7]
	v_mfma_f32_16x16x32_bf16 v[16:19], v[144:147], v[48:51], v[24:27]
	v_mfma_f32_16x16x32_bf16 v[172:175], v[148:151], v[52:55], v[16:19]
	v_mfma_f32_16x16x32_bf16 v[16:19], v[184:187], v[48:51], v[28:31]
	v_mfma_f32_16x16x32_bf16 v[188:191], v[192:195], v[52:55], v[16:19]
	v_mfma_f32_16x16x32_bf16 v[16:19], v[144:147], v[152:155], v[116:119]
	v_mfma_f32_16x16x32_bf16 v[116:119], v[148:151], v[180:183], v[16:19]
	v_mfma_f32_16x16x32_bf16 v[16:19], v[184:187], v[152:155], v[112:115]
	v_mfma_f32_16x16x32_bf16 v[112:115], v[192:195], v[180:183], v[16:19]
	v_mfma_f32_16x16x32_bf16 v[16:19], v[144:147], v[204:207], v[32:35]
	v_mfma_f32_16x16x32_bf16 v[180:183], v[148:151], v[208:211], v[16:19]
	v_mfma_f32_16x16x32_bf16 v[0:3], v[184:187], v[56:59], v[0:3]
	v_mfma_f32_16x16x32_bf16 v[0:3], v[192:195], v[60:63], v[0:3]
	v_mfma_f32_16x16x32_bf16 v[16:19], v[184:187], v[204:207], v[36:39]
	v_mfma_f32_16x16x32_bf16 v[192:195], v[192:195], v[208:211], v[16:19]
	s_setprio 0
	s_barrier
	s_nop 1
	s_add_i32 s2, s9, 2
	s_cmp_gt_u32 s9, 29
	s_mov_b32 s9, s2
	s_cbranch_scc1 .LBB0_1436

.LBB0_1660:
	s_add_i32 s2, s28, 2
	s_add_u32 s3, s12, s26
	s_addc_u32 s29, s13, s27
	s_add_u32 s3, s3, 0x100
	s_addc_u32 s29, s29, 0
	s_add_u32 s55, s15, s26
	s_addc_u32 s63, s41, s27
	s_cmp_eq_u32 s40, s28
	s_cselect_b32 s31, s75, s29
	s_cselect_b32 s30, s74, s3
	s_cselect_b32 s29, s9, s63
	s_cselect_b32 s28, s8, s55
	s_add_i32 s3, 0, 0x10000
	s_add_i32 s55, 0, 0x14000
	v_add_u32_e32 v112, s3, v238
	v_add_u32_e32 v160, s55, v238
	ds_read_b128 v[76:79], v112
	ds_read_b128 v[88:91], v112 offset:1024
	ds_read_b128 v[100:103], v112 offset:2048
	ds_read_b128 v[112:115], v112 offset:3072
	ds_read_b128 v[124:127], v160
	ds_read_b128 v[136:139], v160 offset:1024
	ds_read_b128 v[148:151], v160 offset:2048
	ds_read_b128 v[160:163], v160 offset:3072
	v_lshl_add_u64 v[196:197], v[68:69], 0, s[26:27]
	s_add_i32 m0, s11, 0xc000
	ds_read_b128 v[164:167], v241
	ds_read_b128 v[168:171], v241 offset:1024
	ds_read_b128 v[172:175], v241 offset:2048
	ds_read_b128 v[176:179], v241 offset:3072
	ds_read_b128 v[180:183], v241 offset:4096
	ds_read_b128 v[184:187], v241 offset:5120
	ds_read_b128 v[188:191], v241 offset:6144
	ds_read_b128 v[192:195], v241 offset:7168
	global_load_lds_dwordx4 v[196:197], off
	v_lshl_add_u64 v[196:197], v[70:71], 0, s[26:27]
	s_add_i32 m0, s11, 0xe000
	s_nop 0
	global_load_lds_dwordx4 v[196:197], off
	s_waitcnt vmcnt(8)
	s_waitcnt lgkmcnt(0)
	s_barrier
	s_setprio 1
	s_waitcnt lgkmcnt(0)
	v_mfma_f32_16x16x32_bf16 v[156:159], v[76:79], v[164:167], v[156:159]
	v_mfma_f32_16x16x32_bf16 v[156:159], v[88:91], v[168:171], v[156:159]
	v_mfma_f32_16x16x32_bf16 v[144:147], v[76:79], v[172:175], v[144:147]
	v_mfma_f32_16x16x32_bf16 v[144:147], v[88:91], v[176:179], v[144:147]
	v_mfma_f32_16x16x32_bf16 v[132:135], v[76:79], v[180:183], v[132:135]
	v_mfma_f32_16x16x32_bf16 v[132:135], v[88:91], v[184:187], v[132:135]
	v_mfma_f32_16x16x32_bf16 v[120:123], v[76:79], v[188:191], v[120:123]
	v_mfma_f32_16x16x32_bf16 v[120:123], v[88:91], v[192:195], v[120:123]
	v_mfma_f32_16x16x32_bf16 v[152:155], v[100:103], v[164:167], v[152:155]
	v_mfma_f32_16x16x32_bf16 v[152:155], v[112:115], v[168:171], v[152:155]
	v_mfma_f32_16x16x32_bf16 v[140:143], v[100:103], v[172:175], v[140:143]
	v_mfma_f32_16x16x32_bf16 v[140:143], v[112:115], v[176:179], v[140:143]
	v_mfma_f32_16x16x32_bf16 v[128:131], v[100:103], v[180:183], v[128:131]
	v_mfma_f32_16x16x32_bf16 v[128:131], v[112:115], v[184:187], v[128:131]
	v_mfma_f32_16x16x32_bf16 v[116:119], v[100:103], v[188:191], v[116:119]
	v_mfma_f32_16x16x32_bf16 v[116:119], v[112:115], v[192:195], v[116:119]
	s_setprio 0
	s_setprio 1
	v_mfma_f32_16x16x32_bf16 v[108:111], v[124:127], v[164:167], v[108:111]
	v_mfma_f32_16x16x32_bf16 v[108:111], v[136:139], v[168:171], v[108:111]
	v_mfma_f32_16x16x32_bf16 v[96:99], v[124:127], v[172:175], v[96:99]
	v_mfma_f32_16x16x32_bf16 v[96:99], v[136:139], v[176:179], v[96:99]
	v_mfma_f32_16x16x32_bf16 v[84:87], v[124:127], v[180:183], v[84:87]
	v_mfma_f32_16x16x32_bf16 v[84:87], v[136:139], v[184:187], v[84:87]
	v_mfma_f32_16x16x32_bf16 v[72:75], v[124:127], v[188:191], v[72:75]
	v_mfma_f32_16x16x32_bf16 v[72:75], v[136:139], v[192:195], v[72:75]
	v_mfma_f32_16x16x32_bf16 v[104:107], v[148:151], v[164:167], v[104:107]
	v_mfma_f32_16x16x32_bf16 v[104:107], v[160:163], v[168:171], v[104:107]
	v_mfma_f32_16x16x32_bf16 v[92:95], v[148:151], v[172:175], v[92:95]
	v_mfma_f32_16x16x32_bf16 v[92:95], v[160:163], v[176:179], v[92:95]
	v_mfma_f32_16x16x32_bf16 v[80:83], v[148:151], v[180:183], v[80:83]
	v_mfma_f32_16x16x32_bf16 v[80:83], v[160:163], v[184:187], v[80:83]
	v_mfma_f32_16x16x32_bf16 v[64:67], v[148:151], v[188:191], v[64:67]
	v_mfma_f32_16x16x32_bf16 v[64:67], v[160:163], v[192:195], v[64:67]
	s_setprio 0
	s_barrier
	s_nop 1
	s_add_i32 s3, s3, s33
	v_lshl_add_u64 v[196:197], s[28:29], 0, v[210:211]
	s_mov_b32 m0, s3
	ds_read_b128 v[164:167], v241 offset:16384
	ds_read_b128 v[168:171], v241 offset:17408
	ds_read_b128 v[172:175], v241 offset:18432
	ds_read_b128 v[176:179], v241 offset:19456
	ds_read_b128 v[180:183], v241 offset:20480
	ds_read_b128 v[184:187], v241 offset:21504
	ds_read_b128 v[188:191], v241 offset:22528
	ds_read_b128 v[192:195], v241 offset:23552
	global_load_lds_dwordx4 v[196:197], off
	s_add_i32 m0, s3, 0x2000
	s_add_u32 vcc_lo, s28, 0x160000
	v_lshl_add_u64 v[198:199], s[28:29], 0, v[220:221]
	s_addc_u32 vcc_hi, s29, 0
	s_add_i32 s3, s55, s33
	global_load_lds_dwordx4 v[198:199], off
	v_lshl_add_u64 v[200:201], vcc, 0, v[210:211]
	s_mov_b32 m0, s3
	v_lshl_add_u64 v[202:203], s[30:31], 0, v[218:219]
	global_load_lds_dwordx4 v[200:201], off
	v_lshl_add_u64 v[200:201], vcc, 0, v[220:221]
	s_add_i32 m0, s3, 0x2000
	s_nop 0
	global_load_lds_dwordx4 v[200:201], off
	v_lshl_add_u64 v[200:201], s[30:31], 0, v[208:209]
	s_mov_b32 m0, s11
	s_nop 0
	global_load_lds_dwordx4 v[200:201], off
	s_mov_b32 m0, s65
	s_nop 0
	global_load_lds_dwordx4 v[202:203], off
	s_waitcnt vmcnt(8)
	s_waitcnt lgkmcnt(0)
	s_barrier
	s_setprio 1
	s_waitcnt lgkmcnt(0)
	v_mfma_f32_16x16x32_bf16 v[60:63], v[76:79], v[164:167], v[60:63]
	v_mfma_f32_16x16x32_bf16 v[60:63], v[88:91], v[168:171], v[60:63]
	v_mfma_f32_16x16x32_bf16 v[52:55], v[76:79], v[172:175], v[52:55]
	v_mfma_f32_16x16x32_bf16 v[52:55], v[88:91], v[176:179], v[52:55]
	v_mfma_f32_16x16x32_bf16 v[44:47], v[76:79], v[180:183], v[44:47]
	v_mfma_f32_16x16x32_bf16 v[44:47], v[88:91], v[184:187], v[44:47]
	v_mfma_f32_16x16x32_bf16 v[36:39], v[76:79], v[188:191], v[36:39]
	v_mfma_f32_16x16x32_bf16 v[36:39], v[88:91], v[192:195], v[36:39]
	v_mfma_f32_16x16x32_bf16 v[56:59], v[100:103], v[164:167], v[56:59]
	v_mfma_f32_16x16x32_bf16 v[56:59], v[112:115], v[168:171], v[56:59]
	v_mfma_f32_16x16x32_bf16 v[48:51], v[100:103], v[172:175], v[48:51]
	v_mfma_f32_16x16x32_bf16 v[48:51], v[112:115], v[176:179], v[48:51]
	v_mfma_f32_16x16x32_bf16 v[40:43], v[100:103], v[180:183], v[40:43]
	v_mfma_f32_16x16x32_bf16 v[40:43], v[112:115], v[184:187], v[40:43]
	v_mfma_f32_16x16x32_bf16 v[32:35], v[100:103], v[188:191], v[32:35]
	v_mfma_f32_16x16x32_bf16 v[32:35], v[112:115], v[192:195], v[32:35]
	s_setprio 0
	s_setprio 1
	v_mfma_f32_16x16x32_bf16 v[28:31], v[124:127], v[164:167], v[28:31]
	v_mfma_f32_16x16x32_bf16 v[28:31], v[136:139], v[168:171], v[28:31]
	v_mfma_f32_16x16x32_bf16 v[20:23], v[124:127], v[172:175], v[20:23]
	v_mfma_f32_16x16x32_bf16 v[20:23], v[136:139], v[176:179], v[20:23]
	v_mfma_f32_16x16x32_bf16 v[12:15], v[124:127], v[180:183], v[12:15]
	v_mfma_f32_16x16x32_bf16 v[12:15], v[136:139], v[184:187], v[12:15]
	v_mfma_f32_16x16x32_bf16 v[4:7], v[124:127], v[188:191], v[4:7]
	v_mfma_f32_16x16x32_bf16 v[4:7], v[136:139], v[192:195], v[4:7]
	v_mfma_f32_16x16x32_bf16 v[24:27], v[148:151], v[164:167], v[24:27]
	v_mfma_f32_16x16x32_bf16 v[24:27], v[160:163], v[168:171], v[24:27]
	v_mfma_f32_16x16x32_bf16 v[16:19], v[148:151], v[172:175], v[16:19]
	v_mfma_f32_16x16x32_bf16 v[16:19], v[160:163], v[176:179], v[16:19]
	v_mfma_f32_16x16x32_bf16 v[8:11], v[148:151], v[180:183], v[8:11]
	v_mfma_f32_16x16x32_bf16 v[8:11], v[160:163], v[184:187], v[8:11]
	v_mfma_f32_16x16x32_bf16 v[0:3], v[148:151], v[188:191], v[0:3]
	v_mfma_f32_16x16x32_bf16 v[0:3], v[160:163], v[192:195], v[0:3]
	s_setprio 0
	s_barrier
	s_nop 1
	s_add_i32 s3, 0, 0x18000
	s_add_i32 s55, 0, 0x1c000
	v_add_u32_e32 v112, s3, v238
	v_add_u32_e32 v160, s55, v238
	ds_read_b128 v[76:79], v112
	ds_read_b128 v[88:91], v112 offset:1024
	ds_read_b128 v[100:103], v112 offset:2048
	ds_read_b128 v[112:115], v112 offset:3072
	ds_read_b128 v[124:127], v160
	ds_read_b128 v[136:139], v160 offset:1024
	ds_read_b128 v[148:151], v160 offset:2048
	ds_read_b128 v[160:163], v160 offset:3072
	s_add_u32 s30, s30, 0x160000
	s_addc_u32 s31, s31, 0
	s_mov_b32 m0, s34
	v_lshl_add_u64 v[204:205], s[30:31], 0, v[208:209]
	ds_read_b128 v[164:167], v241 offset:32768
	ds_read_b128 v[168:171], v241 offset:33792
	ds_read_b128 v[172:175], v241 offset:34816
	ds_read_b128 v[176:179], v241 offset:35840
	ds_read_b128 v[180:183], v241 offset:36864
	ds_read_b128 v[184:187], v241 offset:37888
	ds_read_b128 v[188:191], v241 offset:38912
	ds_read_b128 v[192:195], v241 offset:39936
	global_load_lds_dwordx4 v[204:205], off
	v_lshl_add_u64 v[204:205], s[30:31], 0, v[218:219]
	s_mov_b32 m0, s67
	s_nop 0
	global_load_lds_dwordx4 v[204:205], off
	s_waitcnt vmcnt(8)
	s_waitcnt lgkmcnt(0)
	s_barrier
	s_setprio 1
	s_waitcnt lgkmcnt(0)
	v_mfma_f32_16x16x32_bf16 v[156:159], v[76:79], v[164:167], v[156:159]
	v_mfma_f32_16x16x32_bf16 v[156:159], v[88:91], v[168:171], v[156:159]
	v_mfma_f32_16x16x32_bf16 v[144:147], v[76:79], v[172:175], v[144:147]
	v_mfma_f32_16x16x32_bf16 v[144:147], v[88:91], v[176:179], v[144:147]
	v_mfma_f32_16x16x32_bf16 v[132:135], v[76:79], v[180:183], v[132:135]
	v_mfma_f32_16x16x32_bf16 v[132:135], v[88:91], v[184:187], v[132:135]
	v_mfma_f32_16x16x32_bf16 v[120:123], v[76:79], v[188:191], v[120:123]
	v_mfma_f32_16x16x32_bf16 v[120:123], v[88:91], v[192:195], v[120:123]
	v_mfma_f32_16x16x32_bf16 v[152:155], v[100:103], v[164:167], v[152:155]
	v_mfma_f32_16x16x32_bf16 v[152:155], v[112:115], v[168:171], v[152:155]
	v_mfma_f32_16x16x32_bf16 v[140:143], v[100:103], v[172:175], v[140:143]
	v_mfma_f32_16x16x32_bf16 v[140:143], v[112:115], v[176:179], v[140:143]
	v_mfma_f32_16x16x32_bf16 v[128:131], v[100:103], v[180:183], v[128:131]
	v_mfma_f32_16x16x32_bf16 v[128:131], v[112:115], v[184:187], v[128:131]
	v_mfma_f32_16x16x32_bf16 v[116:119], v[100:103], v[188:191], v[116:119]
	v_mfma_f32_16x16x32_bf16 v[116:119], v[112:115], v[192:195], v[116:119]
	s_setprio 0
	s_setprio 1
	v_mfma_f32_16x16x32_bf16 v[108:111], v[124:127], v[164:167], v[108:111]
	v_mfma_f32_16x16x32_bf16 v[108:111], v[136:139], v[168:171], v[108:111]
	v_mfma_f32_16x16x32_bf16 v[96:99], v[124:127], v[172:175], v[96:99]
	v_mfma_f32_16x16x32_bf16 v[96:99], v[136:139], v[176:179], v[96:99]
	v_mfma_f32_16x16x32_bf16 v[84:87], v[124:127], v[180:183], v[84:87]
	v_mfma_f32_16x16x32_bf16 v[84:87], v[136:139], v[184:187], v[84:87]
	v_mfma_f32_16x16x32_bf16 v[72:75], v[124:127], v[188:191], v[72:75]
	v_mfma_f32_16x16x32_bf16 v[72:75], v[136:139], v[192:195], v[72:75]
	v_mfma_f32_16x16x32_bf16 v[104:107], v[148:151], v[164:167], v[104:107]
	v_mfma_f32_16x16x32_bf16 v[104:107], v[160:163], v[168:171], v[104:107]
	v_mfma_f32_16x16x32_bf16 v[92:95], v[148:151], v[172:175], v[92:95]
	v_mfma_f32_16x16x32_bf16 v[92:95], v[160:163], v[176:179], v[92:95]
	v_mfma_f32_16x16x32_bf16 v[80:83], v[148:151], v[180:183], v[80:83]
	v_mfma_f32_16x16x32_bf16 v[80:83], v[160:163], v[184:187], v[80:83]
	v_mfma_f32_16x16x32_bf16 v[64:67], v[148:151], v[188:191], v[64:67]
	v_mfma_f32_16x16x32_bf16 v[64:67], v[160:163], v[192:195], v[64:67]
	s_setprio 0
	s_barrier
	s_nop 1
	s_add_i32 s3, s3, s33
	v_lshl_add_u64 v[196:197], v[196:197], 0, s[72:73]
	s_mov_b32 m0, s3
	ds_read_b128 v[164:167], v241 offset:49152
	ds_read_b128 v[168:171], v241 offset:50176
	ds_read_b128 v[172:175], v241 offset:51200
	ds_read_b128 v[176:179], v241 offset:52224
	ds_read_b128 v[180:183], v241 offset:53248
	ds_read_b128 v[184:187], v241 offset:54272
	ds_read_b128 v[188:191], v241 offset:55296
	ds_read_b128 v[192:195], v241 offset:56320
	global_load_lds_dwordx4 v[196:197], off
	s_add_i32 m0, s3, 0x2000
	s_add_u32 s28, s28, 0x160080
	v_lshl_add_u64 v[196:197], v[198:199], 0, s[72:73]
	s_addc_u32 s29, s29, 0
	s_add_i32 s3, s55, s33
	global_load_lds_dwordx4 v[196:197], off
	v_lshl_add_u64 v[196:197], s[28:29], 0, v[210:211]
	s_mov_b32 m0, s3
	s_nop 0
	global_load_lds_dwordx4 v[196:197], off
	v_lshl_add_u64 v[196:197], s[28:29], 0, v[220:221]
	s_add_i32 m0, s3, 0x2000
	s_nop 0
	global_load_lds_dwordx4 v[196:197], off
	v_lshl_add_u64 v[196:197], v[200:201], 0, s[72:73]
	s_mov_b32 m0, s81
	s_nop 0
	global_load_lds_dwordx4 v[196:197], off
	v_lshl_add_u64 v[196:197], v[202:203], 0, s[72:73]
	s_mov_b32 m0, s82
	s_nop 0
	global_load_lds_dwordx4 v[196:197], off
	s_waitcnt vmcnt(8)
	s_waitcnt lgkmcnt(0)
	s_barrier
	s_setprio 1
	s_waitcnt lgkmcnt(0)
	v_mfma_f32_16x16x32_bf16 v[60:63], v[76:79], v[164:167], v[60:63]
	v_mfma_f32_16x16x32_bf16 v[60:63], v[88:91], v[168:171], v[60:63]
	v_mfma_f32_16x16x32_bf16 v[52:55], v[76:79], v[172:175], v[52:55]
	v_mfma_f32_16x16x32_bf16 v[52:55], v[88:91], v[176:179], v[52:55]
	v_mfma_f32_16x16x32_bf16 v[44:47], v[76:79], v[180:183], v[44:47]
	v_mfma_f32_16x16x32_bf16 v[44:47], v[88:91], v[184:187], v[44:47]
	v_mfma_f32_16x16x32_bf16 v[36:39], v[76:79], v[188:191], v[36:39]
	v_mfma_f32_16x16x32_bf16 v[36:39], v[88:91], v[192:195], v[36:39]
	v_mfma_f32_16x16x32_bf16 v[56:59], v[100:103], v[164:167], v[56:59]
	v_mfma_f32_16x16x32_bf16 v[56:59], v[112:115], v[168:171], v[56:59]
	v_mfma_f32_16x16x32_bf16 v[48:51], v[100:103], v[172:175], v[48:51]
	v_mfma_f32_16x16x32_bf16 v[48:51], v[112:115], v[176:179], v[48:51]
	v_mfma_f32_16x16x32_bf16 v[40:43], v[100:103], v[180:183], v[40:43]
	v_mfma_f32_16x16x32_bf16 v[40:43], v[112:115], v[184:187], v[40:43]
	v_mfma_f32_16x16x32_bf16 v[32:35], v[100:103], v[188:191], v[32:35]
	v_mfma_f32_16x16x32_bf16 v[32:35], v[112:115], v[192:195], v[32:35]
	s_setprio 0
	s_setprio 1
	v_mfma_f32_16x16x32_bf16 v[28:31], v[124:127], v[164:167], v[28:31]
	v_mfma_f32_16x16x32_bf16 v[28:31], v[136:139], v[168:171], v[28:31]
	v_mfma_f32_16x16x32_bf16 v[20:23], v[124:127], v[172:175], v[20:23]
	v_mfma_f32_16x16x32_bf16 v[20:23], v[136:139], v[176:179], v[20:23]
	v_mfma_f32_16x16x32_bf16 v[12:15], v[124:127], v[180:183], v[12:15]
	v_mfma_f32_16x16x32_bf16 v[12:15], v[136:139], v[184:187], v[12:15]
	v_mfma_f32_16x16x32_bf16 v[4:7], v[124:127], v[188:191], v[4:7]
	v_mfma_f32_16x16x32_bf16 v[4:7], v[136:139], v[192:195], v[4:7]
	v_mfma_f32_16x16x32_bf16 v[24:27], v[148:151], v[164:167], v[24:27]
	v_mfma_f32_16x16x32_bf16 v[24:27], v[160:163], v[168:171], v[24:27]
	v_mfma_f32_16x16x32_bf16 v[16:19], v[148:151], v[172:175], v[16:19]
	v_mfma_f32_16x16x32_bf16 v[16:19], v[160:163], v[176:179], v[16:19]
	v_mfma_f32_16x16x32_bf16 v[8:11], v[148:151], v[180:183], v[8:11]
	v_mfma_f32_16x16x32_bf16 v[8:11], v[160:163], v[184:187], v[8:11]
	v_mfma_f32_16x16x32_bf16 v[0:3], v[148:151], v[188:191], v[0:3]
	v_mfma_f32_16x16x32_bf16 v[0:3], v[160:163], v[192:195], v[0:3]
	s_setprio 0
	s_barrier
	s_nop 1
	s_add_u32 s26, s26, 0x100
	s_addc_u32 s27, s27, 0
	s_cmp_ge_i32 s2, s17
	s_mov_b32 s28, s2
	s_cbranch_scc1 .LBB0_1669
